# GEMM main loops: LDS-DMA waits moved just-in-time (vmcnt(10) in phases 1,2,4,5,6,8 instead of vmcnt(6) in phases 4 and 8)
# baseline (speedup 1.0000x reference)
.LBB0_58:
	s_add_u32 s44, s42, 0x100
	s_addc_u32 s45, s43, 0
	s_add_i32 s23, 0, 0x10000
	v_add_u32_e32 v145, s23, v143
	ds_read_b128 v[146:149], v145
	ds_read_b128 v[150:153], v145 offset:1024
	ds_read_b128 v[154:157], v145 offset:2048
	ds_read_b128 v[158:161], v145 offset:3072
	s_cmp_eq_u32 s22, 40
	s_cselect_b32 s49, s1, s45
	s_cselect_b32 s48, s0, s44
	s_cselect_b32 s47, s41, s21
	s_cselect_b32 s46, s40, s20
	v_lshl_add_u64 v[194:195], s[42:43], 0, v[138:139]
	s_add_i32 m0, s52, 0xc000
	ds_read_b128 v[162:165], v144
	ds_read_b128 v[166:169], v144 offset:1024
	ds_read_b128 v[170:173], v144 offset:2048
	ds_read_b128 v[174:177], v144 offset:3072
	ds_read_b128 v[178:181], v144 offset:4096
	ds_read_b128 v[182:185], v144 offset:5120
	ds_read_b128 v[186:189], v144 offset:6144
	ds_read_b128 v[190:193], v144 offset:7168
	global_load_lds_dwordx4 v[194:195], off
	v_lshl_add_u64 v[194:195], s[42:43], 0, v[140:141]
	s_add_i32 m0, s52, 0xe000
	s_nop 0
	global_load_lds_dwordx4 v[194:195], off
	s_waitcnt lgkmcnt(8)
	s_waitcnt vmcnt(10)
	s_barrier
	s_waitcnt lgkmcnt(0)
	s_setprio 1
	s_waitcnt lgkmcnt(0)
	v_mfma_f32_16x16x32_bf16 v[128:131], v[146:149], v[162:165], v[128:131]
	v_mfma_f32_16x16x32_bf16 v[124:127], v[154:157], v[162:165], v[124:127]
	v_mfma_f32_16x16x32_bf16 v[120:123], v[146:149], v[170:173], v[120:123]
	v_mfma_f32_16x16x32_bf16 v[116:119], v[154:157], v[170:173], v[116:119]
	v_mfma_f32_16x16x32_bf16 v[104:107], v[146:149], v[178:181], v[104:107]
	v_mfma_f32_16x16x32_bf16 v[100:103], v[154:157], v[178:181], v[100:103]
	v_mfma_f32_16x16x32_bf16 v[88:91], v[146:149], v[186:189], v[88:91]
	v_mfma_f32_16x16x32_bf16 v[84:87], v[154:157], v[186:189], v[84:87]
	v_mfma_f32_16x16x32_bf16 v[128:131], v[150:153], v[166:169], v[128:131]
	v_mfma_f32_16x16x32_bf16 v[124:127], v[158:161], v[166:169], v[124:127]
	v_mfma_f32_16x16x32_bf16 v[120:123], v[150:153], v[174:177], v[120:123]
	v_mfma_f32_16x16x32_bf16 v[116:119], v[158:161], v[174:177], v[116:119]
	v_mfma_f32_16x16x32_bf16 v[104:107], v[150:153], v[182:185], v[104:107]
	v_mfma_f32_16x16x32_bf16 v[100:103], v[158:161], v[182:185], v[100:103]
	v_mfma_f32_16x16x32_bf16 v[88:91], v[150:153], v[190:193], v[88:91]
	v_mfma_f32_16x16x32_bf16 v[84:87], v[158:161], v[190:193], v[84:87]
	s_setprio 0
	s_barrier
	s_add_i32 s26, 0, 0x14000
	s_add_i32 s23, s23, s37
	v_add_u32_e32 v145, s26, v143
	v_lshl_add_u64 v[194:195], s[46:47], 0, v[132:133]
	s_mov_b32 m0, s23
	ds_read_b128 v[202:205], v145
	ds_read_b128 v[206:209], v145 offset:1024
	ds_read_b128 v[210:213], v145 offset:2048
	ds_read_b128 v[214:217], v145 offset:3072
	global_load_lds_dwordx4 v[194:195], off
	v_lshl_add_u64 v[198:199], s[46:47], 0, v[136:137]
	s_add_i32 m0, s23, 0x2000
	s_nop 0
	global_load_lds_dwordx4 v[198:199], off
	s_waitcnt vmcnt(10)
	s_barrier
	s_waitcnt lgkmcnt(0)
	s_setprio 1
	s_waitcnt lgkmcnt(0)
	v_mfma_f32_16x16x32_bf16 v[112:115], v[202:205], v[162:165], v[112:115]
	v_mfma_f32_16x16x32_bf16 v[108:111], v[210:213], v[162:165], v[108:111]
	v_mfma_f32_16x16x32_bf16 v[96:99], v[202:205], v[170:173], v[96:99]
	v_mfma_f32_16x16x32_bf16 v[92:95], v[210:213], v[170:173], v[92:95]
	v_mfma_f32_16x16x32_bf16 v[80:83], v[202:205], v[178:181], v[80:83]
	v_mfma_f32_16x16x32_bf16 v[76:79], v[210:213], v[178:181], v[76:79]
	v_mfma_f32_16x16x32_bf16 v[72:75], v[202:205], v[186:189], v[72:75]
	v_mfma_f32_16x16x32_bf16 v[68:71], v[210:213], v[186:189], v[68:71]
	v_mfma_f32_16x16x32_bf16 v[112:115], v[206:209], v[166:169], v[112:115]
	v_mfma_f32_16x16x32_bf16 v[108:111], v[214:217], v[166:169], v[108:111]
	v_mfma_f32_16x16x32_bf16 v[96:99], v[206:209], v[174:177], v[96:99]
	v_mfma_f32_16x16x32_bf16 v[92:95], v[214:217], v[174:177], v[92:95]
	v_mfma_f32_16x16x32_bf16 v[80:83], v[206:209], v[182:185], v[80:83]
	v_mfma_f32_16x16x32_bf16 v[76:79], v[214:217], v[182:185], v[76:79]
	v_mfma_f32_16x16x32_bf16 v[72:75], v[206:209], v[190:193], v[72:75]
	v_mfma_f32_16x16x32_bf16 v[68:71], v[214:217], v[190:193], v[68:71]
	s_setprio 0
	s_mov_b32 m0, s52
	v_lshl_add_u64 v[222:223], s[48:49], 0, v[0:1]
	s_barrier
	ds_read_b128 v[162:165], v144 offset:16384
	ds_read_b128 v[166:169], v144 offset:17408
	ds_read_b128 v[170:173], v144 offset:18432
	ds_read_b128 v[174:177], v144 offset:19456
	ds_read_b128 v[178:181], v144 offset:20480
	ds_read_b128 v[182:185], v144 offset:21504
	ds_read_b128 v[186:189], v144 offset:22528
	ds_read_b128 v[190:193], v144 offset:23552
	global_load_lds_dwordx4 v[222:223], off
	v_lshl_add_u64 v[236:237], s[48:49], 0, v[134:135]
	s_mov_b32 m0, s53
	s_nop 0
	global_load_lds_dwordx4 v[236:237], off
	s_barrier
	s_waitcnt lgkmcnt(0)
	s_setprio 1
	s_waitcnt lgkmcnt(0)
	v_mfma_f32_16x16x32_bf16 v[64:67], v[146:149], v[162:165], v[64:67]
	v_mfma_f32_16x16x32_bf16 v[60:63], v[154:157], v[162:165], v[60:63]
	v_mfma_f32_16x16x32_bf16 v[56:59], v[146:149], v[170:173], v[56:59]
	v_mfma_f32_16x16x32_bf16 v[52:55], v[154:157], v[170:173], v[52:55]
	v_mfma_f32_16x16x32_bf16 v[40:43], v[146:149], v[178:181], v[40:43]
	v_mfma_f32_16x16x32_bf16 v[36:39], v[154:157], v[178:181], v[36:39]
	v_mfma_f32_16x16x32_bf16 v[24:27], v[146:149], v[186:189], v[24:27]
	v_mfma_f32_16x16x32_bf16 v[16:19], v[154:157], v[186:189], v[16:19]
	v_mfma_f32_16x16x32_bf16 v[64:67], v[150:153], v[166:169], v[64:67]
	v_mfma_f32_16x16x32_bf16 v[60:63], v[158:161], v[166:169], v[60:63]
	v_mfma_f32_16x16x32_bf16 v[56:59], v[150:153], v[174:177], v[56:59]
	v_mfma_f32_16x16x32_bf16 v[52:55], v[158:161], v[174:177], v[52:55]
	v_mfma_f32_16x16x32_bf16 v[40:43], v[150:153], v[182:185], v[40:43]
	v_mfma_f32_16x16x32_bf16 v[36:39], v[158:161], v[182:185], v[36:39]
	v_mfma_f32_16x16x32_bf16 v[24:27], v[150:153], v[190:193], v[24:27]
	v_mfma_f32_16x16x32_bf16 v[16:19], v[158:161], v[190:193], v[16:19]
	s_setprio 0
	s_barrier
	s_add_u32 s24, s46, 0xb0000
	s_addc_u32 s25, s47, 0
	s_add_i32 s23, s26, s37
	v_lshl_add_u64 v[146:147], s[24:25], 0, v[132:133]
	s_mov_b32 m0, s23
	s_nop 0
	global_load_lds_dwordx4 v[146:147], off
	v_lshl_add_u64 v[146:147], s[24:25], 0, v[136:137]
	s_add_i32 m0, s23, 0x2000
	s_nop 0
	global_load_lds_dwordx4 v[146:147], off
	s_waitcnt vmcnt(10)
	s_barrier
	s_setprio 1
	v_mfma_f32_16x16x32_bf16 v[48:51], v[202:205], v[162:165], v[48:51]
	v_mfma_f32_16x16x32_bf16 v[44:47], v[210:213], v[162:165], v[44:47]
	v_mfma_f32_16x16x32_bf16 v[32:35], v[202:205], v[170:173], v[32:35]
	v_mfma_f32_16x16x32_bf16 v[28:31], v[210:213], v[170:173], v[28:31]
	v_mfma_f32_16x16x32_bf16 v[20:23], v[202:205], v[178:181], v[20:23]
	v_mfma_f32_16x16x32_bf16 v[12:15], v[210:213], v[178:181], v[12:15]
	v_mfma_f32_16x16x32_bf16 v[8:11], v[202:205], v[186:189], v[8:11]
	v_mfma_f32_16x16x32_bf16 v[4:7], v[210:213], v[186:189], v[4:7]
	v_mfma_f32_16x16x32_bf16 v[48:51], v[206:209], v[166:169], v[48:51]
	v_mfma_f32_16x16x32_bf16 v[44:47], v[214:217], v[166:169], v[44:47]
	v_mfma_f32_16x16x32_bf16 v[32:35], v[206:209], v[174:177], v[32:35]
	v_mfma_f32_16x16x32_bf16 v[28:31], v[214:217], v[174:177], v[28:31]
	v_mfma_f32_16x16x32_bf16 v[20:23], v[206:209], v[182:185], v[20:23]
	v_mfma_f32_16x16x32_bf16 v[12:15], v[214:217], v[182:185], v[12:15]
	v_mfma_f32_16x16x32_bf16 v[8:11], v[206:209], v[190:193], v[8:11]
	v_mfma_f32_16x16x32_bf16 v[4:7], v[214:217], v[190:193], v[4:7]
	s_setprio 0
	s_add_i32 s23, 0, 0x18000
	v_add_u32_e32 v145, s23, v143
	s_barrier
	ds_read_b128 v[146:149], v145
	ds_read_b128 v[150:153], v145 offset:1024
	ds_read_b128 v[154:157], v145 offset:2048
	ds_read_b128 v[158:161], v145 offset:3072
	s_add_u32 s24, s48, 0xb0000
	s_addc_u32 s25, s49, 0
	s_mov_b32 m0, s54
	v_lshl_add_u64 v[202:203], s[24:25], 0, v[0:1]
	ds_read_b128 v[162:165], v144 offset:32768
	ds_read_b128 v[166:169], v144 offset:33792
	ds_read_b128 v[170:173], v144 offset:34816
	ds_read_b128 v[174:177], v144 offset:35840
	ds_read_b128 v[178:181], v144 offset:36864
	ds_read_b128 v[182:185], v144 offset:37888
	ds_read_b128 v[186:189], v144 offset:38912
	ds_read_b128 v[190:193], v144 offset:39936
	global_load_lds_dwordx4 v[202:203], off
	v_lshl_add_u64 v[202:203], s[24:25], 0, v[134:135]
	s_mov_b32 m0, s55
	s_nop 0
	global_load_lds_dwordx4 v[202:203], off
	s_waitcnt lgkmcnt(8)
	s_waitcnt vmcnt(10)
	s_barrier
	s_waitcnt lgkmcnt(0)
	s_setprio 1
	s_waitcnt lgkmcnt(0)
	v_mfma_f32_16x16x32_bf16 v[128:131], v[146:149], v[162:165], v[128:131]
	v_mfma_f32_16x16x32_bf16 v[124:127], v[154:157], v[162:165], v[124:127]
	v_mfma_f32_16x16x32_bf16 v[120:123], v[146:149], v[170:173], v[120:123]
	v_mfma_f32_16x16x32_bf16 v[116:119], v[154:157], v[170:173], v[116:119]
	v_mfma_f32_16x16x32_bf16 v[104:107], v[146:149], v[178:181], v[104:107]
	v_mfma_f32_16x16x32_bf16 v[100:103], v[154:157], v[178:181], v[100:103]
	v_mfma_f32_16x16x32_bf16 v[88:91], v[146:149], v[186:189], v[88:91]
	v_mfma_f32_16x16x32_bf16 v[84:87], v[154:157], v[186:189], v[84:87]
	v_mfma_f32_16x16x32_bf16 v[128:131], v[150:153], v[166:169], v[128:131]
	v_mfma_f32_16x16x32_bf16 v[124:127], v[158:161], v[166:169], v[124:127]
	v_mfma_f32_16x16x32_bf16 v[120:123], v[150:153], v[174:177], v[120:123]
	v_mfma_f32_16x16x32_bf16 v[116:119], v[158:161], v[174:177], v[116:119]
	v_mfma_f32_16x16x32_bf16 v[104:107], v[150:153], v[182:185], v[104:107]
	v_mfma_f32_16x16x32_bf16 v[100:103], v[158:161], v[182:185], v[100:103]
	v_mfma_f32_16x16x32_bf16 v[88:91], v[150:153], v[190:193], v[88:91]
	v_mfma_f32_16x16x32_bf16 v[84:87], v[158:161], v[190:193], v[84:87]
	s_setprio 0
	s_barrier
	s_add_i32 s26, 0, 0x1c000
	s_add_i32 s23, s23, s37
	v_add_u32_e32 v145, s26, v143
	v_lshl_add_u64 v[194:195], v[194:195], 0, s[76:77]
	s_mov_b32 m0, s23
	ds_read_b128 v[202:205], v145
	ds_read_b128 v[206:209], v145 offset:1024
	ds_read_b128 v[210:213], v145 offset:2048
	ds_read_b128 v[214:217], v145 offset:3072
	global_load_lds_dwordx4 v[194:195], off
	v_lshl_add_u64 v[194:195], v[198:199], 0, s[76:77]
	s_add_i32 m0, s23, 0x2000
	s_nop 0
	global_load_lds_dwordx4 v[194:195], off
	s_waitcnt vmcnt(10)
	s_barrier
	s_waitcnt lgkmcnt(0)
	s_setprio 1
	s_waitcnt lgkmcnt(0)
	v_mfma_f32_16x16x32_bf16 v[112:115], v[202:205], v[162:165], v[112:115]
	v_mfma_f32_16x16x32_bf16 v[108:111], v[210:213], v[162:165], v[108:111]
	v_mfma_f32_16x16x32_bf16 v[96:99], v[202:205], v[170:173], v[96:99]
	v_mfma_f32_16x16x32_bf16 v[92:95], v[210:213], v[170:173], v[92:95]
	v_mfma_f32_16x16x32_bf16 v[80:83], v[202:205], v[178:181], v[80:83]
	v_mfma_f32_16x16x32_bf16 v[76:79], v[210:213], v[178:181], v[76:79]
	v_mfma_f32_16x16x32_bf16 v[72:75], v[202:205], v[186:189], v[72:75]
	v_mfma_f32_16x16x32_bf16 v[68:71], v[210:213], v[186:189], v[68:71]
	v_mfma_f32_16x16x32_bf16 v[112:115], v[206:209], v[166:169], v[112:115]
	v_mfma_f32_16x16x32_bf16 v[108:111], v[214:217], v[166:169], v[108:111]
	v_mfma_f32_16x16x32_bf16 v[96:99], v[206:209], v[174:177], v[96:99]
	v_mfma_f32_16x16x32_bf16 v[92:95], v[214:217], v[174:177], v[92:95]
	v_mfma_f32_16x16x32_bf16 v[80:83], v[206:209], v[182:185], v[80:83]
	v_mfma_f32_16x16x32_bf16 v[76:79], v[214:217], v[182:185], v[76:79]
	v_mfma_f32_16x16x32_bf16 v[72:75], v[206:209], v[190:193], v[72:75]
	v_mfma_f32_16x16x32_bf16 v[68:71], v[214:217], v[190:193], v[68:71]
	s_setprio 0
	s_mov_b32 m0, s56
	v_lshl_add_u64 v[194:195], v[222:223], 0, s[76:77]
	s_barrier
	ds_read_b128 v[162:165], v144 offset:49152
	ds_read_b128 v[166:169], v144 offset:50176
	ds_read_b128 v[170:173], v144 offset:51200
	ds_read_b128 v[174:177], v144 offset:52224
	ds_read_b128 v[178:181], v144 offset:53248
	ds_read_b128 v[182:185], v144 offset:54272
	ds_read_b128 v[186:189], v144 offset:55296
	ds_read_b128 v[190:193], v144 offset:56320
	global_load_lds_dwordx4 v[194:195], off
	v_lshl_add_u64 v[194:195], v[236:237], 0, s[76:77]
	s_mov_b32 m0, s57
	s_nop 0
	global_load_lds_dwordx4 v[194:195], off
	s_barrier
	s_waitcnt lgkmcnt(0)
	s_setprio 1
	s_waitcnt lgkmcnt(0)
	v_mfma_f32_16x16x32_bf16 v[64:67], v[146:149], v[162:165], v[64:67]
	v_mfma_f32_16x16x32_bf16 v[60:63], v[154:157], v[162:165], v[60:63]
	v_mfma_f32_16x16x32_bf16 v[56:59], v[146:149], v[170:173], v[56:59]
	v_mfma_f32_16x16x32_bf16 v[52:55], v[154:157], v[170:173], v[52:55]
	v_mfma_f32_16x16x32_bf16 v[40:43], v[146:149], v[178:181], v[40:43]
	v_mfma_f32_16x16x32_bf16 v[36:39], v[154:157], v[178:181], v[36:39]
	v_mfma_f32_16x16x32_bf16 v[24:27], v[146:149], v[186:189], v[24:27]
	v_mfma_f32_16x16x32_bf16 v[16:19], v[154:157], v[186:189], v[16:19]
	v_mfma_f32_16x16x32_bf16 v[64:67], v[150:153], v[166:169], v[64:67]
	v_mfma_f32_16x16x32_bf16 v[60:63], v[158:161], v[166:169], v[60:63]
	v_mfma_f32_16x16x32_bf16 v[56:59], v[150:153], v[174:177], v[56:59]
	v_mfma_f32_16x16x32_bf16 v[52:55], v[158:161], v[174:177], v[52:55]
	v_mfma_f32_16x16x32_bf16 v[40:43], v[150:153], v[182:185], v[40:43]
	v_mfma_f32_16x16x32_bf16 v[36:39], v[158:161], v[182:185], v[36:39]
	v_mfma_f32_16x16x32_bf16 v[24:27], v[150:153], v[190:193], v[24:27]
	v_mfma_f32_16x16x32_bf16 v[16:19], v[158:161], v[190:193], v[16:19]
	s_setprio 0
	s_barrier
	s_add_u32 s24, s46, 0xb0080
	s_addc_u32 s25, s47, 0
	s_add_i32 s23, s26, s37
	v_lshl_add_u64 v[146:147], s[24:25], 0, v[132:133]
	s_mov_b32 m0, s23
	s_nop 0
	global_load_lds_dwordx4 v[146:147], off
	v_lshl_add_u64 v[146:147], s[24:25], 0, v[136:137]
	s_add_i32 m0, s23, 0x2000
	s_nop 0
	global_load_lds_dwordx4 v[146:147], off
	s_waitcnt vmcnt(10)
	s_barrier
	s_setprio 1
	v_mfma_f32_16x16x32_bf16 v[48:51], v[202:205], v[162:165], v[48:51]
	v_mfma_f32_16x16x32_bf16 v[44:47], v[210:213], v[162:165], v[44:47]
	v_mfma_f32_16x16x32_bf16 v[32:35], v[202:205], v[170:173], v[32:35]
	v_mfma_f32_16x16x32_bf16 v[28:31], v[210:213], v[170:173], v[28:31]
	v_mfma_f32_16x16x32_bf16 v[20:23], v[202:205], v[178:181], v[20:23]
	v_mfma_f32_16x16x32_bf16 v[12:15], v[210:213], v[178:181], v[12:15]
	v_mfma_f32_16x16x32_bf16 v[8:11], v[202:205], v[186:189], v[8:11]
	v_mfma_f32_16x16x32_bf16 v[4:7], v[210:213], v[186:189], v[4:7]
	v_mfma_f32_16x16x32_bf16 v[48:51], v[206:209], v[166:169], v[48:51]
	v_mfma_f32_16x16x32_bf16 v[44:47], v[214:217], v[166:169], v[44:47]
	v_mfma_f32_16x16x32_bf16 v[32:35], v[206:209], v[174:177], v[32:35]
	v_mfma_f32_16x16x32_bf16 v[28:31], v[214:217], v[174:177], v[28:31]
	v_mfma_f32_16x16x32_bf16 v[20:23], v[206:209], v[182:185], v[20:23]
	v_mfma_f32_16x16x32_bf16 v[12:15], v[214:217], v[182:185], v[12:15]
	v_mfma_f32_16x16x32_bf16 v[8:11], v[206:209], v[190:193], v[8:11]
	v_mfma_f32_16x16x32_bf16 v[4:7], v[214:217], v[190:193], v[4:7]
	s_setprio 0
	s_add_i32 s22, s22, 2
	s_add_u32 s20, s20, 0x100
	s_addc_u32 s21, s21, 0
	s_cmp_gt_u32 s22, 41
	s_mov_b64 s[42:43], s[44:45]
	s_barrier
	s_cbranch_scc0 .LBB0_58
	v_lshl_add_u32 v146, s61, 8, v142
	v_cvt_pk_bf16_f32 v72, v72, v73
	v_cvt_pk_bf16_f32 v73, v74, v75
	v_cvt_pk_bf16_f32 v74, v68, v69
	v_add_u32_e32 v68, 0x80, v146
	s_lshl_b32 s20, s62, 8
	v_ashrrev_i32_e32 v147, 31, v146
	v_readlane_b32 s22, v252, 10
	v_cvt_pk_bf16_f32 v112, v112, v113
	v_cvt_pk_bf16_f32 v113, v114, v115
	v_cvt_pk_bf16_f32 v114, v108, v109
	v_or_b32_e32 v108, 16, v146
	v_ashrrev_i32_e32 v69, 31, v68
	v_cvt_pk_bf16_f32 v48, v48, v49
	v_cvt_pk_bf16_f32 v49, v50, v51
	v_cvt_pk_bf16_f32 v50, v44, v45
	v_add_u32_e32 v44, 0x90, v146
	s_ashr_i32 s21, s20, 31
	v_lshlrev_b64 v[148:149], 11, v[146:147]
	v_readlane_b32 s23, v252, 11
	v_ashrrev_i32_e32 v109, 31, v108
	v_cvt_pk_bf16_f32 v96, v96, v97
	v_cvt_pk_bf16_f32 v97, v98, v99
	v_cvt_pk_bf16_f32 v98, v92, v93
	v_or_b32_e32 v92, 32, v146
	v_lshlrev_b64 v[68:69], 11, v[68:69]
	v_ashrrev_i32_e32 v45, 31, v44
	v_cvt_pk_bf16_f32 v32, v32, v33
	v_cvt_pk_bf16_f32 v33, v34, v35
	v_cvt_pk_bf16_f32 v34, v28, v29
	v_add_u32_e32 v28, 0xa0, v146
	v_lshl_add_u64 v[148:149], s[22:23], 0, v[148:149]
	s_lshl_b64 s[42:43], s[20:21], 1
	v_lshlrev_b64 v[108:109], 11, v[108:109]
	v_ashrrev_i32_e32 v93, 31, v92
	v_cvt_pk_bf16_f32 v80, v80, v81
	v_cvt_pk_bf16_f32 v81, v82, v83
	v_cvt_pk_bf16_f32 v82, v76, v77
	v_or_b32_e32 v76, 48, v146
	v_lshl_add_u64 v[68:69], s[22:23], 0, v[68:69]
	v_lshlrev_b64 v[44:45], 11, v[44:45]
	v_ashrrev_i32_e32 v29, 31, v28
	v_cvt_pk_bf16_f32 v20, v20, v21
	v_cvt_pk_bf16_f32 v21, v22, v23
	v_cvt_pk_bf16_f32 v22, v12, v13
	v_add_u32_e32 v12, 0xb0, v146
	v_lshl_add_u64 v[148:149], v[148:149], 0, s[42:43]
	v_lshl_add_u64 v[108:109], s[22:23], 0, v[108:109]
	v_lshlrev_b64 v[92:93], 11, v[92:93]
	v_ashrrev_i32_e32 v77, 31, v76
	v_lshl_add_u64 v[68:69], v[68:69], 0, s[42:43]
	v_lshl_add_u64 v[44:45], s[22:23], 0, v[44:45]
	v_lshlrev_b64 v[28:29], 11, v[28:29]
	v_ashrrev_i32_e32 v13, 31, v12
	v_lshl_add_u64 v[148:149], v[148:149], 0, s[72:73]
	v_lshl_add_u64 v[108:109], v[108:109], 0, s[42:43]
	v_lshl_add_u64 v[92:93], s[22:23], 0, v[92:93]
	v_lshlrev_b64 v[76:77], 11, v[76:77]
	v_lshl_add_u64 v[68:69], v[68:69], 0, s[72:73]
	v_lshl_add_u64 v[44:45], v[44:45], 0, s[42:43]
	v_lshl_add_u64 v[28:29], s[22:23], 0, v[28:29]
	v_lshlrev_b64 v[12:13], 11, v[12:13]
	v_lshl_add_u64 v[148:149], v[148:149], 0, v[2:3]
	v_cvt_pk_bf16_f32 v115, v110, v111
	v_lshl_add_u64 v[108:109], v[108:109], 0, s[72:73]
	v_lshl_add_u64 v[92:93], v[92:93], 0, s[42:43]
	v_lshl_add_u64 v[76:77], s[22:23], 0, v[76:77]
	v_lshl_add_u64 v[68:69], v[68:69], 0, v[2:3]
	v_cvt_pk_bf16_f32 v51, v46, v47
	v_lshl_add_u64 v[44:45], v[44:45], 0, s[72:73]
	v_lshl_add_u64 v[28:29], v[28:29], 0, s[42:43]
	v_lshl_add_u64 v[12:13], s[22:23], 0, v[12:13]
	global_store_dwordx4 v[148:149], v[112:115], off offset:256
	v_cvt_pk_bf16_f32 v99, v94, v95
	v_lshl_add_u64 v[92:93], v[92:93], 0, s[72:73]
	v_lshl_add_u64 v[112:113], v[108:109], 0, v[2:3]
	v_lshl_add_u64 v[76:77], v[76:77], 0, s[42:43]
	global_store_dwordx4 v[68:69], v[48:51], off offset:256
	v_cvt_pk_bf16_f32 v35, v30, v31
	v_lshl_add_u64 v[28:29], v[28:29], 0, s[72:73]
	v_lshl_add_u64 v[48:49], v[44:45], 0, v[2:3]
	v_lshl_add_u64 v[12:13], v[12:13], 0, s[42:43]
	global_store_dwordx4 v[112:113], v[96:99], off offset:256
	v_cvt_pk_bf16_f32 v83, v78, v79
	v_lshl_add_u64 v[76:77], v[76:77], 0, s[72:73]
	v_lshl_add_u64 v[96:97], v[92:93], 0, v[2:3]
	global_store_dwordx4 v[48:49], v[32:35], off offset:256
	v_cvt_pk_bf16_f32 v23, v14, v15
	v_lshl_add_u64 v[12:13], v[12:13], 0, s[72:73]
	v_lshl_add_u64 v[32:33], v[28:29], 0, v[2:3]
	v_cvt_pk_bf16_f32 v128, v128, v129
	v_cvt_pk_bf16_f32 v129, v130, v131
	v_cvt_pk_bf16_f32 v130, v124, v125
	v_cvt_pk_bf16_f32 v131, v126, v127
	v_cvt_pk_bf16_f32 v108, v120, v121
	v_cvt_pk_bf16_f32 v109, v122, v123
	v_cvt_pk_bf16_f32 v110, v116, v117
	v_cvt_pk_bf16_f32 v111, v118, v119
	v_cvt_pk_bf16_f32 v92, v104, v105
	v_cvt_pk_bf16_f32 v93, v106, v107
	v_cvt_pk_bf16_f32 v94, v100, v101
	v_cvt_pk_bf16_f32 v95, v102, v103
	global_store_dwordx4 v[96:97], v[80:83], off offset:256
	v_cvt_pk_bf16_f32 v78, v84, v85
	v_cvt_pk_bf16_f32 v79, v86, v87
	v_lshl_add_u64 v[80:81], v[76:77], 0, v[2:3]
	v_cvt_pk_bf16_f32 v76, v88, v89
	v_cvt_pk_bf16_f32 v77, v90, v91
	v_cvt_pk_bf16_f32 v75, v70, v71
	v_cvt_pk_bf16_f32 v64, v64, v65
	v_cvt_pk_bf16_f32 v65, v66, v67
	v_cvt_pk_bf16_f32 v66, v60, v61
	v_cvt_pk_bf16_f32 v67, v62, v63
	v_cvt_pk_bf16_f32 v44, v56, v57
	v_cvt_pk_bf16_f32 v45, v58, v59
	v_cvt_pk_bf16_f32 v46, v52, v53
	v_cvt_pk_bf16_f32 v47, v54, v55
	v_cvt_pk_bf16_f32 v28, v40, v41
	v_cvt_pk_bf16_f32 v29, v42, v43
	v_cvt_pk_bf16_f32 v30, v36, v37
	v_cvt_pk_bf16_f32 v31, v38, v39
	global_store_dwordx4 v[32:33], v[20:23], off offset:256
	v_cvt_pk_bf16_f32 v14, v16, v17
	v_cvt_pk_bf16_f32 v15, v18, v19
	v_lshl_add_u64 v[20:21], v[12:13], 0, v[2:3]
	v_cvt_pk_bf16_f32 v12, v24, v25
	v_cvt_pk_bf16_f32 v13, v26, v27
	v_cvt_pk_bf16_f32 v8, v8, v9
	v_cvt_pk_bf16_f32 v9, v10, v11
	v_cvt_pk_bf16_f32 v10, v4, v5
	v_cvt_pk_bf16_f32 v11, v6, v7
	s_and_b64 vcc, exec, s[38:39]
	s_mov_b32 s62, s59
	s_mov_b32 s61, s60
	s_mov_b64 s[44:45], s[40:41]
	s_mov_b64 s[42:43], s[0:1]
	global_store_dwordx4 v[148:149], v[128:131], off
	global_store_dwordx4 v[112:113], v[108:111], off
	global_store_dwordx4 v[96:97], v[92:95], off
	global_store_dwordx4 v[80:81], v[76:79], off
	global_store_dwordx4 v[80:81], v[72:75], off offset:256
	global_store_dwordx4 v[68:69], v[64:67], off
	global_store_dwordx4 v[48:49], v[44:47], off
	global_store_dwordx4 v[32:33], v[28:31], off
	global_store_dwordx4 v[20:21], v[12:15], off
	global_store_dwordx4 v[20:21], v[8:11], off offset:256
	s_cbranch_vccz .LBB0_51
	s_waitcnt vmcnt(0)
	s_cmpk_gt_u32 s36, 0xff
	s_cbranch_scc1 .LBB0_62
	s_barrier

.LBB0_80:
	s_add_u32 s22, s52, 0xfffc0080
	s_addc_u32 s23, s53, -1
	s_add_i32 s24, 0, 0x10000
	v_add_u32_e32 v64, s24, v235
	ds_read_b128 v[52:55], v64
	ds_read_b128 v[56:59], v64 offset:1024
	ds_read_b128 v[60:63], v64 offset:2048
	ds_read_b128 v[64:67], v64 offset:3072
	s_cmp_eq_u32 s21, 12
	s_cselect_b32 s57, s47, s23
	s_cselect_b32 s56, s46, s22
	s_cselect_b32 s55, s49, s20
	s_cselect_b32 s54, s48, s1
	v_lshl_add_u64 v[116:117], s[52:53], 0, v[206:207]
	s_add_i32 m0, s62, 0xc000
	ds_read_b128 v[76:79], v239
	ds_read_b128 v[80:83], v239 offset:1024
	ds_read_b128 v[84:87], v239 offset:2048
	ds_read_b128 v[88:91], v239 offset:3072
	ds_read_b128 v[92:95], v239 offset:4096
	ds_read_b128 v[96:99], v239 offset:5120
	ds_read_b128 v[100:103], v239 offset:6144
	ds_read_b128 v[104:107], v239 offset:7168
	global_load_lds_dwordx4 v[116:117], off
	v_lshl_add_u64 v[116:117], s[52:53], 0, v[208:209]
	s_add_i32 m0, s62, 0xe000
	s_nop 0
	global_load_lds_dwordx4 v[116:117], off
	s_waitcnt lgkmcnt(8)
	s_waitcnt vmcnt(10)
	s_barrier
	s_waitcnt lgkmcnt(0)
	s_setprio 1
	s_waitcnt lgkmcnt(0)
	v_mfma_f32_16x16x32_bf16 v[160:163], v[52:55], v[92:95], v[160:163]
	v_mfma_f32_16x16x32_bf16 v[152:155], v[60:63], v[92:95], v[152:155]
	v_mfma_f32_16x16x32_bf16 v[144:147], v[52:55], v[100:103], v[144:147]
	v_mfma_f32_16x16x32_bf16 v[140:143], v[60:63], v[100:103], v[140:143]
	v_mfma_f32_16x16x32_bf16 v[116:119], v[52:55], v[76:79], v[192:195]
	v_mfma_f32_16x16x32_bf16 v[120:123], v[60:63], v[76:79], v[184:187]
	v_mfma_f32_16x16x32_bf16 v[124:127], v[52:55], v[84:87], v[176:179]
	v_mfma_f32_16x16x32_bf16 v[128:131], v[60:63], v[84:87], v[168:171]
	v_mfma_f32_16x16x32_bf16 v[160:163], v[56:59], v[96:99], v[160:163]
	v_mfma_f32_16x16x32_bf16 v[152:155], v[64:67], v[96:99], v[152:155]
	v_mfma_f32_16x16x32_bf16 v[144:147], v[56:59], v[104:107], v[144:147]
	v_mfma_f32_16x16x32_bf16 v[140:143], v[64:67], v[104:107], v[140:143]
	v_mfma_f32_16x16x32_bf16 v[116:119], v[56:59], v[80:83], v[116:119]
	v_mfma_f32_16x16x32_bf16 v[120:123], v[64:67], v[80:83], v[120:123]
	v_mfma_f32_16x16x32_bf16 v[124:127], v[56:59], v[88:91], v[124:127]
	v_mfma_f32_16x16x32_bf16 v[128:131], v[64:67], v[88:91], v[128:131]
	s_setprio 0
	s_barrier
	s_add_i32 s25, 0, 0x14000
	s_add_i32 s22, s24, s60
	v_add_u32_e32 v192, s25, v235
	v_lshl_add_u64 v[198:199], s[54:55], 0, v[2:3]
	s_mov_b32 m0, s22
	ds_read_b128 v[168:171], v192
	ds_read_b128 v[176:179], v192 offset:1024
	ds_read_b128 v[184:187], v192 offset:2048
	ds_read_b128 v[192:195], v192 offset:3072
	global_load_lds_dwordx4 v[198:199], off
	v_lshl_add_u64 v[222:223], s[54:55], 0, v[0:1]
	s_add_i32 m0, s22, 0x2000
	s_nop 0
	global_load_lds_dwordx4 v[222:223], off
	s_waitcnt vmcnt(10)
	s_barrier
	s_waitcnt lgkmcnt(0)
	s_setprio 1
	s_waitcnt lgkmcnt(0)
	v_mfma_f32_16x16x32_bf16 v[188:191], v[168:171], v[76:79], v[188:191]
	v_mfma_f32_16x16x32_bf16 v[76:79], v[184:187], v[76:79], v[180:183]
	v_mfma_f32_16x16x32_bf16 v[188:191], v[176:179], v[80:83], v[188:191]
	v_mfma_f32_16x16x32_bf16 v[76:79], v[192:195], v[80:83], v[76:79]
	v_mfma_f32_16x16x32_bf16 v[80:83], v[168:171], v[84:87], v[172:175]
	v_mfma_f32_16x16x32_bf16 v[84:87], v[184:187], v[84:87], v[164:167]
	v_mfma_f32_16x16x32_bf16 v[80:83], v[176:179], v[88:91], v[80:83]
	v_mfma_f32_16x16x32_bf16 v[84:87], v[192:195], v[88:91], v[84:87]
	v_mfma_f32_16x16x32_bf16 v[88:91], v[168:171], v[92:95], v[156:159]
	v_mfma_f32_16x16x32_bf16 v[92:95], v[184:187], v[92:95], v[148:151]
	v_mfma_f32_16x16x32_bf16 v[88:91], v[176:179], v[96:99], v[88:91]
	v_mfma_f32_16x16x32_bf16 v[92:95], v[192:195], v[96:99], v[92:95]
	v_mfma_f32_16x16x32_bf16 v[96:99], v[168:171], v[100:103], v[136:139]
	v_mfma_f32_16x16x32_bf16 v[100:103], v[184:187], v[100:103], v[132:135]
	v_mfma_f32_16x16x32_bf16 v[96:99], v[176:179], v[104:107], v[96:99]
	v_mfma_f32_16x16x32_bf16 v[100:103], v[192:195], v[104:107], v[100:103]
	s_setprio 0
	s_mov_b32 m0, s62
	v_lshl_add_u64 v[248:249], s[56:57], 0, v[204:205]
	s_barrier
	ds_read_b128 v[104:107], v239 offset:16384
	ds_read_b128 v[132:135], v239 offset:17408
	ds_read_b128 v[136:139], v239 offset:18432
	ds_read_b128 v[148:151], v239 offset:19456
	ds_read_b128 v[156:159], v239 offset:20480
	ds_read_b128 v[164:167], v239 offset:21504
	ds_read_b128 v[172:175], v239 offset:22528
	ds_read_b128 v[180:183], v239 offset:23552
	global_load_lds_dwordx4 v[248:249], off
	v_lshl_add_u64 v[250:251], s[56:57], 0, v[202:203]
	s_mov_b32 m0, s63
	s_nop 0
	global_load_lds_dwordx4 v[250:251], off
	s_barrier
	s_waitcnt lgkmcnt(0)
	s_setprio 1
	s_waitcnt lgkmcnt(0)
	v_mfma_f32_16x16x32_bf16 v[112:115], v[52:55], v[104:107], v[112:115]
	v_mfma_f32_16x16x32_bf16 v[72:75], v[60:63], v[104:107], v[72:75]
	v_mfma_f32_16x16x32_bf16 v[48:51], v[52:55], v[136:139], v[48:51]
	v_mfma_f32_16x16x32_bf16 v[40:43], v[60:63], v[136:139], v[40:43]
	v_mfma_f32_16x16x32_bf16 v[32:35], v[52:55], v[156:159], v[32:35]
	v_mfma_f32_16x16x32_bf16 v[24:27], v[60:63], v[156:159], v[24:27]
	v_mfma_f32_16x16x32_bf16 v[16:19], v[52:55], v[172:175], v[16:19]
	v_mfma_f32_16x16x32_bf16 v[12:15], v[60:63], v[172:175], v[12:15]
	v_mfma_f32_16x16x32_bf16 v[112:115], v[56:59], v[132:135], v[112:115]
	v_mfma_f32_16x16x32_bf16 v[72:75], v[64:67], v[132:135], v[72:75]
	v_mfma_f32_16x16x32_bf16 v[48:51], v[56:59], v[148:151], v[48:51]
	v_mfma_f32_16x16x32_bf16 v[40:43], v[64:67], v[148:151], v[40:43]
	v_mfma_f32_16x16x32_bf16 v[32:35], v[56:59], v[164:167], v[32:35]
	v_mfma_f32_16x16x32_bf16 v[24:27], v[64:67], v[164:167], v[24:27]
	v_mfma_f32_16x16x32_bf16 v[16:19], v[56:59], v[180:183], v[16:19]
	v_mfma_f32_16x16x32_bf16 v[12:15], v[64:67], v[180:183], v[12:15]
	s_setprio 0
	s_barrier
	s_add_u32 s22, s54, 0x40000
	s_addc_u32 s23, s55, 0
	s_add_i32 s24, s25, s60
	v_lshl_add_u64 v[52:53], s[22:23], 0, v[2:3]
	s_mov_b32 m0, s24
	s_nop 0
	global_load_lds_dwordx4 v[52:53], off
	v_lshl_add_u64 v[52:53], s[22:23], 0, v[0:1]
	s_add_i32 m0, s24, 0x2000
	s_nop 0
	global_load_lds_dwordx4 v[52:53], off
	s_waitcnt vmcnt(10)
	s_barrier
	s_setprio 1
	v_mfma_f32_16x16x32_bf16 v[44:47], v[168:171], v[136:139], v[44:47]
	v_mfma_f32_16x16x32_bf16 v[36:39], v[184:187], v[136:139], v[36:39]
	v_mfma_f32_16x16x32_bf16 v[28:31], v[168:171], v[156:159], v[28:31]
	v_mfma_f32_16x16x32_bf16 v[20:23], v[184:187], v[156:159], v[20:23]
	v_mfma_f32_16x16x32_bf16 v[8:11], v[168:171], v[172:175], v[8:11]
	v_mfma_f32_16x16x32_bf16 v[4:7], v[184:187], v[172:175], v[4:7]
	v_mfma_f32_16x16x32_bf16 v[52:55], v[168:171], v[104:107], v[108:111]
	v_mfma_f32_16x16x32_bf16 v[56:59], v[184:187], v[104:107], v[68:71]
	v_mfma_f32_16x16x32_bf16 v[44:47], v[176:179], v[148:151], v[44:47]
	v_mfma_f32_16x16x32_bf16 v[36:39], v[192:195], v[148:151], v[36:39]
	v_mfma_f32_16x16x32_bf16 v[28:31], v[176:179], v[164:167], v[28:31]
	v_mfma_f32_16x16x32_bf16 v[20:23], v[192:195], v[164:167], v[20:23]
	v_mfma_f32_16x16x32_bf16 v[8:11], v[176:179], v[180:183], v[8:11]
	v_mfma_f32_16x16x32_bf16 v[4:7], v[192:195], v[180:183], v[4:7]
	v_mfma_f32_16x16x32_bf16 v[52:55], v[176:179], v[132:135], v[52:55]
	v_mfma_f32_16x16x32_bf16 v[56:59], v[192:195], v[132:135], v[56:59]
	s_setprio 0
	s_add_i32 s24, 0, 0x18000
	v_add_u32_e32 v104, s24, v235
	s_barrier
	ds_read_b128 v[60:63], v104
	ds_read_b128 v[64:67], v104 offset:1024
	ds_read_b128 v[68:71], v104 offset:2048
	ds_read_b128 v[104:107], v104 offset:3072
	s_add_u32 s22, s56, 0x40000
	s_addc_u32 s23, s57, 0
	s_mov_b32 m0, s64
	v_lshl_add_u64 v[156:157], s[22:23], 0, v[204:205]
	ds_read_b128 v[108:111], v239 offset:32768
	ds_read_b128 v[132:135], v239 offset:33792
	ds_read_b128 v[136:139], v239 offset:34816
	ds_read_b128 v[148:151], v239 offset:35840
	ds_read_b128 v[210:213], v239 offset:36864
	ds_read_b128 v[214:217], v239 offset:37888
	ds_read_b128 v[240:243], v239 offset:38912
	ds_read_b128 v[244:247], v239 offset:39936
	global_load_lds_dwordx4 v[156:157], off
	v_lshl_add_u64 v[156:157], s[22:23], 0, v[202:203]
	s_mov_b32 m0, s65
	s_nop 0
	global_load_lds_dwordx4 v[156:157], off
	s_waitcnt lgkmcnt(8)
	s_waitcnt vmcnt(10)
	s_barrier
	s_waitcnt lgkmcnt(0)
	s_setprio 1
	s_waitcnt lgkmcnt(0)
	v_mfma_f32_16x16x32_bf16 v[116:119], v[60:63], v[108:111], v[116:119]
	v_mfma_f32_16x16x32_bf16 v[192:195], v[64:67], v[132:135], v[116:119]
	v_mfma_f32_16x16x32_bf16 v[116:119], v[68:71], v[108:111], v[120:123]
	v_mfma_f32_16x16x32_bf16 v[184:187], v[104:107], v[132:135], v[116:119]
	v_mfma_f32_16x16x32_bf16 v[116:119], v[60:63], v[136:139], v[124:127]
	v_mfma_f32_16x16x32_bf16 v[176:179], v[64:67], v[148:151], v[116:119]
	v_mfma_f32_16x16x32_bf16 v[116:119], v[68:71], v[136:139], v[128:131]
	v_mfma_f32_16x16x32_bf16 v[168:171], v[104:107], v[148:151], v[116:119]
	v_mfma_f32_16x16x32_bf16 v[116:119], v[60:63], v[210:213], v[160:163]
	v_mfma_f32_16x16x32_bf16 v[160:163], v[64:67], v[214:217], v[116:119]
	v_mfma_f32_16x16x32_bf16 v[116:119], v[68:71], v[210:213], v[152:155]
	v_mfma_f32_16x16x32_bf16 v[152:155], v[104:107], v[214:217], v[116:119]
	v_mfma_f32_16x16x32_bf16 v[116:119], v[60:63], v[240:243], v[144:147]
	v_mfma_f32_16x16x32_bf16 v[144:147], v[64:67], v[244:247], v[116:119]
	v_mfma_f32_16x16x32_bf16 v[116:119], v[68:71], v[240:243], v[140:143]
	v_mfma_f32_16x16x32_bf16 v[140:143], v[104:107], v[244:247], v[116:119]
	s_setprio 0
	s_barrier
	s_add_i32 s25, 0, 0x1c000
	s_add_i32 s22, s24, s60
	v_add_u32_e32 v128, s25, v235
	v_lshl_add_u64 v[156:157], v[198:199], 0, s[76:77]
	s_mov_b32 m0, s22
	ds_read_b128 v[116:119], v128
	ds_read_b128 v[120:123], v128 offset:1024
	ds_read_b128 v[124:127], v128 offset:2048
	ds_read_b128 v[128:131], v128 offset:3072
	global_load_lds_dwordx4 v[156:157], off
	v_lshl_add_u64 v[156:157], v[222:223], 0, s[76:77]
	s_add_i32 m0, s22, 0x2000
	s_nop 0
	global_load_lds_dwordx4 v[156:157], off
	s_waitcnt vmcnt(10)
	s_barrier
	s_waitcnt lgkmcnt(0)
	s_setprio 1
	s_waitcnt lgkmcnt(0)
	v_mfma_f32_16x16x32_bf16 v[76:79], v[124:127], v[108:111], v[76:79]
	v_mfma_f32_16x16x32_bf16 v[180:183], v[128:131], v[132:135], v[76:79]
	v_mfma_f32_16x16x32_bf16 v[76:79], v[116:119], v[136:139], v[80:83]
	v_mfma_f32_16x16x32_bf16 v[172:175], v[120:123], v[148:151], v[76:79]
	v_mfma_f32_16x16x32_bf16 v[76:79], v[124:127], v[136:139], v[84:87]
	v_mfma_f32_16x16x32_bf16 v[156:159], v[116:119], v[108:111], v[188:191]
	v_mfma_f32_16x16x32_bf16 v[164:167], v[128:131], v[148:151], v[76:79]
	v_mfma_f32_16x16x32_bf16 v[76:79], v[116:119], v[210:213], v[88:91]
	v_mfma_f32_16x16x32_bf16 v[188:191], v[120:123], v[132:135], v[156:159]
	v_mfma_f32_16x16x32_bf16 v[156:159], v[120:123], v[214:217], v[76:79]
	v_mfma_f32_16x16x32_bf16 v[76:79], v[124:127], v[210:213], v[92:95]
	v_mfma_f32_16x16x32_bf16 v[148:151], v[128:131], v[214:217], v[76:79]
	v_mfma_f32_16x16x32_bf16 v[76:79], v[116:119], v[240:243], v[96:99]
	v_mfma_f32_16x16x32_bf16 v[136:139], v[120:123], v[244:247], v[76:79]
	v_mfma_f32_16x16x32_bf16 v[76:79], v[124:127], v[240:243], v[100:103]
	v_mfma_f32_16x16x32_bf16 v[132:135], v[128:131], v[244:247], v[76:79]
	s_setprio 0
	s_mov_b32 m0, s72
	v_lshl_add_u64 v[108:109], v[248:249], 0, s[76:77]
	s_barrier
	s_nop 2
	ds_read_b128 v[76:79], v239 offset:49152
	ds_read_b128 v[80:83], v239 offset:50176
	ds_read_b128 v[84:87], v239 offset:51200
	ds_read_b128 v[88:91], v239 offset:52224
	ds_read_b128 v[92:95], v239 offset:53248
	ds_read_b128 v[96:99], v239 offset:54272
	ds_read_b128 v[100:103], v239 offset:55296
	ds_read_b128 v[210:213], v239 offset:56320
	global_load_lds_dwordx4 v[108:109], off
	v_lshl_add_u64 v[108:109], v[250:251], 0, s[76:77]
	s_mov_b32 m0, s74
	s_nop 0
	global_load_lds_dwordx4 v[108:109], off
	s_barrier
	s_waitcnt lgkmcnt(0)
	s_setprio 1
	s_waitcnt lgkmcnt(0)
	v_mfma_f32_16x16x32_bf16 v[108:111], v[60:63], v[76:79], v[112:115]
	v_mfma_f32_16x16x32_bf16 v[72:75], v[68:71], v[76:79], v[72:75]
	v_mfma_f32_16x16x32_bf16 v[48:51], v[60:63], v[84:87], v[48:51]
	v_mfma_f32_16x16x32_bf16 v[40:43], v[68:71], v[84:87], v[40:43]
	v_mfma_f32_16x16x32_bf16 v[32:35], v[60:63], v[92:95], v[32:35]
	v_mfma_f32_16x16x32_bf16 v[24:27], v[68:71], v[92:95], v[24:27]
	v_mfma_f32_16x16x32_bf16 v[16:19], v[60:63], v[100:103], v[16:19]
	v_mfma_f32_16x16x32_bf16 v[12:15], v[68:71], v[100:103], v[12:15]
	v_mfma_f32_16x16x32_bf16 v[112:115], v[64:67], v[80:83], v[108:111]
	v_mfma_f32_16x16x32_bf16 v[72:75], v[104:107], v[80:83], v[72:75]
	v_mfma_f32_16x16x32_bf16 v[48:51], v[64:67], v[88:91], v[48:51]
	v_mfma_f32_16x16x32_bf16 v[40:43], v[104:107], v[88:91], v[40:43]
	v_mfma_f32_16x16x32_bf16 v[32:35], v[64:67], v[96:99], v[32:35]
	v_mfma_f32_16x16x32_bf16 v[24:27], v[104:107], v[96:99], v[24:27]
	v_mfma_f32_16x16x32_bf16 v[16:19], v[64:67], v[210:213], v[16:19]
	v_mfma_f32_16x16x32_bf16 v[12:15], v[104:107], v[210:213], v[12:15]
	s_setprio 0
	s_barrier
	s_add_u32 s22, s54, 0x40080
	s_addc_u32 s23, s55, 0
	s_add_i32 s24, s25, s60
	v_lshl_add_u64 v[60:61], s[22:23], 0, v[2:3]
	s_mov_b32 m0, s24
	s_nop 0
	global_load_lds_dwordx4 v[60:61], off
	v_lshl_add_u64 v[60:61], s[22:23], 0, v[0:1]
	s_add_i32 m0, s24, 0x2000
	s_nop 0
	global_load_lds_dwordx4 v[60:61], off
	s_waitcnt vmcnt(10)
	s_barrier
	s_setprio 1
	v_mfma_f32_16x16x32_bf16 v[52:55], v[116:119], v[76:79], v[52:55]
	v_mfma_f32_16x16x32_bf16 v[108:111], v[120:123], v[80:83], v[52:55]
	v_mfma_f32_16x16x32_bf16 v[52:55], v[124:127], v[76:79], v[56:59]
	v_mfma_f32_16x16x32_bf16 v[44:47], v[116:119], v[84:87], v[44:47]
	v_mfma_f32_16x16x32_bf16 v[36:39], v[124:127], v[84:87], v[36:39]
	v_mfma_f32_16x16x32_bf16 v[28:31], v[116:119], v[92:95], v[28:31]
	v_mfma_f32_16x16x32_bf16 v[20:23], v[124:127], v[92:95], v[20:23]
	v_mfma_f32_16x16x32_bf16 v[8:11], v[116:119], v[100:103], v[8:11]
	v_mfma_f32_16x16x32_bf16 v[4:7], v[124:127], v[100:103], v[4:7]
	v_mfma_f32_16x16x32_bf16 v[68:71], v[128:131], v[80:83], v[52:55]
	v_mfma_f32_16x16x32_bf16 v[44:47], v[120:123], v[88:91], v[44:47]
	v_mfma_f32_16x16x32_bf16 v[36:39], v[128:131], v[88:91], v[36:39]
	v_mfma_f32_16x16x32_bf16 v[28:31], v[120:123], v[96:99], v[28:31]
	v_mfma_f32_16x16x32_bf16 v[20:23], v[128:131], v[96:99], v[20:23]
	v_mfma_f32_16x16x32_bf16 v[8:11], v[120:123], v[210:213], v[8:11]
	v_mfma_f32_16x16x32_bf16 v[4:7], v[128:131], v[210:213], v[4:7]
	s_setprio 0
	s_add_i32 s21, s21, 2
	s_add_u32 s52, s52, 0x100
	s_addc_u32 s53, s53, 0
	s_add_u32 s1, s1, 0x100
	s_addc_u32 s20, s20, 0
	s_cmp_gt_u32 s21, 13
	s_barrier
	s_cbranch_scc0 .LBB0_80
	v_readlane_b32 s20, v252, 0
	v_lshl_or_b32 v210, s30, 7, v238
	v_readlane_b32 s21, v252, 1
	v_ashrrev_i32_e32 v211, 31, v210
	v_readlane_b32 s20, v252, 20
	v_lshlrev_b64 v[88:89], 2, v[210:211]
	v_readlane_b32 s21, v252, 21
	v_readlane_b32 s24, v252, 4
	v_readlane_b32 s25, v252, 5
	v_lshl_add_u64 v[54:55], s[20:21], 0, v[88:89]
	v_readlane_b32 s20, v252, 22
	v_readlane_b32 s21, v252, 23
	v_readlane_b32 s22, v252, 2
	v_readlane_b32 s23, v252, 3
	v_lshl_add_u64 v[52:53], s[24:25], 0, v[88:89]
	v_lshl_add_u64 v[60:61], s[20:21], 0, v[88:89]
	v_readlane_b32 s20, v252, 24
	global_load_dwordx4 v[80:83], v[52:53], off offset:16
	global_load_dwordx4 v[120:123], v[52:53], off
	global_load_dwordx4 v[76:79], v[54:55], off offset:16
	global_load_dwordx4 v[116:119], v[54:55], off
	v_lshl_add_u64 v[52:53], s[22:23], 0, v[88:89]
	v_readlane_b32 s21, v252, 25
	global_load_dwordx4 v[56:59], v[52:53], off offset:16
	global_load_dwordx4 v[96:99], v[52:53], off
	s_nop 0
	global_load_dwordx4 v[52:55], v[60:61], off offset:16
	global_load_dwordx4 v[92:95], v[60:61], off
	v_lshl_add_u64 v[60:61], s[20:21], 0, v[88:89]
	v_readlane_b32 s20, v252, 26
	v_readlane_b32 s21, v252, 27
	global_load_dwordx4 v[64:67], v[60:61], off offset:16
	global_load_dwordx4 v[104:107], v[60:61], off
	v_lshl_add_u64 v[84:85], s[20:21], 0, v[88:89]
	v_readlane_b32 s20, v252, 28
	v_readlane_b32 s21, v252, 29
	global_load_dwordx4 v[60:63], v[84:85], off offset:16
	global_load_dwordx4 v[100:103], v[84:85], off
	v_lshl_add_u64 v[90:91], s[20:21], 0, v[88:89]
	global_load_dwordx4 v[84:87], v[90:91], off offset:16
	global_load_dwordx4 v[124:127], v[90:91], off
	v_readlane_b32 s20, v252, 30
	v_readlane_b32 s21, v252, 31
	v_mov_b32_dpp v198, v192 row_ror:1 row_mask:0xf bank_mask:0xf
	v_mov_b32_dpp v199, v193 row_ror:1 row_mask:0xf bank_mask:0xf
	v_lshl_add_u64 v[128:129], s[20:21], 0, v[88:89]
	global_load_dwordx4 v[88:91], v[128:129], off offset:16
	s_nop 0
	global_load_dwordx4 v[128:131], v[128:129], off
	v_mov_b32_dpp v198, v192 row_shr:1 row_mask:0xf bank_mask:0xf
	v_mov_b32_dpp v212, v192 row_ror:2 row_mask:0xf bank_mask:0xf
	v_mov_b32_dpp v199, v193 row_shr:1 row_mask:0xf bank_mask:0xf
	v_mov_b32_dpp v213, v193 row_ror:2 row_mask:0xf bank_mask:0xf
	v_mov_b32_dpp v212, v192 row_shr:2 row_mask:0xf bank_mask:0xf
	v_mov_b32_dpp v214, v188 row_ror:1 row_mask:0xf bank_mask:0xf
	v_mov_b32_dpp v213, v193 row_shr:2 row_mask:0xf bank_mask:0xf
	v_mov_b32_dpp v215, v189 row_ror:1 row_mask:0xf bank_mask:0xf
	v_mov_b32_dpp v214, v188 row_shr:1 row_mask:0xf bank_mask:0xf
	v_mov_b32_dpp v216, v188 row_ror:2 row_mask:0xf bank_mask:0xf
	v_mov_b32_dpp v215, v189 row_shr:1 row_mask:0xf bank_mask:0xf
	v_mov_b32_dpp v217, v189 row_ror:2 row_mask:0xf bank_mask:0xf
	v_mov_b32_dpp v216, v188 row_shr:2 row_mask:0xf bank_mask:0xf
	s_lshl_b32 s1, s50, 8
	v_mov_b32_dpp v217, v189 row_shr:2 row_mask:0xf bank_mask:0xf
	s_add_i32 s1, s1, s67
	v_or_b32_e32 v240, s1, v201
	s_movk_i32 s2, 0x1600
	v_readlane_b32 s26, v252, 6
	v_readlane_b32 s27, v252, 7
	s_waitcnt vmcnt(0)
	v_pk_fma_f32 v[246:247], v[184:185], v[84:85], v[80:81]
	v_pk_fma_f32 v[242:243], v[192:193], v[124:125], v[120:121]
	v_pk_fma_f32 v[222:223], v[194:195], v[126:127], v[122:123]
	v_pk_fma_f32 v[198:199], v[104:105], v[198:199], v[242:243]
	v_pk_fma_f32 v[248:249], v[180:181], v[88:89], v[76:77]
	v_pk_fma_f32 v[198:199], v[96:97], v[212:213], v[198:199]
	v_pk_fma_f32 v[244:245], v[188:189], v[128:129], v[116:117]
	v_mul_f32_e32 v212, 0xbfb8aa3b, v198
	v_mul_f32_e32 v213, 0xbfb8aa3b, v199
	v_exp_f32_e32 v212, v212
	v_exp_f32_e32 v213, v213
	v_pk_fma_f32 v[214:215], v[100:101], v[214:215], v[244:245]
	v_pk_fma_f32 v[242:243], v[190:191], v[130:131], v[118:119]
	v_add_f32_e32 v212, 1.0, v212
	v_add_f32_e32 v213, 1.0, v213
	v_rcp_f32_e32 v212, v212
	v_rcp_f32_e32 v213, v213
	v_pk_fma_f32 v[214:215], v[92:93], v[216:217], v[214:215]
	v_mov_b32_dpp v216, v190 row_ror:1 row_mask:0xf bank_mask:0xf
	v_mov_b32_dpp v217, v191 row_ror:1 row_mask:0xf bank_mask:0xf
	v_pk_mul_f32 v[198:199], v[198:199], v[212:213]
	v_mov_b32_dpp v216, v190 row_shr:1 row_mask:0xf bank_mask:0xf
	v_pk_mul_f32 v[212:213], v[214:215], v[198:199]
	v_mov_b32_dpp v198, v194 row_ror:1 row_mask:0xf bank_mask:0xf
	v_mov_b32_dpp v199, v195 row_ror:1 row_mask:0xf bank_mask:0xf
	v_mov_b32_dpp v214, v194 row_ror:2 row_mask:0xf bank_mask:0xf
	v_mov_b32_dpp v198, v194 row_shr:1 row_mask:0xf bank_mask:0xf
	v_mov_b32_dpp v199, v195 row_shr:1 row_mask:0xf bank_mask:0xf
	v_mov_b32_dpp v215, v195 row_ror:2 row_mask:0xf bank_mask:0xf
	v_mov_b32_dpp v214, v194 row_shr:2 row_mask:0xf bank_mask:0xf
	v_pk_fma_f32 v[198:199], v[106:107], v[198:199], v[222:223]
	v_mov_b32_dpp v215, v195 row_shr:2 row_mask:0xf bank_mask:0xf
	v_pk_fma_f32 v[198:199], v[98:99], v[214:215], v[198:199]
	v_mov_b32_dpp v244, v190 row_ror:2 row_mask:0xf bank_mask:0xf
	v_mul_f32_e32 v214, 0xbfb8aa3b, v198
	v_mul_f32_e32 v215, 0xbfb8aa3b, v199
	v_exp_f32_e32 v214, v214
	v_exp_f32_e32 v215, v215
	v_mov_b32_dpp v217, v191 row_shr:1 row_mask:0xf bank_mask:0xf
	v_mov_b32_dpp v245, v191 row_ror:2 row_mask:0xf bank_mask:0xf
	v_add_f32_e32 v214, 1.0, v214
	v_add_f32_e32 v215, 1.0, v215
	v_rcp_f32_e32 v214, v214
	v_rcp_f32_e32 v215, v215
	v_mov_b32_dpp v244, v190 row_shr:2 row_mask:0xf bank_mask:0xf
	v_mov_b32_dpp v245, v191 row_shr:2 row_mask:0xf bank_mask:0xf
	v_pk_fma_f32 v[216:217], v[102:103], v[216:217], v[242:243]
	v_pk_mul_f32 v[198:199], v[198:199], v[214:215]
	v_pk_fma_f32 v[216:217], v[94:95], v[244:245], v[216:217]
	v_mov_b32_dpp v222, v180 row_ror:1 row_mask:0xf bank_mask:0xf
	v_pk_mul_f32 v[214:215], v[216:217], v[198:199]
	v_mov_b32_dpp v216, v184 row_ror:1 row_mask:0xf bank_mask:0xf
	v_mov_b32_dpp v217, v185 row_ror:1 row_mask:0xf bank_mask:0xf
	v_mov_b32_dpp v198, v184 row_ror:2 row_mask:0xf bank_mask:0xf
	v_mov_b32_dpp v216, v184 row_shr:1 row_mask:0xf bank_mask:0xf
	v_mov_b32_dpp v217, v185 row_shr:1 row_mask:0xf bank_mask:0xf
	v_mov_b32_dpp v199, v185 row_ror:2 row_mask:0xf bank_mask:0xf
	v_mov_b32_dpp v198, v184 row_shr:2 row_mask:0xf bank_mask:0xf
	v_pk_fma_f32 v[216:217], v[64:65], v[216:217], v[246:247]
	v_mov_b32_dpp v199, v185 row_shr:2 row_mask:0xf bank_mask:0xf
	v_pk_fma_f32 v[198:199], v[56:57], v[198:199], v[216:217]
	v_mov_b32_dpp v223, v181 row_ror:1 row_mask:0xf bank_mask:0xf
	v_mul_f32_e32 v216, 0xbfb8aa3b, v198
	v_mul_f32_e32 v217, 0xbfb8aa3b, v199
	v_exp_f32_e32 v216, v216
	v_exp_f32_e32 v217, v217
	v_mov_b32_dpp v222, v180 row_shr:1 row_mask:0xf bank_mask:0xf
	v_mov_b32_dpp v242, v180 row_ror:2 row_mask:0xf bank_mask:0xf
	v_add_f32_e32 v216, 1.0, v216
	v_add_f32_e32 v217, 1.0, v217
	v_rcp_f32_e32 v216, v216
	v_rcp_f32_e32 v217, v217
	v_mov_b32_dpp v223, v181 row_shr:1 row_mask:0xf bank_mask:0xf
	v_mov_b32_dpp v243, v181 row_ror:2 row_mask:0xf bank_mask:0xf
	v_mov_b32_dpp v242, v180 row_shr:2 row_mask:0xf bank_mask:0xf
	v_pk_fma_f32 v[222:223], v[60:61], v[222:223], v[248:249]
	v_mov_b32_dpp v243, v181 row_shr:2 row_mask:0xf bank_mask:0xf
	v_pk_fma_f32 v[222:223], v[52:53], v[242:243], v[222:223]
	v_pk_mul_f32 v[198:199], v[198:199], v[216:217]
	v_mov_b32_dpp v216, v186 row_ror:1 row_mask:0xf bank_mask:0xf
	v_mov_b32_dpp v217, v187 row_ror:1 row_mask:0xf bank_mask:0xf
	v_pk_fma_f32 v[244:245], v[186:187], v[86:87], v[82:83]
	v_pk_mul_f32 v[198:199], v[222:223], v[198:199]
	v_mov_b32_dpp v216, v186 row_shr:1 row_mask:0xf bank_mask:0xf
	v_mov_b32_dpp v222, v186 row_ror:2 row_mask:0xf bank_mask:0xf
	v_mov_b32_dpp v217, v187 row_shr:1 row_mask:0xf bank_mask:0xf
	v_mov_b32_dpp v223, v187 row_ror:2 row_mask:0xf bank_mask:0xf
	v_mov_b32_dpp v222, v186 row_shr:2 row_mask:0xf bank_mask:0xf
	v_pk_fma_f32 v[216:217], v[66:67], v[216:217], v[244:245]
	v_mov_b32_dpp v223, v187 row_shr:2 row_mask:0xf bank_mask:0xf
	v_pk_fma_f32 v[216:217], v[58:59], v[222:223], v[216:217]
	v_mov_b32_dpp v242, v182 row_ror:1 row_mask:0xf bank_mask:0xf
	v_mul_f32_e32 v219, 0xbfb8aa3b, v216
	v_exp_f32_e32 v219, v219
	v_mov_b32_dpp v243, v183 row_ror:1 row_mask:0xf bank_mask:0xf
	v_pk_fma_f32 v[246:247], v[182:183], v[90:91], v[78:79]
	v_mov_b32_dpp v242, v182 row_shr:1 row_mask:0xf bank_mask:0xf
	v_add_f32_e32 v219, 1.0, v219
	v_rcp_f32_e32 v222, v219
	v_mul_f32_e32 v219, 0xbfb8aa3b, v217
	v_exp_f32_e32 v219, v219
	v_mov_b32_dpp v248, v182 row_ror:2 row_mask:0xf bank_mask:0xf
	v_mov_b32_dpp v243, v183 row_shr:1 row_mask:0xf bank_mask:0xf
	v_mov_b32_dpp v249, v183 row_ror:2 row_mask:0xf bank_mask:0xf
	v_add_f32_e32 v219, 1.0, v219
	v_rcp_f32_e32 v223, v219
	v_mov_b32_dpp v248, v182 row_shr:2 row_mask:0xf bank_mask:0xf
	v_mov_b32_dpp v249, v183 row_shr:2 row_mask:0xf bank_mask:0xf
	v_pk_fma_f32 v[242:243], v[62:63], v[242:243], v[246:247]
	v_pk_mul_f32 v[216:217], v[216:217], v[222:223]
	v_pk_fma_f32 v[242:243], v[54:55], v[248:249], v[242:243]
	v_cvt_pk_bf16_f32 v212, v212, v213
	v_cvt_pk_bf16_f32 v213, v214, v215
	v_cvt_pk_bf16_f32 v214, v198, v199
	v_mov_b64_e32 v[198:199], s[82:83]
	v_pk_mul_f32 v[216:217], v[242:243], v[216:217]
	v_mad_i64_i32 v[198:199], s[20:21], v240, s2, v[198:199]
	v_cvt_pk_bf16_f32 v215, v216, v217
	v_lshl_add_u64 v[198:199], v[210:211], 1, v[198:199]
	global_store_dwordx4 v[198:199], v[212:215], off
	s_and_saveexec_b64 s[50:51], s[38:39]
	v_readlane_b32 s56, v254, 63
	v_readlane_b32 s57, v255, 0
	s_cbranch_execz .LBB0_83
	s_ashr_i32 s20, s1, 4
	v_or_b32_e32 v212, s20, v237
	v_mov_b64_e32 v[198:199], s[56:57]
	s_movk_i32 s2, 0x2c00
	v_mad_i64_i32 v[198:199], s[20:21], v212, s2, v[198:199]
	v_lshl_add_u64 v[198:199], v[210:211], 1, v[198:199]
	v_cvt_pk_bf16_f32 v212, v192, v193
	v_cvt_pk_bf16_f32 v213, v194, v195
	v_cvt_pk_bf16_f32 v214, v184, v185
	v_cvt_pk_bf16_f32 v215, v186, v187
	global_store_dwordx4 v[198:199], v[212:215], off
	v_add_co_u32_e32 v198, vcc, 0x1000, v198
	s_nop 0
	v_cvt_pk_bf16_f32 v212, v188, v189
	v_cvt_pk_bf16_f32 v213, v190, v191
	v_cvt_pk_bf16_f32 v214, v180, v181
	v_cvt_pk_bf16_f32 v215, v182, v183
	v_addc_co_u32_e32 v199, vcc, 0, v199, vcc
	global_store_dwordx4 v[198:199], v[212:215], off offset:1536

.LBB0_136:
	s_add_u32 s23, s48, 0xfffc0080
	s_addc_u32 s24, s49, -1
	s_add_i32 s25, 0, 0x10000
	v_add_u32_e32 v145, s25, v143
	ds_read_b128 v[146:149], v145
	ds_read_b128 v[150:153], v145 offset:1024
	ds_read_b128 v[154:157], v145 offset:2048
	ds_read_b128 v[158:161], v145 offset:3072
	s_cmp_eq_u32 s22, 12
	s_cselect_b32 s53, s45, s24
	s_cselect_b32 s52, s44, s23
	s_cselect_b32 s51, s47, s21
	s_cselect_b32 s50, s46, s20
	v_lshl_add_u64 v[194:195], s[48:49], 0, v[138:139]
	s_add_i32 m0, s54, 0xc000
	ds_read_b128 v[162:165], v144
	ds_read_b128 v[166:169], v144 offset:1024
	ds_read_b128 v[170:173], v144 offset:2048
	ds_read_b128 v[174:177], v144 offset:3072
	ds_read_b128 v[178:181], v144 offset:4096
	ds_read_b128 v[182:185], v144 offset:5120
	ds_read_b128 v[186:189], v144 offset:6144
	ds_read_b128 v[190:193], v144 offset:7168
	global_load_lds_dwordx4 v[194:195], off
	v_lshl_add_u64 v[194:195], s[48:49], 0, v[140:141]
	s_add_i32 m0, s54, 0xe000
	s_nop 0
	global_load_lds_dwordx4 v[194:195], off
	s_waitcnt lgkmcnt(8)
	s_waitcnt vmcnt(10)
	s_barrier
	s_waitcnt lgkmcnt(0)
	s_setprio 1
	s_waitcnt lgkmcnt(0)
	v_mfma_f32_16x16x32_bf16 v[128:131], v[146:149], v[162:165], v[128:131]
	v_mfma_f32_16x16x32_bf16 v[124:127], v[154:157], v[162:165], v[124:127]
	v_mfma_f32_16x16x32_bf16 v[120:123], v[146:149], v[170:173], v[120:123]
	v_mfma_f32_16x16x32_bf16 v[116:119], v[154:157], v[170:173], v[116:119]
	v_mfma_f32_16x16x32_bf16 v[104:107], v[146:149], v[178:181], v[104:107]
	v_mfma_f32_16x16x32_bf16 v[100:103], v[154:157], v[178:181], v[100:103]
	v_mfma_f32_16x16x32_bf16 v[88:91], v[146:149], v[186:189], v[88:91]
	v_mfma_f32_16x16x32_bf16 v[84:87], v[154:157], v[186:189], v[84:87]
	v_mfma_f32_16x16x32_bf16 v[128:131], v[150:153], v[166:169], v[128:131]
	v_mfma_f32_16x16x32_bf16 v[124:127], v[158:161], v[166:169], v[124:127]
	v_mfma_f32_16x16x32_bf16 v[120:123], v[150:153], v[174:177], v[120:123]
	v_mfma_f32_16x16x32_bf16 v[116:119], v[158:161], v[174:177], v[116:119]
	v_mfma_f32_16x16x32_bf16 v[104:107], v[150:153], v[182:185], v[104:107]
	v_mfma_f32_16x16x32_bf16 v[100:103], v[158:161], v[182:185], v[100:103]
	v_mfma_f32_16x16x32_bf16 v[88:91], v[150:153], v[190:193], v[88:91]
	v_mfma_f32_16x16x32_bf16 v[84:87], v[158:161], v[190:193], v[84:87]
	s_setprio 0
	s_barrier
	s_add_i32 s23, 0, 0x14000
	s_add_i32 s24, s25, s37
	v_add_u32_e32 v145, s23, v143
	v_lshl_add_u64 v[194:195], s[50:51], 0, v[132:133]
	s_mov_b32 m0, s24
	ds_read_b128 v[202:205], v145
	ds_read_b128 v[206:209], v145 offset:1024
	ds_read_b128 v[210:213], v145 offset:2048
	ds_read_b128 v[214:217], v145 offset:3072
	global_load_lds_dwordx4 v[194:195], off
	v_lshl_add_u64 v[198:199], s[50:51], 0, v[136:137]
	s_add_i32 m0, s24, 0x2000
	s_nop 0
	global_load_lds_dwordx4 v[198:199], off
	s_waitcnt vmcnt(10)
	s_barrier
	s_waitcnt lgkmcnt(0)
	s_setprio 1
	s_waitcnt lgkmcnt(0)
	v_mfma_f32_16x16x32_bf16 v[112:115], v[202:205], v[162:165], v[112:115]
	v_mfma_f32_16x16x32_bf16 v[108:111], v[210:213], v[162:165], v[108:111]
	v_mfma_f32_16x16x32_bf16 v[96:99], v[202:205], v[170:173], v[96:99]
	v_mfma_f32_16x16x32_bf16 v[92:95], v[210:213], v[170:173], v[92:95]
	v_mfma_f32_16x16x32_bf16 v[80:83], v[202:205], v[178:181], v[80:83]
	v_mfma_f32_16x16x32_bf16 v[76:79], v[210:213], v[178:181], v[76:79]
	v_mfma_f32_16x16x32_bf16 v[72:75], v[202:205], v[186:189], v[72:75]
	v_mfma_f32_16x16x32_bf16 v[68:71], v[210:213], v[186:189], v[68:71]
	v_mfma_f32_16x16x32_bf16 v[112:115], v[206:209], v[166:169], v[112:115]
	v_mfma_f32_16x16x32_bf16 v[108:111], v[214:217], v[166:169], v[108:111]
	v_mfma_f32_16x16x32_bf16 v[96:99], v[206:209], v[174:177], v[96:99]
	v_mfma_f32_16x16x32_bf16 v[92:95], v[214:217], v[174:177], v[92:95]
	v_mfma_f32_16x16x32_bf16 v[80:83], v[206:209], v[182:185], v[80:83]
	v_mfma_f32_16x16x32_bf16 v[76:79], v[214:217], v[182:185], v[76:79]
	v_mfma_f32_16x16x32_bf16 v[72:75], v[206:209], v[190:193], v[72:75]
	v_mfma_f32_16x16x32_bf16 v[68:71], v[214:217], v[190:193], v[68:71]
	s_setprio 0
	s_mov_b32 m0, s54
	v_lshl_add_u64 v[222:223], s[52:53], 0, v[0:1]
	s_barrier
	ds_read_b128 v[162:165], v144 offset:16384
	ds_read_b128 v[166:169], v144 offset:17408
	ds_read_b128 v[170:173], v144 offset:18432
	ds_read_b128 v[174:177], v144 offset:19456
	ds_read_b128 v[178:181], v144 offset:20480
	ds_read_b128 v[182:185], v144 offset:21504
	ds_read_b128 v[186:189], v144 offset:22528
	ds_read_b128 v[190:193], v144 offset:23552
	global_load_lds_dwordx4 v[222:223], off
	v_lshl_add_u64 v[236:237], s[52:53], 0, v[134:135]
	s_mov_b32 m0, s55
	s_nop 0
	global_load_lds_dwordx4 v[236:237], off
	s_barrier
	s_waitcnt lgkmcnt(0)
	s_setprio 1
	s_waitcnt lgkmcnt(0)
	v_mfma_f32_16x16x32_bf16 v[64:67], v[146:149], v[162:165], v[64:67]
	v_mfma_f32_16x16x32_bf16 v[60:63], v[154:157], v[162:165], v[60:63]
	v_mfma_f32_16x16x32_bf16 v[56:59], v[146:149], v[170:173], v[56:59]
	v_mfma_f32_16x16x32_bf16 v[52:55], v[154:157], v[170:173], v[52:55]
	v_mfma_f32_16x16x32_bf16 v[40:43], v[146:149], v[178:181], v[40:43]
	v_mfma_f32_16x16x32_bf16 v[36:39], v[154:157], v[178:181], v[36:39]
	v_mfma_f32_16x16x32_bf16 v[24:27], v[146:149], v[186:189], v[24:27]
	v_mfma_f32_16x16x32_bf16 v[16:19], v[154:157], v[186:189], v[16:19]
	v_mfma_f32_16x16x32_bf16 v[64:67], v[150:153], v[166:169], v[64:67]
	v_mfma_f32_16x16x32_bf16 v[60:63], v[158:161], v[166:169], v[60:63]
	v_mfma_f32_16x16x32_bf16 v[56:59], v[150:153], v[174:177], v[56:59]
	v_mfma_f32_16x16x32_bf16 v[52:55], v[158:161], v[174:177], v[52:55]
	v_mfma_f32_16x16x32_bf16 v[40:43], v[150:153], v[182:185], v[40:43]
	v_mfma_f32_16x16x32_bf16 v[36:39], v[158:161], v[182:185], v[36:39]
	v_mfma_f32_16x16x32_bf16 v[24:27], v[150:153], v[190:193], v[24:27]
	v_mfma_f32_16x16x32_bf16 v[16:19], v[158:161], v[190:193], v[16:19]
	s_setprio 0
	s_barrier
	s_add_u32 s24, s50, 0x40000
	s_addc_u32 s25, s51, 0
	s_add_i32 s23, s23, s37
	v_lshl_add_u64 v[146:147], s[24:25], 0, v[132:133]
	s_mov_b32 m0, s23
	s_nop 0
	global_load_lds_dwordx4 v[146:147], off
	v_lshl_add_u64 v[146:147], s[24:25], 0, v[136:137]
	s_add_i32 m0, s23, 0x2000
	s_nop 0
	global_load_lds_dwordx4 v[146:147], off
	s_waitcnt vmcnt(10)
	s_barrier
	s_setprio 1
	v_mfma_f32_16x16x32_bf16 v[48:51], v[202:205], v[162:165], v[48:51]
	v_mfma_f32_16x16x32_bf16 v[44:47], v[210:213], v[162:165], v[44:47]
	v_mfma_f32_16x16x32_bf16 v[32:35], v[202:205], v[170:173], v[32:35]
	v_mfma_f32_16x16x32_bf16 v[28:31], v[210:213], v[170:173], v[28:31]
	v_mfma_f32_16x16x32_bf16 v[20:23], v[202:205], v[178:181], v[20:23]
	v_mfma_f32_16x16x32_bf16 v[12:15], v[210:213], v[178:181], v[12:15]
	v_mfma_f32_16x16x32_bf16 v[8:11], v[202:205], v[186:189], v[8:11]
	v_mfma_f32_16x16x32_bf16 v[4:7], v[210:213], v[186:189], v[4:7]
	v_mfma_f32_16x16x32_bf16 v[48:51], v[206:209], v[166:169], v[48:51]
	v_mfma_f32_16x16x32_bf16 v[44:47], v[214:217], v[166:169], v[44:47]
	v_mfma_f32_16x16x32_bf16 v[32:35], v[206:209], v[174:177], v[32:35]
	v_mfma_f32_16x16x32_bf16 v[28:31], v[214:217], v[174:177], v[28:31]
	v_mfma_f32_16x16x32_bf16 v[20:23], v[206:209], v[182:185], v[20:23]
	v_mfma_f32_16x16x32_bf16 v[12:15], v[214:217], v[182:185], v[12:15]
	v_mfma_f32_16x16x32_bf16 v[8:11], v[206:209], v[190:193], v[8:11]
	v_mfma_f32_16x16x32_bf16 v[4:7], v[214:217], v[190:193], v[4:7]
	s_setprio 0
	s_add_i32 s23, 0, 0x18000
	v_add_u32_e32 v145, s23, v143
	s_barrier
	ds_read_b128 v[146:149], v145
	ds_read_b128 v[150:153], v145 offset:1024
	ds_read_b128 v[154:157], v145 offset:2048
	ds_read_b128 v[158:161], v145 offset:3072
	s_add_u32 s24, s52, 0x40000
	s_addc_u32 s25, s53, 0
	s_mov_b32 m0, s56
	v_lshl_add_u64 v[202:203], s[24:25], 0, v[0:1]
	ds_read_b128 v[162:165], v144 offset:32768
	ds_read_b128 v[166:169], v144 offset:33792
	ds_read_b128 v[170:173], v144 offset:34816
	ds_read_b128 v[174:177], v144 offset:35840
	ds_read_b128 v[178:181], v144 offset:36864
	ds_read_b128 v[182:185], v144 offset:37888
	ds_read_b128 v[186:189], v144 offset:38912
	ds_read_b128 v[190:193], v144 offset:39936
	global_load_lds_dwordx4 v[202:203], off
	v_lshl_add_u64 v[202:203], s[24:25], 0, v[134:135]
	s_mov_b32 m0, s57
	s_nop 0
	global_load_lds_dwordx4 v[202:203], off
	s_waitcnt lgkmcnt(8)
	s_waitcnt vmcnt(10)
	s_barrier
	s_waitcnt lgkmcnt(0)
	s_setprio 1
	s_waitcnt lgkmcnt(0)
	v_mfma_f32_16x16x32_bf16 v[128:131], v[146:149], v[162:165], v[128:131]
	v_mfma_f32_16x16x32_bf16 v[124:127], v[154:157], v[162:165], v[124:127]
	v_mfma_f32_16x16x32_bf16 v[120:123], v[146:149], v[170:173], v[120:123]
	v_mfma_f32_16x16x32_bf16 v[116:119], v[154:157], v[170:173], v[116:119]
	v_mfma_f32_16x16x32_bf16 v[104:107], v[146:149], v[178:181], v[104:107]
	v_mfma_f32_16x16x32_bf16 v[100:103], v[154:157], v[178:181], v[100:103]
	v_mfma_f32_16x16x32_bf16 v[88:91], v[146:149], v[186:189], v[88:91]
	v_mfma_f32_16x16x32_bf16 v[84:87], v[154:157], v[186:189], v[84:87]
	v_mfma_f32_16x16x32_bf16 v[128:131], v[150:153], v[166:169], v[128:131]
	v_mfma_f32_16x16x32_bf16 v[124:127], v[158:161], v[166:169], v[124:127]
	v_mfma_f32_16x16x32_bf16 v[120:123], v[150:153], v[174:177], v[120:123]
	v_mfma_f32_16x16x32_bf16 v[116:119], v[158:161], v[174:177], v[116:119]
	v_mfma_f32_16x16x32_bf16 v[104:107], v[150:153], v[182:185], v[104:107]
	v_mfma_f32_16x16x32_bf16 v[100:103], v[158:161], v[182:185], v[100:103]
	v_mfma_f32_16x16x32_bf16 v[88:91], v[150:153], v[190:193], v[88:91]
	v_mfma_f32_16x16x32_bf16 v[84:87], v[158:161], v[190:193], v[84:87]
	s_setprio 0
	s_barrier
	s_add_i32 s26, 0, 0x1c000
	s_add_i32 s23, s23, s37
	v_add_u32_e32 v145, s26, v143
	v_lshl_add_u64 v[194:195], v[194:195], 0, s[76:77]
	s_mov_b32 m0, s23
	ds_read_b128 v[202:205], v145
	ds_read_b128 v[206:209], v145 offset:1024
	ds_read_b128 v[210:213], v145 offset:2048
	ds_read_b128 v[214:217], v145 offset:3072
	global_load_lds_dwordx4 v[194:195], off
	v_lshl_add_u64 v[194:195], v[198:199], 0, s[76:77]
	s_add_i32 m0, s23, 0x2000
	s_nop 0
	global_load_lds_dwordx4 v[194:195], off
	s_waitcnt vmcnt(10)
	s_barrier
	s_waitcnt lgkmcnt(0)
	s_setprio 1
	s_waitcnt lgkmcnt(0)
	v_mfma_f32_16x16x32_bf16 v[112:115], v[202:205], v[162:165], v[112:115]
	v_mfma_f32_16x16x32_bf16 v[108:111], v[210:213], v[162:165], v[108:111]
	v_mfma_f32_16x16x32_bf16 v[96:99], v[202:205], v[170:173], v[96:99]
	v_mfma_f32_16x16x32_bf16 v[92:95], v[210:213], v[170:173], v[92:95]
	v_mfma_f32_16x16x32_bf16 v[80:83], v[202:205], v[178:181], v[80:83]
	v_mfma_f32_16x16x32_bf16 v[76:79], v[210:213], v[178:181], v[76:79]
	v_mfma_f32_16x16x32_bf16 v[72:75], v[202:205], v[186:189], v[72:75]
	v_mfma_f32_16x16x32_bf16 v[68:71], v[210:213], v[186:189], v[68:71]
	v_mfma_f32_16x16x32_bf16 v[112:115], v[206:209], v[166:169], v[112:115]
	v_mfma_f32_16x16x32_bf16 v[108:111], v[214:217], v[166:169], v[108:111]
	v_mfma_f32_16x16x32_bf16 v[96:99], v[206:209], v[174:177], v[96:99]
	v_mfma_f32_16x16x32_bf16 v[92:95], v[214:217], v[174:177], v[92:95]
	v_mfma_f32_16x16x32_bf16 v[80:83], v[206:209], v[182:185], v[80:83]
	v_mfma_f32_16x16x32_bf16 v[76:79], v[214:217], v[182:185], v[76:79]
	v_mfma_f32_16x16x32_bf16 v[72:75], v[206:209], v[190:193], v[72:75]
	v_mfma_f32_16x16x32_bf16 v[68:71], v[214:217], v[190:193], v[68:71]
	s_setprio 0
	s_mov_b32 m0, s59
	v_lshl_add_u64 v[194:195], v[222:223], 0, s[76:77]
	s_barrier
	ds_read_b128 v[162:165], v144 offset:49152
	ds_read_b128 v[166:169], v144 offset:50176
	ds_read_b128 v[170:173], v144 offset:51200
	ds_read_b128 v[174:177], v144 offset:52224
	ds_read_b128 v[178:181], v144 offset:53248
	ds_read_b128 v[182:185], v144 offset:54272
	ds_read_b128 v[186:189], v144 offset:55296
	ds_read_b128 v[190:193], v144 offset:56320
	global_load_lds_dwordx4 v[194:195], off
	v_lshl_add_u64 v[194:195], v[236:237], 0, s[76:77]
	s_mov_b32 m0, s60
	s_nop 0
	global_load_lds_dwordx4 v[194:195], off
	s_barrier
	s_waitcnt lgkmcnt(0)
	s_setprio 1
	s_waitcnt lgkmcnt(0)
	v_mfma_f32_16x16x32_bf16 v[64:67], v[146:149], v[162:165], v[64:67]
	v_mfma_f32_16x16x32_bf16 v[60:63], v[154:157], v[162:165], v[60:63]
	v_mfma_f32_16x16x32_bf16 v[56:59], v[146:149], v[170:173], v[56:59]
	v_mfma_f32_16x16x32_bf16 v[52:55], v[154:157], v[170:173], v[52:55]
	v_mfma_f32_16x16x32_bf16 v[40:43], v[146:149], v[178:181], v[40:43]
	v_mfma_f32_16x16x32_bf16 v[36:39], v[154:157], v[178:181], v[36:39]
	v_mfma_f32_16x16x32_bf16 v[24:27], v[146:149], v[186:189], v[24:27]
	v_mfma_f32_16x16x32_bf16 v[16:19], v[154:157], v[186:189], v[16:19]
	v_mfma_f32_16x16x32_bf16 v[64:67], v[150:153], v[166:169], v[64:67]
	v_mfma_f32_16x16x32_bf16 v[60:63], v[158:161], v[166:169], v[60:63]
	v_mfma_f32_16x16x32_bf16 v[56:59], v[150:153], v[174:177], v[56:59]
	v_mfma_f32_16x16x32_bf16 v[52:55], v[158:161], v[174:177], v[52:55]
	v_mfma_f32_16x16x32_bf16 v[40:43], v[150:153], v[182:185], v[40:43]
	v_mfma_f32_16x16x32_bf16 v[36:39], v[158:161], v[182:185], v[36:39]
	v_mfma_f32_16x16x32_bf16 v[24:27], v[150:153], v[190:193], v[24:27]
	v_mfma_f32_16x16x32_bf16 v[16:19], v[158:161], v[190:193], v[16:19]
	s_setprio 0
	s_barrier
	s_add_u32 s24, s50, 0x40080
	s_addc_u32 s25, s51, 0
	s_add_i32 s23, s26, s37
	v_lshl_add_u64 v[146:147], s[24:25], 0, v[132:133]
	s_mov_b32 m0, s23
	s_nop 0
	global_load_lds_dwordx4 v[146:147], off
	v_lshl_add_u64 v[146:147], s[24:25], 0, v[136:137]
	s_add_i32 m0, s23, 0x2000
	s_nop 0
	global_load_lds_dwordx4 v[146:147], off
	s_waitcnt vmcnt(10)
	s_barrier
	s_setprio 1
	v_mfma_f32_16x16x32_bf16 v[48:51], v[202:205], v[162:165], v[48:51]
	v_mfma_f32_16x16x32_bf16 v[44:47], v[210:213], v[162:165], v[44:47]
	v_mfma_f32_16x16x32_bf16 v[32:35], v[202:205], v[170:173], v[32:35]
	v_mfma_f32_16x16x32_bf16 v[28:31], v[210:213], v[170:173], v[28:31]
	v_mfma_f32_16x16x32_bf16 v[20:23], v[202:205], v[178:181], v[20:23]
	v_mfma_f32_16x16x32_bf16 v[12:15], v[210:213], v[178:181], v[12:15]
	v_mfma_f32_16x16x32_bf16 v[8:11], v[202:205], v[186:189], v[8:11]
	v_mfma_f32_16x16x32_bf16 v[4:7], v[210:213], v[186:189], v[4:7]
	v_mfma_f32_16x16x32_bf16 v[48:51], v[206:209], v[166:169], v[48:51]
	v_mfma_f32_16x16x32_bf16 v[44:47], v[214:217], v[166:169], v[44:47]
	v_mfma_f32_16x16x32_bf16 v[32:35], v[206:209], v[174:177], v[32:35]
	v_mfma_f32_16x16x32_bf16 v[28:31], v[214:217], v[174:177], v[28:31]
	v_mfma_f32_16x16x32_bf16 v[20:23], v[206:209], v[182:185], v[20:23]
	v_mfma_f32_16x16x32_bf16 v[12:15], v[214:217], v[182:185], v[12:15]
	v_mfma_f32_16x16x32_bf16 v[8:11], v[206:209], v[190:193], v[8:11]
	v_mfma_f32_16x16x32_bf16 v[4:7], v[214:217], v[190:193], v[4:7]
	s_setprio 0
	s_add_i32 s22, s22, 2
	s_add_u32 s48, s48, 0x100
	s_addc_u32 s49, s49, 0
	s_add_u32 s20, s20, 0x100
	s_addc_u32 s21, s21, 0
	s_cmp_gt_u32 s22, 13
	s_barrier
	s_cbranch_scc0 .LBB0_136
	v_lshl_add_u32 v146, s0, 8, v142
	v_cvt_pk_bf16_f32 v72, v72, v73
	v_cvt_pk_bf16_f32 v73, v74, v75
	v_cvt_pk_bf16_f32 v74, v68, v69
	v_add_u32_e32 v68, 0x80, v146
	s_lshl_b32 s0, s1, 8
	v_ashrrev_i32_e32 v147, 31, v146
	v_readlane_b32 s20, v252, 12
	v_cvt_pk_bf16_f32 v112, v112, v113
	v_cvt_pk_bf16_f32 v113, v114, v115
	v_cvt_pk_bf16_f32 v114, v108, v109
	v_or_b32_e32 v108, 16, v146
	v_ashrrev_i32_e32 v69, 31, v68
	v_cvt_pk_bf16_f32 v48, v48, v49
	v_cvt_pk_bf16_f32 v49, v50, v51
	v_cvt_pk_bf16_f32 v50, v44, v45
	v_add_u32_e32 v44, 0x90, v146
	s_ashr_i32 s1, s0, 31
	v_lshlrev_b64 v[148:149], 11, v[146:147]
	v_readlane_b32 s21, v252, 13
	v_ashrrev_i32_e32 v109, 31, v108
	v_cvt_pk_bf16_f32 v96, v96, v97
	v_cvt_pk_bf16_f32 v97, v98, v99
	v_cvt_pk_bf16_f32 v98, v92, v93
	v_or_b32_e32 v92, 32, v146
	v_lshlrev_b64 v[68:69], 11, v[68:69]
	v_ashrrev_i32_e32 v45, 31, v44
	v_cvt_pk_bf16_f32 v32, v32, v33
	v_cvt_pk_bf16_f32 v33, v34, v35
	v_cvt_pk_bf16_f32 v34, v28, v29
	v_add_u32_e32 v28, 0xa0, v146
	v_lshl_add_u64 v[148:149], s[20:21], 0, v[148:149]
	s_lshl_b64 s[0:1], s[0:1], 1
	v_lshlrev_b64 v[108:109], 11, v[108:109]
	v_ashrrev_i32_e32 v93, 31, v92
	v_cvt_pk_bf16_f32 v80, v80, v81
	v_cvt_pk_bf16_f32 v81, v82, v83
	v_cvt_pk_bf16_f32 v82, v76, v77
	v_or_b32_e32 v76, 48, v146
	v_lshl_add_u64 v[68:69], s[20:21], 0, v[68:69]
	v_lshlrev_b64 v[44:45], 11, v[44:45]
	v_ashrrev_i32_e32 v29, 31, v28
	v_cvt_pk_bf16_f32 v20, v20, v21
	v_cvt_pk_bf16_f32 v21, v22, v23
	v_cvt_pk_bf16_f32 v22, v12, v13
	v_add_u32_e32 v12, 0xb0, v146
	v_lshl_add_u64 v[148:149], v[148:149], 0, s[0:1]
	v_lshl_add_u64 v[108:109], s[20:21], 0, v[108:109]
	v_lshlrev_b64 v[92:93], 11, v[92:93]
	v_ashrrev_i32_e32 v77, 31, v76
	v_lshl_add_u64 v[68:69], v[68:69], 0, s[0:1]
	v_lshl_add_u64 v[44:45], s[20:21], 0, v[44:45]
	v_lshlrev_b64 v[28:29], 11, v[28:29]
	v_ashrrev_i32_e32 v13, 31, v12
	v_lshl_add_u64 v[148:149], v[148:149], 0, s[72:73]
	v_lshl_add_u64 v[108:109], v[108:109], 0, s[0:1]
	v_lshl_add_u64 v[92:93], s[20:21], 0, v[92:93]
	v_lshlrev_b64 v[76:77], 11, v[76:77]
	v_lshl_add_u64 v[68:69], v[68:69], 0, s[72:73]
	v_lshl_add_u64 v[44:45], v[44:45], 0, s[0:1]
	v_lshl_add_u64 v[28:29], s[20:21], 0, v[28:29]
	v_lshlrev_b64 v[12:13], 11, v[12:13]
	v_lshl_add_u64 v[148:149], v[148:149], 0, v[2:3]
	v_cvt_pk_bf16_f32 v115, v110, v111
	v_lshl_add_u64 v[108:109], v[108:109], 0, s[72:73]
	v_lshl_add_u64 v[92:93], v[92:93], 0, s[0:1]
	v_lshl_add_u64 v[76:77], s[20:21], 0, v[76:77]
	v_lshl_add_u64 v[68:69], v[68:69], 0, v[2:3]
	v_cvt_pk_bf16_f32 v51, v46, v47
	v_lshl_add_u64 v[44:45], v[44:45], 0, s[72:73]
	v_lshl_add_u64 v[28:29], v[28:29], 0, s[0:1]
	v_lshl_add_u64 v[12:13], s[20:21], 0, v[12:13]
	global_store_dwordx4 v[148:149], v[112:115], off offset:256
	v_cvt_pk_bf16_f32 v99, v94, v95
	v_lshl_add_u64 v[92:93], v[92:93], 0, s[72:73]
	v_lshl_add_u64 v[112:113], v[108:109], 0, v[2:3]
	v_lshl_add_u64 v[76:77], v[76:77], 0, s[0:1]
	global_store_dwordx4 v[68:69], v[48:51], off offset:256
	v_cvt_pk_bf16_f32 v35, v30, v31
	v_lshl_add_u64 v[28:29], v[28:29], 0, s[72:73]
	v_lshl_add_u64 v[48:49], v[44:45], 0, v[2:3]
	v_lshl_add_u64 v[12:13], v[12:13], 0, s[0:1]
	global_store_dwordx4 v[112:113], v[96:99], off offset:256
	v_cvt_pk_bf16_f32 v83, v78, v79
	v_lshl_add_u64 v[76:77], v[76:77], 0, s[72:73]
	v_lshl_add_u64 v[96:97], v[92:93], 0, v[2:3]
	global_store_dwordx4 v[48:49], v[32:35], off offset:256
	v_cvt_pk_bf16_f32 v23, v14, v15
	v_lshl_add_u64 v[12:13], v[12:13], 0, s[72:73]
	v_lshl_add_u64 v[32:33], v[28:29], 0, v[2:3]
	v_cvt_pk_bf16_f32 v128, v128, v129
	v_cvt_pk_bf16_f32 v129, v130, v131
	v_cvt_pk_bf16_f32 v130, v124, v125
	v_cvt_pk_bf16_f32 v131, v126, v127
	v_cvt_pk_bf16_f32 v108, v120, v121
	v_cvt_pk_bf16_f32 v109, v122, v123
	v_cvt_pk_bf16_f32 v110, v116, v117
	v_cvt_pk_bf16_f32 v111, v118, v119
	v_cvt_pk_bf16_f32 v92, v104, v105
	v_cvt_pk_bf16_f32 v93, v106, v107
	v_cvt_pk_bf16_f32 v94, v100, v101
	v_cvt_pk_bf16_f32 v95, v102, v103
	global_store_dwordx4 v[96:97], v[80:83], off offset:256
	v_cvt_pk_bf16_f32 v78, v84, v85
	v_cvt_pk_bf16_f32 v79, v86, v87
	v_lshl_add_u64 v[80:81], v[76:77], 0, v[2:3]
	v_cvt_pk_bf16_f32 v76, v88, v89
	v_cvt_pk_bf16_f32 v77, v90, v91
	v_cvt_pk_bf16_f32 v75, v70, v71
	v_cvt_pk_bf16_f32 v64, v64, v65
	v_cvt_pk_bf16_f32 v65, v66, v67
	v_cvt_pk_bf16_f32 v66, v60, v61
	v_cvt_pk_bf16_f32 v67, v62, v63
	v_cvt_pk_bf16_f32 v44, v56, v57
	v_cvt_pk_bf16_f32 v45, v58, v59
	v_cvt_pk_bf16_f32 v46, v52, v53
	v_cvt_pk_bf16_f32 v47, v54, v55
	v_cvt_pk_bf16_f32 v28, v40, v41
	v_cvt_pk_bf16_f32 v29, v42, v43
	v_cvt_pk_bf16_f32 v30, v36, v37
	v_cvt_pk_bf16_f32 v31, v38, v39
	global_store_dwordx4 v[32:33], v[20:23], off offset:256
	v_cvt_pk_bf16_f32 v14, v16, v17
	v_cvt_pk_bf16_f32 v15, v18, v19
	v_lshl_add_u64 v[20:21], v[12:13], 0, v[2:3]
	v_cvt_pk_bf16_f32 v12, v24, v25
	v_cvt_pk_bf16_f32 v13, v26, v27
	v_cvt_pk_bf16_f32 v8, v8, v9
	v_cvt_pk_bf16_f32 v9, v10, v11
	v_cvt_pk_bf16_f32 v10, v4, v5
	v_cvt_pk_bf16_f32 v11, v6, v7
	s_and_b64 vcc, exec, s[38:39]
	s_mov_b32 s1, s40
	s_mov_b32 s0, s42
	s_mov_b64 s[50:51], s[46:47]
	s_mov_b64 s[48:49], s[44:45]
	global_store_dwordx4 v[148:149], v[128:131], off
	global_store_dwordx4 v[112:113], v[108:111], off
	global_store_dwordx4 v[96:97], v[92:95], off
	global_store_dwordx4 v[80:81], v[76:79], off
	global_store_dwordx4 v[80:81], v[72:75], off offset:256
	global_store_dwordx4 v[68:69], v[64:67], off
	global_store_dwordx4 v[48:49], v[44:47], off
	global_store_dwordx4 v[32:33], v[28:31], off
	global_store_dwordx4 v[20:21], v[12:15], off
	global_store_dwordx4 v[20:21], v[8:11], off offset:256
	s_cbranch_vccz .LBB0_129
	s_waitcnt vmcnt(0)
	s_cmpk_gt_u32 s31, 0xff
	s_cbranch_scc1 .LBB0_140
	s_barrier

.LBB0_175:
	s_add_i32 s26, s27, 2
	s_add_u32 s44, s40, 0x100
	s_addc_u32 s45, s41, 0
	s_add_i32 s30, 0, 0x10000
	v_add_u32_e32 v0, s30, v157
	ds_read_b128 v[132:135], v0
	ds_read_b128 v[164:167], v0 offset:1024
	ds_read_b128 v[168:171], v0 offset:2048
	ds_read_b128 v[174:177], v0 offset:3072
	s_cmp_eq_u32 s23, s27
	s_cselect_b32 s49, s1, s45
	s_cselect_b32 s48, s0, s44
	s_cselect_b32 s47, s43, s25
	s_cselect_b32 s46, s42, s24
	v_lshl_add_u64 v[0:1], s[40:41], 0, v[160:161]
	s_add_i32 m0, s53, 0xc000
	ds_read_b128 v[178:181], v172
	ds_read_b128 v[182:185], v172 offset:1024
	ds_read_b128 v[186:189], v172 offset:2048
	ds_read_b128 v[190:193], v172 offset:3072
	ds_read_b128 v[202:205], v172 offset:4096
	ds_read_b128 v[206:209], v172 offset:5120
	ds_read_b128 v[210:213], v172 offset:6144
	ds_read_b128 v[214:217], v172 offset:7168
	global_load_lds_dwordx4 v[0:1], off
	v_lshl_add_u64 v[0:1], s[40:41], 0, v[162:163]
	s_add_i32 m0, s53, 0xe000
	s_nop 0
	global_load_lds_dwordx4 v[0:1], off
	s_waitcnt lgkmcnt(8)
	s_waitcnt vmcnt(10)
	s_barrier
	s_waitcnt lgkmcnt(0)
	s_setprio 1
	s_waitcnt lgkmcnt(0)
	v_mfma_f32_16x16x32_bf16 v[4:7], v[132:135], v[178:181], v[4:7]
	v_mfma_f32_16x16x32_bf16 v[8:11], v[168:171], v[178:181], v[8:11]
	v_mfma_f32_16x16x32_bf16 v[128:131], v[132:135], v[186:189], v[128:131]
	v_mfma_f32_16x16x32_bf16 v[124:127], v[168:171], v[186:189], v[124:127]
	v_mfma_f32_16x16x32_bf16 v[120:123], v[132:135], v[202:205], v[120:123]
	v_mfma_f32_16x16x32_bf16 v[116:119], v[168:171], v[202:205], v[116:119]
	v_mfma_f32_16x16x32_bf16 v[112:115], v[132:135], v[210:213], v[112:115]
	v_mfma_f32_16x16x32_bf16 v[108:111], v[168:171], v[210:213], v[108:111]
	v_mfma_f32_16x16x32_bf16 v[4:7], v[164:167], v[182:185], v[4:7]
	v_mfma_f32_16x16x32_bf16 v[8:11], v[174:177], v[182:185], v[8:11]
	v_mfma_f32_16x16x32_bf16 v[128:131], v[164:167], v[190:193], v[128:131]
	v_mfma_f32_16x16x32_bf16 v[124:127], v[174:177], v[190:193], v[124:127]
	v_mfma_f32_16x16x32_bf16 v[120:123], v[164:167], v[206:209], v[120:123]
	v_mfma_f32_16x16x32_bf16 v[116:119], v[174:177], v[206:209], v[116:119]
	v_mfma_f32_16x16x32_bf16 v[112:115], v[164:167], v[214:217], v[112:115]
	v_mfma_f32_16x16x32_bf16 v[108:111], v[174:177], v[214:217], v[108:111]
	s_setprio 0
	s_barrier
	s_add_i32 s27, 0, 0x14000
	v_add_u32_e32 v0, s27, v157
	s_add_i32 s30, s30, s52
	ds_read_b128 v[236:239], v0
	ds_read_b128 v[240:243], v0 offset:1024
	ds_read_b128 v[244:247], v0 offset:2048
	ds_read_b128 v[248:251], v0 offset:3072
	v_lshl_add_u64 v[0:1], s[46:47], 0, v[138:139]
	s_mov_b32 m0, s30
	v_lshl_add_u64 v[194:195], s[46:47], 0, v[142:143]
	global_load_lds_dwordx4 v[0:1], off
	s_add_i32 m0, s30, 0x2000
	s_nop 0
	global_load_lds_dwordx4 v[194:195], off
	s_waitcnt vmcnt(10)
	s_barrier
	s_waitcnt lgkmcnt(0)
	s_setprio 1
	s_waitcnt lgkmcnt(0)
	v_mfma_f32_16x16x32_bf16 v[12:15], v[236:239], v[178:181], v[12:15]
	v_mfma_f32_16x16x32_bf16 v[16:19], v[244:247], v[178:181], v[16:19]
	v_mfma_f32_16x16x32_bf16 v[104:107], v[236:239], v[186:189], v[104:107]
	v_mfma_f32_16x16x32_bf16 v[100:103], v[244:247], v[186:189], v[100:103]
	v_mfma_f32_16x16x32_bf16 v[96:99], v[236:239], v[202:205], v[96:99]
	v_mfma_f32_16x16x32_bf16 v[92:95], v[244:247], v[202:205], v[92:95]
	v_mfma_f32_16x16x32_bf16 v[88:91], v[236:239], v[210:213], v[88:91]
	v_mfma_f32_16x16x32_bf16 v[84:87], v[244:247], v[210:213], v[84:87]
	v_mfma_f32_16x16x32_bf16 v[12:15], v[240:243], v[182:185], v[12:15]
	v_mfma_f32_16x16x32_bf16 v[16:19], v[248:251], v[182:185], v[16:19]
	v_mfma_f32_16x16x32_bf16 v[104:107], v[240:243], v[190:193], v[104:107]
	v_mfma_f32_16x16x32_bf16 v[100:103], v[248:251], v[190:193], v[100:103]
	v_mfma_f32_16x16x32_bf16 v[96:99], v[240:243], v[206:209], v[96:99]
	v_mfma_f32_16x16x32_bf16 v[92:95], v[248:251], v[206:209], v[92:95]
	v_mfma_f32_16x16x32_bf16 v[88:91], v[240:243], v[214:217], v[88:91]
	v_mfma_f32_16x16x32_bf16 v[84:87], v[248:251], v[214:217], v[84:87]
	s_setprio 0
	s_mov_b32 m0, s53
	v_lshl_add_u64 v[222:223], s[48:49], 0, v[136:137]
	s_barrier
	ds_read_b128 v[178:181], v172 offset:16384
	ds_read_b128 v[182:185], v172 offset:17408
	ds_read_b128 v[186:189], v172 offset:18432
	ds_read_b128 v[190:193], v172 offset:19456
	ds_read_b128 v[202:205], v172 offset:20480
	ds_read_b128 v[206:209], v172 offset:21504
	ds_read_b128 v[210:213], v172 offset:22528
	ds_read_b128 v[214:217], v172 offset:23552
	global_load_lds_dwordx4 v[222:223], off
	v_lshl_add_u64 v[198:199], s[48:49], 0, v[140:141]
	s_mov_b32 m0, s54
	s_nop 0
	global_load_lds_dwordx4 v[198:199], off
	s_barrier
	s_waitcnt lgkmcnt(0)
	s_setprio 1
	s_waitcnt lgkmcnt(0)
	v_mfma_f32_16x16x32_bf16 v[80:83], v[132:135], v[178:181], v[80:83]
	v_mfma_f32_16x16x32_bf16 v[76:79], v[168:171], v[178:181], v[76:79]
	v_mfma_f32_16x16x32_bf16 v[72:75], v[132:135], v[186:189], v[72:75]
	v_mfma_f32_16x16x32_bf16 v[68:71], v[168:171], v[186:189], v[68:71]
	v_mfma_f32_16x16x32_bf16 v[64:67], v[132:135], v[202:205], v[64:67]
	v_mfma_f32_16x16x32_bf16 v[60:63], v[168:171], v[202:205], v[60:63]
	v_mfma_f32_16x16x32_bf16 v[56:59], v[132:135], v[210:213], v[56:59]
	v_mfma_f32_16x16x32_bf16 v[52:55], v[168:171], v[210:213], v[52:55]
	v_mfma_f32_16x16x32_bf16 v[80:83], v[164:167], v[182:185], v[80:83]
	v_mfma_f32_16x16x32_bf16 v[76:79], v[174:177], v[182:185], v[76:79]
	v_mfma_f32_16x16x32_bf16 v[72:75], v[164:167], v[190:193], v[72:75]
	v_mfma_f32_16x16x32_bf16 v[68:71], v[174:177], v[190:193], v[68:71]
	v_mfma_f32_16x16x32_bf16 v[64:67], v[164:167], v[206:209], v[64:67]
	v_mfma_f32_16x16x32_bf16 v[60:63], v[174:177], v[206:209], v[60:63]
	v_mfma_f32_16x16x32_bf16 v[56:59], v[164:167], v[214:217], v[56:59]
	v_mfma_f32_16x16x32_bf16 v[52:55], v[174:177], v[214:217], v[52:55]
	s_setprio 0
	s_barrier
	s_add_u32 s30, s46, 0xc0000
	s_addc_u32 s31, s47, 0
	s_add_i32 s27, s27, s52
	v_lshl_add_u64 v[132:133], s[30:31], 0, v[138:139]
	s_mov_b32 m0, s27
	s_nop 0
	global_load_lds_dwordx4 v[132:133], off
	v_lshl_add_u64 v[132:133], s[30:31], 0, v[142:143]
	s_add_i32 m0, s27, 0x2000
	s_nop 0
	global_load_lds_dwordx4 v[132:133], off
	s_waitcnt vmcnt(10)
	s_barrier
	s_setprio 1
	v_mfma_f32_16x16x32_bf16 v[48:51], v[236:239], v[178:181], v[48:51]
	v_mfma_f32_16x16x32_bf16 v[44:47], v[244:247], v[178:181], v[44:47]
	v_mfma_f32_16x16x32_bf16 v[40:43], v[236:239], v[186:189], v[40:43]
	v_mfma_f32_16x16x32_bf16 v[36:39], v[244:247], v[186:189], v[36:39]
	v_mfma_f32_16x16x32_bf16 v[32:35], v[236:239], v[202:205], v[32:35]
	v_mfma_f32_16x16x32_bf16 v[28:31], v[244:247], v[202:205], v[28:31]
	v_mfma_f32_16x16x32_bf16 v[24:27], v[236:239], v[210:213], v[24:27]
	v_mfma_f32_16x16x32_bf16 v[20:23], v[244:247], v[210:213], v[20:23]
	v_mfma_f32_16x16x32_bf16 v[48:51], v[240:243], v[182:185], v[48:51]
	v_mfma_f32_16x16x32_bf16 v[44:47], v[248:251], v[182:185], v[44:47]
	v_mfma_f32_16x16x32_bf16 v[40:43], v[240:243], v[190:193], v[40:43]
	v_mfma_f32_16x16x32_bf16 v[36:39], v[248:251], v[190:193], v[36:39]
	v_mfma_f32_16x16x32_bf16 v[32:35], v[240:243], v[206:209], v[32:35]
	v_mfma_f32_16x16x32_bf16 v[28:31], v[248:251], v[206:209], v[28:31]
	v_mfma_f32_16x16x32_bf16 v[24:27], v[240:243], v[214:217], v[24:27]
	v_mfma_f32_16x16x32_bf16 v[20:23], v[248:251], v[214:217], v[20:23]
	s_setprio 0
	s_add_i32 s27, 0, 0x18000
	v_add_u32_e32 v2, s27, v157
	s_barrier
	ds_read_b128 v[132:135], v2
	ds_read_b128 v[164:167], v2 offset:1024
	ds_read_b128 v[168:171], v2 offset:2048
	ds_read_b128 v[174:177], v2 offset:3072
	s_add_u32 s30, s48, 0x1a0000
	s_addc_u32 s31, s49, 0
	s_mov_b32 m0, s55
	v_lshl_add_u64 v[236:237], s[30:31], 0, v[136:137]
	ds_read_b128 v[178:181], v172 offset:32768
	ds_read_b128 v[182:185], v172 offset:33792
	ds_read_b128 v[186:189], v172 offset:34816
	ds_read_b128 v[190:193], v172 offset:35840
	ds_read_b128 v[202:205], v172 offset:36864
	ds_read_b128 v[206:209], v172 offset:37888
	ds_read_b128 v[210:213], v172 offset:38912
	ds_read_b128 v[214:217], v172 offset:39936
	global_load_lds_dwordx4 v[236:237], off
	v_lshl_add_u64 v[236:237], s[30:31], 0, v[140:141]
	s_mov_b32 m0, s56
	s_nop 0
	global_load_lds_dwordx4 v[236:237], off
	s_waitcnt lgkmcnt(8)
	s_waitcnt vmcnt(10)
	s_barrier
	s_waitcnt lgkmcnt(0)
	s_setprio 1
	s_waitcnt lgkmcnt(0)
	v_mfma_f32_16x16x32_bf16 v[4:7], v[132:135], v[178:181], v[4:7]
	v_mfma_f32_16x16x32_bf16 v[8:11], v[168:171], v[178:181], v[8:11]
	v_mfma_f32_16x16x32_bf16 v[128:131], v[132:135], v[186:189], v[128:131]
	v_mfma_f32_16x16x32_bf16 v[124:127], v[168:171], v[186:189], v[124:127]
	v_mfma_f32_16x16x32_bf16 v[120:123], v[132:135], v[202:205], v[120:123]
	v_mfma_f32_16x16x32_bf16 v[116:119], v[168:171], v[202:205], v[116:119]
	v_mfma_f32_16x16x32_bf16 v[112:115], v[132:135], v[210:213], v[112:115]
	v_mfma_f32_16x16x32_bf16 v[108:111], v[168:171], v[210:213], v[108:111]
	v_mfma_f32_16x16x32_bf16 v[4:7], v[164:167], v[182:185], v[4:7]
	v_mfma_f32_16x16x32_bf16 v[8:11], v[174:177], v[182:185], v[8:11]
	v_mfma_f32_16x16x32_bf16 v[128:131], v[164:167], v[190:193], v[128:131]
	v_mfma_f32_16x16x32_bf16 v[124:127], v[174:177], v[190:193], v[124:127]
	v_mfma_f32_16x16x32_bf16 v[120:123], v[164:167], v[206:209], v[120:123]
	v_mfma_f32_16x16x32_bf16 v[116:119], v[174:177], v[206:209], v[116:119]
	v_mfma_f32_16x16x32_bf16 v[112:115], v[164:167], v[214:217], v[112:115]
	v_mfma_f32_16x16x32_bf16 v[108:111], v[174:177], v[214:217], v[108:111]
	s_setprio 0
	s_barrier
	s_add_i32 s36, 0, 0x1c000
	s_add_i32 s27, s27, s52
	v_add_u32_e32 v2, s36, v157
	v_lshl_add_u64 v[0:1], v[0:1], 0, s[76:77]
	s_mov_b32 m0, s27
	ds_read_b128 v[236:239], v2
	ds_read_b128 v[240:243], v2 offset:1024
	ds_read_b128 v[244:247], v2 offset:2048
	ds_read_b128 v[248:251], v2 offset:3072
	global_load_lds_dwordx4 v[0:1], off
	v_lshl_add_u64 v[0:1], v[194:195], 0, s[76:77]
	s_add_i32 m0, s27, 0x2000
	s_nop 0
	global_load_lds_dwordx4 v[0:1], off
	s_waitcnt vmcnt(10)
	s_barrier
	s_waitcnt lgkmcnt(0)
	s_setprio 1
	s_waitcnt lgkmcnt(0)
	v_mfma_f32_16x16x32_bf16 v[12:15], v[236:239], v[178:181], v[12:15]
	v_mfma_f32_16x16x32_bf16 v[16:19], v[244:247], v[178:181], v[16:19]
	v_mfma_f32_16x16x32_bf16 v[104:107], v[236:239], v[186:189], v[104:107]
	v_mfma_f32_16x16x32_bf16 v[100:103], v[244:247], v[186:189], v[100:103]
	v_mfma_f32_16x16x32_bf16 v[96:99], v[236:239], v[202:205], v[96:99]
	v_mfma_f32_16x16x32_bf16 v[92:95], v[244:247], v[202:205], v[92:95]
	v_mfma_f32_16x16x32_bf16 v[88:91], v[236:239], v[210:213], v[88:91]
	v_mfma_f32_16x16x32_bf16 v[84:87], v[244:247], v[210:213], v[84:87]
	v_mfma_f32_16x16x32_bf16 v[12:15], v[240:243], v[182:185], v[12:15]
	v_mfma_f32_16x16x32_bf16 v[16:19], v[248:251], v[182:185], v[16:19]
	v_mfma_f32_16x16x32_bf16 v[104:107], v[240:243], v[190:193], v[104:107]
	v_mfma_f32_16x16x32_bf16 v[100:103], v[248:251], v[190:193], v[100:103]
	v_mfma_f32_16x16x32_bf16 v[96:99], v[240:243], v[206:209], v[96:99]
	v_mfma_f32_16x16x32_bf16 v[92:95], v[248:251], v[206:209], v[92:95]
	v_mfma_f32_16x16x32_bf16 v[88:91], v[240:243], v[214:217], v[88:91]
	v_mfma_f32_16x16x32_bf16 v[84:87], v[248:251], v[214:217], v[84:87]
	s_setprio 0
	s_mov_b32 m0, s59
	v_lshl_add_u64 v[0:1], v[222:223], 0, s[76:77]
	s_barrier
	ds_read_b128 v[178:181], v172 offset:49152
	ds_read_b128 v[182:185], v172 offset:50176
	ds_read_b128 v[186:189], v172 offset:51200
	ds_read_b128 v[190:193], v172 offset:52224
	ds_read_b128 v[202:205], v172 offset:53248
	ds_read_b128 v[206:209], v172 offset:54272
	ds_read_b128 v[210:213], v172 offset:55296
	ds_read_b128 v[214:217], v172 offset:56320
	global_load_lds_dwordx4 v[0:1], off
	v_lshl_add_u64 v[0:1], v[198:199], 0, s[76:77]
	s_mov_b32 m0, s60
	s_nop 0
	global_load_lds_dwordx4 v[0:1], off
	s_barrier
	s_waitcnt lgkmcnt(0)
	s_setprio 1
	s_waitcnt lgkmcnt(0)
	v_mfma_f32_16x16x32_bf16 v[80:83], v[132:135], v[178:181], v[80:83]
	v_mfma_f32_16x16x32_bf16 v[76:79], v[168:171], v[178:181], v[76:79]
	v_mfma_f32_16x16x32_bf16 v[72:75], v[132:135], v[186:189], v[72:75]
	v_mfma_f32_16x16x32_bf16 v[68:71], v[168:171], v[186:189], v[68:71]
	v_mfma_f32_16x16x32_bf16 v[64:67], v[132:135], v[202:205], v[64:67]
	v_mfma_f32_16x16x32_bf16 v[60:63], v[168:171], v[202:205], v[60:63]
	v_mfma_f32_16x16x32_bf16 v[56:59], v[132:135], v[210:213], v[56:59]
	v_mfma_f32_16x16x32_bf16 v[52:55], v[168:171], v[210:213], v[52:55]
	v_mfma_f32_16x16x32_bf16 v[80:83], v[164:167], v[182:185], v[80:83]
	v_mfma_f32_16x16x32_bf16 v[76:79], v[174:177], v[182:185], v[76:79]
	v_mfma_f32_16x16x32_bf16 v[72:75], v[164:167], v[190:193], v[72:75]
	v_mfma_f32_16x16x32_bf16 v[68:71], v[174:177], v[190:193], v[68:71]
	v_mfma_f32_16x16x32_bf16 v[64:67], v[164:167], v[206:209], v[64:67]
	v_mfma_f32_16x16x32_bf16 v[60:63], v[174:177], v[206:209], v[60:63]
	v_mfma_f32_16x16x32_bf16 v[56:59], v[164:167], v[214:217], v[56:59]
	v_mfma_f32_16x16x32_bf16 v[52:55], v[174:177], v[214:217], v[52:55]
	s_setprio 0
	s_barrier
	s_add_u32 s30, s46, 0xc0080
	s_addc_u32 s31, s47, 0
	s_add_i32 s27, s36, s52
	v_lshl_add_u64 v[0:1], s[30:31], 0, v[138:139]
	s_mov_b32 m0, s27
	s_nop 0
	global_load_lds_dwordx4 v[0:1], off
	v_lshl_add_u64 v[0:1], s[30:31], 0, v[142:143]
	s_add_i32 m0, s27, 0x2000
	s_nop 0
	global_load_lds_dwordx4 v[0:1], off
	s_waitcnt vmcnt(10)
	s_barrier
	s_setprio 1
	v_mfma_f32_16x16x32_bf16 v[48:51], v[236:239], v[178:181], v[48:51]
	v_mfma_f32_16x16x32_bf16 v[44:47], v[244:247], v[178:181], v[44:47]
	v_mfma_f32_16x16x32_bf16 v[40:43], v[236:239], v[186:189], v[40:43]
	v_mfma_f32_16x16x32_bf16 v[36:39], v[244:247], v[186:189], v[36:39]
	v_mfma_f32_16x16x32_bf16 v[32:35], v[236:239], v[202:205], v[32:35]
	v_mfma_f32_16x16x32_bf16 v[28:31], v[244:247], v[202:205], v[28:31]
	v_mfma_f32_16x16x32_bf16 v[24:27], v[236:239], v[210:213], v[24:27]
	v_mfma_f32_16x16x32_bf16 v[20:23], v[244:247], v[210:213], v[20:23]
	v_mfma_f32_16x16x32_bf16 v[48:51], v[240:243], v[182:185], v[48:51]
	v_mfma_f32_16x16x32_bf16 v[44:47], v[248:251], v[182:185], v[44:47]
	v_mfma_f32_16x16x32_bf16 v[40:43], v[240:243], v[190:193], v[40:43]
	v_mfma_f32_16x16x32_bf16 v[36:39], v[248:251], v[190:193], v[36:39]
	v_mfma_f32_16x16x32_bf16 v[32:35], v[240:243], v[206:209], v[32:35]
	v_mfma_f32_16x16x32_bf16 v[28:31], v[248:251], v[206:209], v[28:31]
	v_mfma_f32_16x16x32_bf16 v[24:27], v[240:243], v[214:217], v[24:27]
	v_mfma_f32_16x16x32_bf16 v[20:23], v[248:251], v[214:217], v[20:23]
	s_setprio 0
	s_add_u32 s24, s24, 0x100
	s_addc_u32 s25, s25, 0
	s_cmp_ge_i32 s26, s22
	s_mov_b64 s[40:41], s[44:45]
	s_mov_b32 s27, s26
	s_barrier
	s_cbranch_scc0 .LBB0_175
	s_lshl_b32 s46, s66, 8
	v_lshl_or_b32 v0, s20, 8, v159
	s_mov_b32 s44, 0xbfb8aa3b
	s_mov_b32 s45, 0xbfb8aa3b
	v_lshlrev_b32_e32 v0, 1, v0
	v_add_u32_e32 v0, 0x1000, v0
	s_cmp_lg_u32 s21, 1
	s_cbranch_scc0 .Lg2_kind1
	v_readlane_b32 s22, v252, 34
	v_readlane_b32 s23, v252, 35
	v_add_u32_e32 v2, s46, v144
	v_mad_u32_u24 v2, v2, s29, v0
	global_load_dwordx4 v[132:135], v2, s[96:97] offset:2048
	v_add_u32_e32 v2, s46, v144
	v_mad_u32_u24 v2, v2, s29, v0
	global_load_dwordx4 v[178:181], v2, s[96:97] offset:2304
	v_add_u32_e32 v2, s46, v146
	v_mad_u32_u24 v2, v2, s29, v0
	global_load_dwordx4 v[182:185], v2, s[96:97] offset:2048
	v_add_u32_e32 v2, s46, v146
	v_mad_u32_u24 v2, v2, s29, v0
	global_load_dwordx4 v[186:189], v2, s[96:97] offset:2304
	v_add_u32_e32 v2, s46, v148
	v_mad_u32_u24 v2, v2, s29, v0
	global_load_dwordx4 v[190:193], v2, s[96:97] offset:2048
	v_add_u32_e32 v2, s46, v148
	v_mad_u32_u24 v2, v2, s29, v0
	global_load_dwordx4 v[202:205], v2, s[96:97] offset:2304
	v_add_u32_e32 v2, s46, v150
	v_mad_u32_u24 v2, v2, s29, v0
	global_load_dwordx4 v[206:209], v2, s[96:97] offset:2048
	v_add_u32_e32 v2, s46, v150
	v_mad_u32_u24 v2, v2, s29, v0
	global_load_dwordx4 v[210:213], v2, s[96:97] offset:2304
	v_add_u32_e32 v2, s46, v152
	v_mad_u32_u24 v2, v2, s29, v0
	global_load_dwordx4 v[214:217], v2, s[96:97] offset:2048
	v_add_u32_e32 v2, s46, v152
	v_mad_u32_u24 v2, v2, s29, v0
	global_load_dwordx4 v[236:239], v2, s[96:97] offset:2304
	v_add_u32_e32 v2, s46, v154
	v_mad_u32_u24 v2, v2, s29, v0
	global_load_dwordx4 v[240:243], v2, s[96:97] offset:2048
	v_add_u32_e32 v2, s46, v154
	v_mad_u32_u24 v2, v2, s29, v0
	global_load_dwordx4 v[244:247], v2, s[96:97] offset:2304
	v_add_u32_e32 v2, s46, v156
	v_mad_u32_u24 v2, v2, s29, v0
	global_load_dwordx4 v[248:251], v2, s[96:97] offset:2048
	s_waitcnt vmcnt(12)
	v_lshlrev_b32_e32 v164, 16, v132
	v_and_b32_e32 v165, 0xffff0000, v132
	v_lshlrev_b32_e32 v166, 16, v133
	v_and_b32_e32 v167, 0xffff0000, v133
	v_lshlrev_b32_e32 v168, 16, v134
	v_and_b32_e32 v169, 0xffff0000, v134
	v_lshlrev_b32_e32 v170, 16, v135
	v_and_b32_e32 v171, 0xffff0000, v135
	v_add_u32_e32 v2, s46, v156
	v_mad_u32_u24 v2, v2, s29, v0
	global_load_dwordx4 v[132:135], v2, s[96:97] offset:2304
	v_add_u32_e32 v1, s46, v144
	v_lshl_add_u32 v1, v1, 11, v0
	v_med3_f32 v164, v164, s34, v227
	v_med3_f32 v165, v165, s34, v227
	v_med3_f32 v166, v166, s34, v227
	v_med3_f32 v167, v167, s34, v227
	v_med3_f32 v168, v168, s34, v227
	v_med3_f32 v169, v169, s34, v227
	v_med3_f32 v170, v170, s34, v227
	v_med3_f32 v171, v171, s34, v227
	v_pk_mul_f32 v[164:165], v[164:165], s[44:45]
	v_pk_mul_f32 v[166:167], v[166:167], s[44:45]
	v_pk_mul_f32 v[168:169], v[168:169], s[44:45]
	v_pk_mul_f32 v[170:171], v[170:171], s[44:45]
	v_exp_f32_e32 v164, v164
	v_exp_f32_e32 v165, v165
	v_exp_f32_e32 v166, v166
	v_exp_f32_e32 v167, v167
	v_exp_f32_e32 v168, v168
	v_exp_f32_e32 v169, v169
	v_exp_f32_e32 v170, v170
	v_exp_f32_e32 v171, v171
	v_pk_add_f32 v[164:165], v[164:165], 1.0 op_sel_hi:[1,0]
	v_pk_add_f32 v[166:167], v[166:167], 1.0 op_sel_hi:[1,0]
	v_pk_add_f32 v[168:169], v[168:169], 1.0 op_sel_hi:[1,0]
	v_pk_add_f32 v[170:171], v[170:171], 1.0 op_sel_hi:[1,0]
	v_rcp_f32_e32 v164, v164
	v_rcp_f32_e32 v165, v165
	v_rcp_f32_e32 v166, v166
	v_rcp_f32_e32 v167, v167
	v_rcp_f32_e32 v168, v168
	v_rcp_f32_e32 v169, v169
	v_rcp_f32_e32 v170, v170
	v_rcp_f32_e32 v171, v171
	v_pk_mul_f32 v[164:165], v[4:5], v[164:165]
	v_pk_mul_f32 v[166:167], v[6:7], v[166:167]
	v_pk_mul_f32 v[168:169], v[8:9], v[168:169]
	v_pk_mul_f32 v[170:171], v[10:11], v[170:171]
	v_cvt_pk_bf16_f32 v174, v164, v165
	v_cvt_pk_bf16_f32 v175, v166, v167
	v_cvt_pk_bf16_f32 v176, v168, v169
	v_cvt_pk_bf16_f32 v177, v170, v171
	global_store_dwordx4 v1, v[174:177], s[22:23] offset:-4096
	s_waitcnt vmcnt(13)
	v_lshlrev_b32_e32 v164, 16, v178
	v_and_b32_e32 v165, 0xffff0000, v178
	v_lshlrev_b32_e32 v166, 16, v179
	v_and_b32_e32 v167, 0xffff0000, v179
	v_lshlrev_b32_e32 v168, 16, v180
	v_and_b32_e32 v169, 0xffff0000, v180
	v_lshlrev_b32_e32 v170, 16, v181
	v_and_b32_e32 v171, 0xffff0000, v181
	v_add_u32_e32 v2, s46, v158
	v_mad_u32_u24 v2, v2, s29, v0
	global_load_dwordx4 v[178:181], v2, s[96:97] offset:2048
	v_med3_f32 v164, v164, s34, v227
	v_med3_f32 v165, v165, s34, v227
	v_med3_f32 v166, v166, s34, v227
	v_med3_f32 v167, v167, s34, v227
	v_med3_f32 v168, v168, s34, v227
	v_med3_f32 v169, v169, s34, v227
	v_med3_f32 v170, v170, s34, v227
	v_med3_f32 v171, v171, s34, v227
	v_pk_mul_f32 v[164:165], v[164:165], s[44:45]
	v_pk_mul_f32 v[166:167], v[166:167], s[44:45]
	v_pk_mul_f32 v[168:169], v[168:169], s[44:45]
	v_pk_mul_f32 v[170:171], v[170:171], s[44:45]
	v_exp_f32_e32 v164, v164
	v_exp_f32_e32 v165, v165
	v_exp_f32_e32 v166, v166
	v_exp_f32_e32 v167, v167
	v_exp_f32_e32 v168, v168
	v_exp_f32_e32 v169, v169
	v_exp_f32_e32 v170, v170
	v_exp_f32_e32 v171, v171
	v_pk_add_f32 v[164:165], v[164:165], 1.0 op_sel_hi:[1,0]
	v_pk_add_f32 v[166:167], v[166:167], 1.0 op_sel_hi:[1,0]
	v_pk_add_f32 v[168:169], v[168:169], 1.0 op_sel_hi:[1,0]
	v_pk_add_f32 v[170:171], v[170:171], 1.0 op_sel_hi:[1,0]
	v_rcp_f32_e32 v164, v164
	v_rcp_f32_e32 v165, v165
	v_rcp_f32_e32 v166, v166
	v_rcp_f32_e32 v167, v167
	v_rcp_f32_e32 v168, v168
	v_rcp_f32_e32 v169, v169
	v_rcp_f32_e32 v170, v170
	v_rcp_f32_e32 v171, v171
	v_pk_mul_f32 v[164:165], v[12:13], v[164:165]
	v_pk_mul_f32 v[166:167], v[14:15], v[166:167]
	v_pk_mul_f32 v[168:169], v[16:17], v[168:169]
	v_pk_mul_f32 v[170:171], v[18:19], v[170:171]
	v_cvt_pk_bf16_f32 v174, v164, v165
	v_cvt_pk_bf16_f32 v175, v166, v167
	v_cvt_pk_bf16_f32 v176, v168, v169
	v_cvt_pk_bf16_f32 v177, v170, v171
	global_store_dwordx4 v1, v[174:177], s[22:23] offset:-3840
	s_waitcnt vmcnt(14)
	v_lshlrev_b32_e32 v164, 16, v182
	v_and_b32_e32 v165, 0xffff0000, v182
	v_lshlrev_b32_e32 v166, 16, v183
	v_and_b32_e32 v167, 0xffff0000, v183
	v_lshlrev_b32_e32 v168, 16, v184
	v_and_b32_e32 v169, 0xffff0000, v184
	v_lshlrev_b32_e32 v170, 16, v185
	v_and_b32_e32 v171, 0xffff0000, v185
	v_add_u32_e32 v2, s46, v158
	v_mad_u32_u24 v2, v2, s29, v0
	global_load_dwordx4 v[182:185], v2, s[96:97] offset:2304
	v_add_u32_e32 v1, s46, v146
	v_lshl_add_u32 v1, v1, 11, v0
	v_med3_f32 v164, v164, s34, v227
	v_med3_f32 v165, v165, s34, v227
	v_med3_f32 v166, v166, s34, v227
	v_med3_f32 v167, v167, s34, v227
	v_med3_f32 v168, v168, s34, v227
	v_med3_f32 v169, v169, s34, v227
	v_med3_f32 v170, v170, s34, v227
	v_med3_f32 v171, v171, s34, v227
	v_pk_mul_f32 v[164:165], v[164:165], s[44:45]
	v_pk_mul_f32 v[166:167], v[166:167], s[44:45]
	v_pk_mul_f32 v[168:169], v[168:169], s[44:45]
	v_pk_mul_f32 v[170:171], v[170:171], s[44:45]
	v_exp_f32_e32 v164, v164
	v_exp_f32_e32 v165, v165
	v_exp_f32_e32 v166, v166
	v_exp_f32_e32 v167, v167
	v_exp_f32_e32 v168, v168
	v_exp_f32_e32 v169, v169
	v_exp_f32_e32 v170, v170
	v_exp_f32_e32 v171, v171
	v_pk_add_f32 v[164:165], v[164:165], 1.0 op_sel_hi:[1,0]
	v_pk_add_f32 v[166:167], v[166:167], 1.0 op_sel_hi:[1,0]
	v_pk_add_f32 v[168:169], v[168:169], 1.0 op_sel_hi:[1,0]
	v_pk_add_f32 v[170:171], v[170:171], 1.0 op_sel_hi:[1,0]
	v_rcp_f32_e32 v164, v164
	v_rcp_f32_e32 v165, v165
	v_rcp_f32_e32 v166, v166
	v_rcp_f32_e32 v167, v167
	v_rcp_f32_e32 v168, v168
	v_rcp_f32_e32 v169, v169
	v_rcp_f32_e32 v170, v170
	v_rcp_f32_e32 v171, v171
	v_pk_mul_f32 v[164:165], v[128:129], v[164:165]
	v_pk_mul_f32 v[166:167], v[130:131], v[166:167]
	v_pk_mul_f32 v[168:169], v[124:125], v[168:169]
	v_pk_mul_f32 v[170:171], v[126:127], v[170:171]
	v_cvt_pk_bf16_f32 v174, v164, v165
	v_cvt_pk_bf16_f32 v175, v166, v167
	v_cvt_pk_bf16_f32 v176, v168, v169
	v_cvt_pk_bf16_f32 v177, v170, v171
	global_store_dwordx4 v1, v[174:177], s[22:23] offset:-4096
	s_waitcnt vmcnt(15)
	v_lshlrev_b32_e32 v164, 16, v186
	v_and_b32_e32 v165, 0xffff0000, v186
	v_lshlrev_b32_e32 v166, 16, v187
	v_and_b32_e32 v167, 0xffff0000, v187
	v_lshlrev_b32_e32 v168, 16, v188
	v_and_b32_e32 v169, 0xffff0000, v188
	v_lshlrev_b32_e32 v170, 16, v189
	v_and_b32_e32 v171, 0xffff0000, v189
	v_med3_f32 v164, v164, s34, v227
	v_med3_f32 v165, v165, s34, v227
	v_med3_f32 v166, v166, s34, v227
	v_med3_f32 v167, v167, s34, v227
	v_med3_f32 v168, v168, s34, v227
	v_med3_f32 v169, v169, s34, v227
	v_med3_f32 v170, v170, s34, v227
	v_med3_f32 v171, v171, s34, v227
	v_pk_mul_f32 v[164:165], v[164:165], s[44:45]
	v_pk_mul_f32 v[166:167], v[166:167], s[44:45]
	v_pk_mul_f32 v[168:169], v[168:169], s[44:45]
	v_pk_mul_f32 v[170:171], v[170:171], s[44:45]
	v_exp_f32_e32 v164, v164
	v_exp_f32_e32 v165, v165
	v_exp_f32_e32 v166, v166
	v_exp_f32_e32 v167, v167
	v_exp_f32_e32 v168, v168
	v_exp_f32_e32 v169, v169
	v_exp_f32_e32 v170, v170
	v_exp_f32_e32 v171, v171
	v_pk_add_f32 v[164:165], v[164:165], 1.0 op_sel_hi:[1,0]
	v_pk_add_f32 v[166:167], v[166:167], 1.0 op_sel_hi:[1,0]
	v_pk_add_f32 v[168:169], v[168:169], 1.0 op_sel_hi:[1,0]
	v_pk_add_f32 v[170:171], v[170:171], 1.0 op_sel_hi:[1,0]
	v_rcp_f32_e32 v164, v164
	v_rcp_f32_e32 v165, v165
	v_rcp_f32_e32 v166, v166
	v_rcp_f32_e32 v167, v167
	v_rcp_f32_e32 v168, v168
	v_rcp_f32_e32 v169, v169
	v_rcp_f32_e32 v170, v170
	v_rcp_f32_e32 v171, v171
	v_pk_mul_f32 v[164:165], v[104:105], v[164:165]
	v_pk_mul_f32 v[166:167], v[106:107], v[166:167]
	v_pk_mul_f32 v[168:169], v[100:101], v[168:169]
	v_pk_mul_f32 v[170:171], v[102:103], v[170:171]
	v_cvt_pk_bf16_f32 v174, v164, v165
	v_cvt_pk_bf16_f32 v175, v166, v167
	v_cvt_pk_bf16_f32 v176, v168, v169
	v_cvt_pk_bf16_f32 v177, v170, v171
	global_store_dwordx4 v1, v[174:177], s[22:23] offset:-3840
	s_waitcnt vmcnt(15)
	v_lshlrev_b32_e32 v164, 16, v190
	v_and_b32_e32 v165, 0xffff0000, v190
	v_lshlrev_b32_e32 v166, 16, v191
	v_and_b32_e32 v167, 0xffff0000, v191
	v_lshlrev_b32_e32 v168, 16, v192
	v_and_b32_e32 v169, 0xffff0000, v192
	v_lshlrev_b32_e32 v170, 16, v193
	v_and_b32_e32 v171, 0xffff0000, v193
	v_add_u32_e32 v1, s46, v148
	v_lshl_add_u32 v1, v1, 11, v0
	v_med3_f32 v164, v164, s34, v227
	v_med3_f32 v165, v165, s34, v227
	v_med3_f32 v166, v166, s34, v227
	v_med3_f32 v167, v167, s34, v227
	v_med3_f32 v168, v168, s34, v227
	v_med3_f32 v169, v169, s34, v227
	v_med3_f32 v170, v170, s34, v227
	v_med3_f32 v171, v171, s34, v227
	v_pk_mul_f32 v[164:165], v[164:165], s[44:45]
	v_pk_mul_f32 v[166:167], v[166:167], s[44:45]
	v_pk_mul_f32 v[168:169], v[168:169], s[44:45]
	v_pk_mul_f32 v[170:171], v[170:171], s[44:45]
	v_exp_f32_e32 v164, v164
	v_exp_f32_e32 v165, v165
	v_exp_f32_e32 v166, v166
	v_exp_f32_e32 v167, v167
	v_exp_f32_e32 v168, v168
	v_exp_f32_e32 v169, v169
	v_exp_f32_e32 v170, v170
	v_exp_f32_e32 v171, v171
	v_pk_add_f32 v[164:165], v[164:165], 1.0 op_sel_hi:[1,0]
	v_pk_add_f32 v[166:167], v[166:167], 1.0 op_sel_hi:[1,0]
	v_pk_add_f32 v[168:169], v[168:169], 1.0 op_sel_hi:[1,0]
	v_pk_add_f32 v[170:171], v[170:171], 1.0 op_sel_hi:[1,0]
	v_rcp_f32_e32 v164, v164
	v_rcp_f32_e32 v165, v165
	v_rcp_f32_e32 v166, v166
	v_rcp_f32_e32 v167, v167
	v_rcp_f32_e32 v168, v168
	v_rcp_f32_e32 v169, v169
	v_rcp_f32_e32 v170, v170
	v_rcp_f32_e32 v171, v171
	v_pk_mul_f32 v[164:165], v[120:121], v[164:165]
	v_pk_mul_f32 v[166:167], v[122:123], v[166:167]
	v_pk_mul_f32 v[168:169], v[116:117], v[168:169]
	v_pk_mul_f32 v[170:171], v[118:119], v[170:171]
	v_cvt_pk_bf16_f32 v174, v164, v165
	v_cvt_pk_bf16_f32 v175, v166, v167
	v_cvt_pk_bf16_f32 v176, v168, v169
	v_cvt_pk_bf16_f32 v177, v170, v171
	global_store_dwordx4 v1, v[174:177], s[22:23] offset:-4096
	s_waitcnt vmcnt(15)
	v_lshlrev_b32_e32 v164, 16, v202
	v_and_b32_e32 v165, 0xffff0000, v202
	v_lshlrev_b32_e32 v166, 16, v203
	v_and_b32_e32 v167, 0xffff0000, v203
	v_lshlrev_b32_e32 v168, 16, v204
	v_and_b32_e32 v169, 0xffff0000, v204
	v_lshlrev_b32_e32 v170, 16, v205
	v_and_b32_e32 v171, 0xffff0000, v205
	v_med3_f32 v164, v164, s34, v227
	v_med3_f32 v165, v165, s34, v227
	v_med3_f32 v166, v166, s34, v227
	v_med3_f32 v167, v167, s34, v227
	v_med3_f32 v168, v168, s34, v227
	v_med3_f32 v169, v169, s34, v227
	v_med3_f32 v170, v170, s34, v227
	v_med3_f32 v171, v171, s34, v227
	v_pk_mul_f32 v[164:165], v[164:165], s[44:45]
	v_pk_mul_f32 v[166:167], v[166:167], s[44:45]
	v_pk_mul_f32 v[168:169], v[168:169], s[44:45]
	v_pk_mul_f32 v[170:171], v[170:171], s[44:45]
	v_exp_f32_e32 v164, v164
	v_exp_f32_e32 v165, v165
	v_exp_f32_e32 v166, v166
	v_exp_f32_e32 v167, v167
	v_exp_f32_e32 v168, v168
	v_exp_f32_e32 v169, v169
	v_exp_f32_e32 v170, v170
	v_exp_f32_e32 v171, v171
	v_pk_add_f32 v[164:165], v[164:165], 1.0 op_sel_hi:[1,0]
	v_pk_add_f32 v[166:167], v[166:167], 1.0 op_sel_hi:[1,0]
	v_pk_add_f32 v[168:169], v[168:169], 1.0 op_sel_hi:[1,0]
	v_pk_add_f32 v[170:171], v[170:171], 1.0 op_sel_hi:[1,0]
	v_rcp_f32_e32 v164, v164
	v_rcp_f32_e32 v165, v165
	v_rcp_f32_e32 v166, v166
	v_rcp_f32_e32 v167, v167
	v_rcp_f32_e32 v168, v168
	v_rcp_f32_e32 v169, v169
	v_rcp_f32_e32 v170, v170
	v_rcp_f32_e32 v171, v171
	v_pk_mul_f32 v[164:165], v[96:97], v[164:165]
	v_pk_mul_f32 v[166:167], v[98:99], v[166:167]
	v_pk_mul_f32 v[168:169], v[92:93], v[168:169]
	v_pk_mul_f32 v[170:171], v[94:95], v[170:171]
	v_cvt_pk_bf16_f32 v174, v164, v165
	v_cvt_pk_bf16_f32 v175, v166, v167
	v_cvt_pk_bf16_f32 v176, v168, v169
	v_cvt_pk_bf16_f32 v177, v170, v171
	global_store_dwordx4 v1, v[174:177], s[22:23] offset:-3840
	s_waitcnt vmcnt(15)
	v_lshlrev_b32_e32 v164, 16, v206
	v_and_b32_e32 v165, 0xffff0000, v206
	v_lshlrev_b32_e32 v166, 16, v207
	v_and_b32_e32 v167, 0xffff0000, v207
	v_lshlrev_b32_e32 v168, 16, v208
	v_and_b32_e32 v169, 0xffff0000, v208
	v_lshlrev_b32_e32 v170, 16, v209
	v_and_b32_e32 v171, 0xffff0000, v209
	v_add_u32_e32 v1, s46, v150
	v_lshl_add_u32 v1, v1, 11, v0
	v_med3_f32 v164, v164, s34, v227
	v_med3_f32 v165, v165, s34, v227
	v_med3_f32 v166, v166, s34, v227
	v_med3_f32 v167, v167, s34, v227
	v_med3_f32 v168, v168, s34, v227
	v_med3_f32 v169, v169, s34, v227
	v_med3_f32 v170, v170, s34, v227
	v_med3_f32 v171, v171, s34, v227
	v_pk_mul_f32 v[164:165], v[164:165], s[44:45]
	v_pk_mul_f32 v[166:167], v[166:167], s[44:45]
	v_pk_mul_f32 v[168:169], v[168:169], s[44:45]
	v_pk_mul_f32 v[170:171], v[170:171], s[44:45]
	v_exp_f32_e32 v164, v164
	v_exp_f32_e32 v165, v165
	v_exp_f32_e32 v166, v166
	v_exp_f32_e32 v167, v167
	v_exp_f32_e32 v168, v168
	v_exp_f32_e32 v169, v169
	v_exp_f32_e32 v170, v170
	v_exp_f32_e32 v171, v171
	v_pk_add_f32 v[164:165], v[164:165], 1.0 op_sel_hi:[1,0]
	v_pk_add_f32 v[166:167], v[166:167], 1.0 op_sel_hi:[1,0]
	v_pk_add_f32 v[168:169], v[168:169], 1.0 op_sel_hi:[1,0]
	v_pk_add_f32 v[170:171], v[170:171], 1.0 op_sel_hi:[1,0]
	v_rcp_f32_e32 v164, v164
	v_rcp_f32_e32 v165, v165
	v_rcp_f32_e32 v166, v166
	v_rcp_f32_e32 v167, v167
	v_rcp_f32_e32 v168, v168
	v_rcp_f32_e32 v169, v169
	v_rcp_f32_e32 v170, v170
	v_rcp_f32_e32 v171, v171
	v_pk_mul_f32 v[164:165], v[112:113], v[164:165]
	v_pk_mul_f32 v[166:167], v[114:115], v[166:167]
	v_pk_mul_f32 v[168:169], v[108:109], v[168:169]
	v_pk_mul_f32 v[170:171], v[110:111], v[170:171]
	v_cvt_pk_bf16_f32 v174, v164, v165
	v_cvt_pk_bf16_f32 v175, v166, v167
	v_cvt_pk_bf16_f32 v176, v168, v169
	v_cvt_pk_bf16_f32 v177, v170, v171
	global_store_dwordx4 v1, v[174:177], s[22:23] offset:-4096
	s_waitcnt vmcnt(15)
	v_lshlrev_b32_e32 v164, 16, v210
	v_and_b32_e32 v165, 0xffff0000, v210
	v_lshlrev_b32_e32 v166, 16, v211
	v_and_b32_e32 v167, 0xffff0000, v211
	v_lshlrev_b32_e32 v168, 16, v212
	v_and_b32_e32 v169, 0xffff0000, v212
	v_lshlrev_b32_e32 v170, 16, v213
	v_and_b32_e32 v171, 0xffff0000, v213
	v_med3_f32 v164, v164, s34, v227
	v_med3_f32 v165, v165, s34, v227
	v_med3_f32 v166, v166, s34, v227
	v_med3_f32 v167, v167, s34, v227
	v_med3_f32 v168, v168, s34, v227
	v_med3_f32 v169, v169, s34, v227
	v_med3_f32 v170, v170, s34, v227
	v_med3_f32 v171, v171, s34, v227
	v_pk_mul_f32 v[164:165], v[164:165], s[44:45]
	v_pk_mul_f32 v[166:167], v[166:167], s[44:45]
	v_pk_mul_f32 v[168:169], v[168:169], s[44:45]
	v_pk_mul_f32 v[170:171], v[170:171], s[44:45]
	v_exp_f32_e32 v164, v164
	v_exp_f32_e32 v165, v165
	v_exp_f32_e32 v166, v166
	v_exp_f32_e32 v167, v167
	v_exp_f32_e32 v168, v168
	v_exp_f32_e32 v169, v169
	v_exp_f32_e32 v170, v170
	v_exp_f32_e32 v171, v171
	v_pk_add_f32 v[164:165], v[164:165], 1.0 op_sel_hi:[1,0]
	v_pk_add_f32 v[166:167], v[166:167], 1.0 op_sel_hi:[1,0]
	v_pk_add_f32 v[168:169], v[168:169], 1.0 op_sel_hi:[1,0]
	v_pk_add_f32 v[170:171], v[170:171], 1.0 op_sel_hi:[1,0]
	v_rcp_f32_e32 v164, v164
	v_rcp_f32_e32 v165, v165
	v_rcp_f32_e32 v166, v166
	v_rcp_f32_e32 v167, v167
	v_rcp_f32_e32 v168, v168
	v_rcp_f32_e32 v169, v169
	v_rcp_f32_e32 v170, v170
	v_rcp_f32_e32 v171, v171
	v_pk_mul_f32 v[164:165], v[88:89], v[164:165]
	v_pk_mul_f32 v[166:167], v[90:91], v[166:167]
	v_pk_mul_f32 v[168:169], v[84:85], v[168:169]
	v_pk_mul_f32 v[170:171], v[86:87], v[170:171]
	v_cvt_pk_bf16_f32 v174, v164, v165
	v_cvt_pk_bf16_f32 v175, v166, v167
	v_cvt_pk_bf16_f32 v176, v168, v169
	v_cvt_pk_bf16_f32 v177, v170, v171
	global_store_dwordx4 v1, v[174:177], s[22:23] offset:-3840
	s_waitcnt vmcnt(15)
	v_lshlrev_b32_e32 v164, 16, v214
	v_and_b32_e32 v165, 0xffff0000, v214
	v_lshlrev_b32_e32 v166, 16, v215
	v_and_b32_e32 v167, 0xffff0000, v215
	v_lshlrev_b32_e32 v168, 16, v216
	v_and_b32_e32 v169, 0xffff0000, v216
	v_lshlrev_b32_e32 v170, 16, v217
	v_and_b32_e32 v171, 0xffff0000, v217
	v_add_u32_e32 v1, s46, v152
	v_lshl_add_u32 v1, v1, 11, v0
	v_med3_f32 v164, v164, s34, v227
	v_med3_f32 v165, v165, s34, v227
	v_med3_f32 v166, v166, s34, v227
	v_med3_f32 v167, v167, s34, v227
	v_med3_f32 v168, v168, s34, v227
	v_med3_f32 v169, v169, s34, v227
	v_med3_f32 v170, v170, s34, v227
	v_med3_f32 v171, v171, s34, v227
	v_pk_mul_f32 v[164:165], v[164:165], s[44:45]
	v_pk_mul_f32 v[166:167], v[166:167], s[44:45]
	v_pk_mul_f32 v[168:169], v[168:169], s[44:45]
	v_pk_mul_f32 v[170:171], v[170:171], s[44:45]
	v_exp_f32_e32 v164, v164
	v_exp_f32_e32 v165, v165
	v_exp_f32_e32 v166, v166
	v_exp_f32_e32 v167, v167
	v_exp_f32_e32 v168, v168
	v_exp_f32_e32 v169, v169
	v_exp_f32_e32 v170, v170
	v_exp_f32_e32 v171, v171
	v_pk_add_f32 v[164:165], v[164:165], 1.0 op_sel_hi:[1,0]
	v_pk_add_f32 v[166:167], v[166:167], 1.0 op_sel_hi:[1,0]
	v_pk_add_f32 v[168:169], v[168:169], 1.0 op_sel_hi:[1,0]
	v_pk_add_f32 v[170:171], v[170:171], 1.0 op_sel_hi:[1,0]
	v_rcp_f32_e32 v164, v164
	v_rcp_f32_e32 v165, v165
	v_rcp_f32_e32 v166, v166
	v_rcp_f32_e32 v167, v167
	v_rcp_f32_e32 v168, v168
	v_rcp_f32_e32 v169, v169
	v_rcp_f32_e32 v170, v170
	v_rcp_f32_e32 v171, v171
	v_pk_mul_f32 v[164:165], v[80:81], v[164:165]
	v_pk_mul_f32 v[166:167], v[82:83], v[166:167]
	v_pk_mul_f32 v[168:169], v[76:77], v[168:169]
	v_pk_mul_f32 v[170:171], v[78:79], v[170:171]
	v_cvt_pk_bf16_f32 v174, v164, v165
	v_cvt_pk_bf16_f32 v175, v166, v167
	v_cvt_pk_bf16_f32 v176, v168, v169
	v_cvt_pk_bf16_f32 v177, v170, v171
	global_store_dwordx4 v1, v[174:177], s[22:23] offset:-4096
	s_waitcnt vmcnt(15)
	v_lshlrev_b32_e32 v164, 16, v236
	v_and_b32_e32 v165, 0xffff0000, v236
	v_lshlrev_b32_e32 v166, 16, v237
	v_and_b32_e32 v167, 0xffff0000, v237
	v_lshlrev_b32_e32 v168, 16, v238
	v_and_b32_e32 v169, 0xffff0000, v238
	v_lshlrev_b32_e32 v170, 16, v239
	v_and_b32_e32 v171, 0xffff0000, v239
	v_med3_f32 v164, v164, s34, v227
	v_med3_f32 v165, v165, s34, v227
	v_med3_f32 v166, v166, s34, v227
	v_med3_f32 v167, v167, s34, v227
	v_med3_f32 v168, v168, s34, v227
	v_med3_f32 v169, v169, s34, v227
	v_med3_f32 v170, v170, s34, v227
	v_med3_f32 v171, v171, s34, v227
	v_pk_mul_f32 v[164:165], v[164:165], s[44:45]
	v_pk_mul_f32 v[166:167], v[166:167], s[44:45]
	v_pk_mul_f32 v[168:169], v[168:169], s[44:45]
	v_pk_mul_f32 v[170:171], v[170:171], s[44:45]
	v_exp_f32_e32 v164, v164
	v_exp_f32_e32 v165, v165
	v_exp_f32_e32 v166, v166
	v_exp_f32_e32 v167, v167
	v_exp_f32_e32 v168, v168
	v_exp_f32_e32 v169, v169
	v_exp_f32_e32 v170, v170
	v_exp_f32_e32 v171, v171
	v_pk_add_f32 v[164:165], v[164:165], 1.0 op_sel_hi:[1,0]
	v_pk_add_f32 v[166:167], v[166:167], 1.0 op_sel_hi:[1,0]
	v_pk_add_f32 v[168:169], v[168:169], 1.0 op_sel_hi:[1,0]
	v_pk_add_f32 v[170:171], v[170:171], 1.0 op_sel_hi:[1,0]
	v_rcp_f32_e32 v164, v164
	v_rcp_f32_e32 v165, v165
	v_rcp_f32_e32 v166, v166
	v_rcp_f32_e32 v167, v167
	v_rcp_f32_e32 v168, v168
	v_rcp_f32_e32 v169, v169
	v_rcp_f32_e32 v170, v170
	v_rcp_f32_e32 v171, v171
	v_pk_mul_f32 v[164:165], v[48:49], v[164:165]
	v_pk_mul_f32 v[166:167], v[50:51], v[166:167]
	v_pk_mul_f32 v[168:169], v[44:45], v[168:169]
	v_pk_mul_f32 v[170:171], v[46:47], v[170:171]
	v_cvt_pk_bf16_f32 v174, v164, v165
	v_cvt_pk_bf16_f32 v175, v166, v167
	v_cvt_pk_bf16_f32 v176, v168, v169
	v_cvt_pk_bf16_f32 v177, v170, v171
	global_store_dwordx4 v1, v[174:177], s[22:23] offset:-3840
	s_waitcnt vmcnt(15)
	v_lshlrev_b32_e32 v164, 16, v240
	v_and_b32_e32 v165, 0xffff0000, v240
	v_lshlrev_b32_e32 v166, 16, v241
	v_and_b32_e32 v167, 0xffff0000, v241
	v_lshlrev_b32_e32 v168, 16, v242
	v_and_b32_e32 v169, 0xffff0000, v242
	v_lshlrev_b32_e32 v170, 16, v243
	v_and_b32_e32 v171, 0xffff0000, v243
	v_add_u32_e32 v1, s46, v154
	v_lshl_add_u32 v1, v1, 11, v0
	v_med3_f32 v164, v164, s34, v227
	v_med3_f32 v165, v165, s34, v227
	v_med3_f32 v166, v166, s34, v227
	v_med3_f32 v167, v167, s34, v227
	v_med3_f32 v168, v168, s34, v227
	v_med3_f32 v169, v169, s34, v227
	v_med3_f32 v170, v170, s34, v227
	v_med3_f32 v171, v171, s34, v227
	v_pk_mul_f32 v[164:165], v[164:165], s[44:45]
	v_pk_mul_f32 v[166:167], v[166:167], s[44:45]
	v_pk_mul_f32 v[168:169], v[168:169], s[44:45]
	v_pk_mul_f32 v[170:171], v[170:171], s[44:45]
	v_exp_f32_e32 v164, v164
	v_exp_f32_e32 v165, v165
	v_exp_f32_e32 v166, v166
	v_exp_f32_e32 v167, v167
	v_exp_f32_e32 v168, v168
	v_exp_f32_e32 v169, v169
	v_exp_f32_e32 v170, v170
	v_exp_f32_e32 v171, v171
	v_pk_add_f32 v[164:165], v[164:165], 1.0 op_sel_hi:[1,0]
	v_pk_add_f32 v[166:167], v[166:167], 1.0 op_sel_hi:[1,0]
	v_pk_add_f32 v[168:169], v[168:169], 1.0 op_sel_hi:[1,0]
	v_pk_add_f32 v[170:171], v[170:171], 1.0 op_sel_hi:[1,0]
	v_rcp_f32_e32 v164, v164
	v_rcp_f32_e32 v165, v165
	v_rcp_f32_e32 v166, v166
	v_rcp_f32_e32 v167, v167
	v_rcp_f32_e32 v168, v168
	v_rcp_f32_e32 v169, v169
	v_rcp_f32_e32 v170, v170
	v_rcp_f32_e32 v171, v171
	v_pk_mul_f32 v[164:165], v[72:73], v[164:165]
	v_pk_mul_f32 v[166:167], v[74:75], v[166:167]
	v_pk_mul_f32 v[168:169], v[68:69], v[168:169]
	v_pk_mul_f32 v[170:171], v[70:71], v[170:171]
	v_cvt_pk_bf16_f32 v174, v164, v165
	v_cvt_pk_bf16_f32 v175, v166, v167
	v_cvt_pk_bf16_f32 v176, v168, v169
	v_cvt_pk_bf16_f32 v177, v170, v171
	global_store_dwordx4 v1, v[174:177], s[22:23] offset:-4096
	s_waitcnt vmcnt(15)
	v_lshlrev_b32_e32 v164, 16, v244
	v_and_b32_e32 v165, 0xffff0000, v244
	v_lshlrev_b32_e32 v166, 16, v245
	v_and_b32_e32 v167, 0xffff0000, v245
	v_lshlrev_b32_e32 v168, 16, v246
	v_and_b32_e32 v169, 0xffff0000, v246
	v_lshlrev_b32_e32 v170, 16, v247
	v_and_b32_e32 v171, 0xffff0000, v247
	v_med3_f32 v164, v164, s34, v227
	v_med3_f32 v165, v165, s34, v227
	v_med3_f32 v166, v166, s34, v227
	v_med3_f32 v167, v167, s34, v227
	v_med3_f32 v168, v168, s34, v227
	v_med3_f32 v169, v169, s34, v227
	v_med3_f32 v170, v170, s34, v227
	v_med3_f32 v171, v171, s34, v227
	v_pk_mul_f32 v[164:165], v[164:165], s[44:45]
	v_pk_mul_f32 v[166:167], v[166:167], s[44:45]
	v_pk_mul_f32 v[168:169], v[168:169], s[44:45]
	v_pk_mul_f32 v[170:171], v[170:171], s[44:45]
	v_exp_f32_e32 v164, v164
	v_exp_f32_e32 v165, v165
	v_exp_f32_e32 v166, v166
	v_exp_f32_e32 v167, v167
	v_exp_f32_e32 v168, v168
	v_exp_f32_e32 v169, v169
	v_exp_f32_e32 v170, v170
	v_exp_f32_e32 v171, v171
	v_pk_add_f32 v[164:165], v[164:165], 1.0 op_sel_hi:[1,0]
	v_pk_add_f32 v[166:167], v[166:167], 1.0 op_sel_hi:[1,0]
	v_pk_add_f32 v[168:169], v[168:169], 1.0 op_sel_hi:[1,0]
	v_pk_add_f32 v[170:171], v[170:171], 1.0 op_sel_hi:[1,0]
	v_rcp_f32_e32 v164, v164
	v_rcp_f32_e32 v165, v165
	v_rcp_f32_e32 v166, v166
	v_rcp_f32_e32 v167, v167
	v_rcp_f32_e32 v168, v168
	v_rcp_f32_e32 v169, v169
	v_rcp_f32_e32 v170, v170
	v_rcp_f32_e32 v171, v171
	v_pk_mul_f32 v[164:165], v[40:41], v[164:165]
	v_pk_mul_f32 v[166:167], v[42:43], v[166:167]
	v_pk_mul_f32 v[168:169], v[36:37], v[168:169]
	v_pk_mul_f32 v[170:171], v[38:39], v[170:171]
	v_cvt_pk_bf16_f32 v174, v164, v165
	v_cvt_pk_bf16_f32 v175, v166, v167
	v_cvt_pk_bf16_f32 v176, v168, v169
	v_cvt_pk_bf16_f32 v177, v170, v171
	global_store_dwordx4 v1, v[174:177], s[22:23] offset:-3840
	s_waitcnt vmcnt(15)
	v_lshlrev_b32_e32 v164, 16, v248
	v_and_b32_e32 v165, 0xffff0000, v248
	v_lshlrev_b32_e32 v166, 16, v249
	v_and_b32_e32 v167, 0xffff0000, v249
	v_lshlrev_b32_e32 v168, 16, v250
	v_and_b32_e32 v169, 0xffff0000, v250
	v_lshlrev_b32_e32 v170, 16, v251
	v_and_b32_e32 v171, 0xffff0000, v251
	v_add_u32_e32 v1, s46, v156
	v_lshl_add_u32 v1, v1, 11, v0
	v_med3_f32 v164, v164, s34, v227
	v_med3_f32 v165, v165, s34, v227
	v_med3_f32 v166, v166, s34, v227
	v_med3_f32 v167, v167, s34, v227
	v_med3_f32 v168, v168, s34, v227
	v_med3_f32 v169, v169, s34, v227
	v_med3_f32 v170, v170, s34, v227
	v_med3_f32 v171, v171, s34, v227
	v_pk_mul_f32 v[164:165], v[164:165], s[44:45]
	v_pk_mul_f32 v[166:167], v[166:167], s[44:45]
	v_pk_mul_f32 v[168:169], v[168:169], s[44:45]
	v_pk_mul_f32 v[170:171], v[170:171], s[44:45]
	v_exp_f32_e32 v164, v164
	v_exp_f32_e32 v165, v165
	v_exp_f32_e32 v166, v166
	v_exp_f32_e32 v167, v167
	v_exp_f32_e32 v168, v168
	v_exp_f32_e32 v169, v169
	v_exp_f32_e32 v170, v170
	v_exp_f32_e32 v171, v171
	v_pk_add_f32 v[164:165], v[164:165], 1.0 op_sel_hi:[1,0]
	v_pk_add_f32 v[166:167], v[166:167], 1.0 op_sel_hi:[1,0]
	v_pk_add_f32 v[168:169], v[168:169], 1.0 op_sel_hi:[1,0]
	v_pk_add_f32 v[170:171], v[170:171], 1.0 op_sel_hi:[1,0]
	v_rcp_f32_e32 v164, v164
	v_rcp_f32_e32 v165, v165
	v_rcp_f32_e32 v166, v166
	v_rcp_f32_e32 v167, v167
	v_rcp_f32_e32 v168, v168
	v_rcp_f32_e32 v169, v169
	v_rcp_f32_e32 v170, v170
	v_rcp_f32_e32 v171, v171
	v_pk_mul_f32 v[164:165], v[64:65], v[164:165]
	v_pk_mul_f32 v[166:167], v[66:67], v[166:167]
	v_pk_mul_f32 v[168:169], v[60:61], v[168:169]
	v_pk_mul_f32 v[170:171], v[62:63], v[170:171]
	v_cvt_pk_bf16_f32 v174, v164, v165
	v_cvt_pk_bf16_f32 v175, v166, v167
	v_cvt_pk_bf16_f32 v176, v168, v169
	v_cvt_pk_bf16_f32 v177, v170, v171
	global_store_dwordx4 v1, v[174:177], s[22:23] offset:-4096
	s_waitcnt vmcnt(15)
	v_lshlrev_b32_e32 v164, 16, v132
	v_and_b32_e32 v165, 0xffff0000, v132
	v_lshlrev_b32_e32 v166, 16, v133
	v_and_b32_e32 v167, 0xffff0000, v133
	v_lshlrev_b32_e32 v168, 16, v134
	v_and_b32_e32 v169, 0xffff0000, v134
	v_lshlrev_b32_e32 v170, 16, v135
	v_and_b32_e32 v171, 0xffff0000, v135
	v_med3_f32 v164, v164, s34, v227
	v_med3_f32 v165, v165, s34, v227
	v_med3_f32 v166, v166, s34, v227
	v_med3_f32 v167, v167, s34, v227
	v_med3_f32 v168, v168, s34, v227
	v_med3_f32 v169, v169, s34, v227
	v_med3_f32 v170, v170, s34, v227
	v_med3_f32 v171, v171, s34, v227
	v_pk_mul_f32 v[164:165], v[164:165], s[44:45]
	v_pk_mul_f32 v[166:167], v[166:167], s[44:45]
	v_pk_mul_f32 v[168:169], v[168:169], s[44:45]
	v_pk_mul_f32 v[170:171], v[170:171], s[44:45]
	v_exp_f32_e32 v164, v164
	v_exp_f32_e32 v165, v165
	v_exp_f32_e32 v166, v166
	v_exp_f32_e32 v167, v167
	v_exp_f32_e32 v168, v168
	v_exp_f32_e32 v169, v169
	v_exp_f32_e32 v170, v170
	v_exp_f32_e32 v171, v171
	v_pk_add_f32 v[164:165], v[164:165], 1.0 op_sel_hi:[1,0]
	v_pk_add_f32 v[166:167], v[166:167], 1.0 op_sel_hi:[1,0]
	v_pk_add_f32 v[168:169], v[168:169], 1.0 op_sel_hi:[1,0]
	v_pk_add_f32 v[170:171], v[170:171], 1.0 op_sel_hi:[1,0]
	v_rcp_f32_e32 v164, v164
	v_rcp_f32_e32 v165, v165
	v_rcp_f32_e32 v166, v166
	v_rcp_f32_e32 v167, v167
	v_rcp_f32_e32 v168, v168
	v_rcp_f32_e32 v169, v169
	v_rcp_f32_e32 v170, v170
	v_rcp_f32_e32 v171, v171
	v_pk_mul_f32 v[164:165], v[32:33], v[164:165]
	v_pk_mul_f32 v[166:167], v[34:35], v[166:167]
	v_pk_mul_f32 v[168:169], v[28:29], v[168:169]
	v_pk_mul_f32 v[170:171], v[30:31], v[170:171]
	v_cvt_pk_bf16_f32 v174, v164, v165
	v_cvt_pk_bf16_f32 v175, v166, v167
	v_cvt_pk_bf16_f32 v176, v168, v169
	v_cvt_pk_bf16_f32 v177, v170, v171
	global_store_dwordx4 v1, v[174:177], s[22:23] offset:-3840
	s_waitcnt vmcnt(14)
	v_lshlrev_b32_e32 v164, 16, v178
	v_and_b32_e32 v165, 0xffff0000, v178
	v_lshlrev_b32_e32 v166, 16, v179
	v_and_b32_e32 v167, 0xffff0000, v179
	v_lshlrev_b32_e32 v168, 16, v180
	v_and_b32_e32 v169, 0xffff0000, v180
	v_lshlrev_b32_e32 v170, 16, v181
	v_and_b32_e32 v171, 0xffff0000, v181
	v_add_u32_e32 v1, s46, v158
	v_lshl_add_u32 v1, v1, 11, v0
	v_med3_f32 v164, v164, s34, v227
	v_med3_f32 v165, v165, s34, v227
	v_med3_f32 v166, v166, s34, v227
	v_med3_f32 v167, v167, s34, v227
	v_med3_f32 v168, v168, s34, v227
	v_med3_f32 v169, v169, s34, v227
	v_med3_f32 v170, v170, s34, v227
	v_med3_f32 v171, v171, s34, v227
	v_pk_mul_f32 v[164:165], v[164:165], s[44:45]
	v_pk_mul_f32 v[166:167], v[166:167], s[44:45]
	v_pk_mul_f32 v[168:169], v[168:169], s[44:45]
	v_pk_mul_f32 v[170:171], v[170:171], s[44:45]
	v_exp_f32_e32 v164, v164
	v_exp_f32_e32 v165, v165
	v_exp_f32_e32 v166, v166
	v_exp_f32_e32 v167, v167
	v_exp_f32_e32 v168, v168
	v_exp_f32_e32 v169, v169
	v_exp_f32_e32 v170, v170
	v_exp_f32_e32 v171, v171
	v_pk_add_f32 v[164:165], v[164:165], 1.0 op_sel_hi:[1,0]
	v_pk_add_f32 v[166:167], v[166:167], 1.0 op_sel_hi:[1,0]
	v_pk_add_f32 v[168:169], v[168:169], 1.0 op_sel_hi:[1,0]
	v_pk_add_f32 v[170:171], v[170:171], 1.0 op_sel_hi:[1,0]
	v_rcp_f32_e32 v164, v164
	v_rcp_f32_e32 v165, v165
	v_rcp_f32_e32 v166, v166
	v_rcp_f32_e32 v167, v167
	v_rcp_f32_e32 v168, v168
	v_rcp_f32_e32 v169, v169
	v_rcp_f32_e32 v170, v170
	v_rcp_f32_e32 v171, v171
	v_pk_mul_f32 v[164:165], v[56:57], v[164:165]
	v_pk_mul_f32 v[166:167], v[58:59], v[166:167]
	v_pk_mul_f32 v[168:169], v[52:53], v[168:169]
	v_pk_mul_f32 v[170:171], v[54:55], v[170:171]
	v_cvt_pk_bf16_f32 v174, v164, v165
	v_cvt_pk_bf16_f32 v175, v166, v167
	v_cvt_pk_bf16_f32 v176, v168, v169
	v_cvt_pk_bf16_f32 v177, v170, v171
	global_store_dwordx4 v1, v[174:177], s[22:23] offset:-4096
	s_waitcnt vmcnt(13)
	v_lshlrev_b32_e32 v164, 16, v182
	v_and_b32_e32 v165, 0xffff0000, v182
	v_lshlrev_b32_e32 v166, 16, v183
	v_and_b32_e32 v167, 0xffff0000, v183
	v_lshlrev_b32_e32 v168, 16, v184
	v_and_b32_e32 v169, 0xffff0000, v184
	v_lshlrev_b32_e32 v170, 16, v185
	v_and_b32_e32 v171, 0xffff0000, v185
	v_med3_f32 v164, v164, s34, v227
	v_med3_f32 v165, v165, s34, v227
	v_med3_f32 v166, v166, s34, v227
	v_med3_f32 v167, v167, s34, v227
	v_med3_f32 v168, v168, s34, v227
	v_med3_f32 v169, v169, s34, v227
	v_med3_f32 v170, v170, s34, v227
	v_med3_f32 v171, v171, s34, v227
	v_pk_mul_f32 v[164:165], v[164:165], s[44:45]
	v_pk_mul_f32 v[166:167], v[166:167], s[44:45]
	v_pk_mul_f32 v[168:169], v[168:169], s[44:45]
	v_pk_mul_f32 v[170:171], v[170:171], s[44:45]
	v_exp_f32_e32 v164, v164
	v_exp_f32_e32 v165, v165
	v_exp_f32_e32 v166, v166
	v_exp_f32_e32 v167, v167
	v_exp_f32_e32 v168, v168
	v_exp_f32_e32 v169, v169
	v_exp_f32_e32 v170, v170
	v_exp_f32_e32 v171, v171
	v_pk_add_f32 v[164:165], v[164:165], 1.0 op_sel_hi:[1,0]
	v_pk_add_f32 v[166:167], v[166:167], 1.0 op_sel_hi:[1,0]
	v_pk_add_f32 v[168:169], v[168:169], 1.0 op_sel_hi:[1,0]
	v_pk_add_f32 v[170:171], v[170:171], 1.0 op_sel_hi:[1,0]
	v_rcp_f32_e32 v164, v164
	v_rcp_f32_e32 v165, v165
	v_rcp_f32_e32 v166, v166
	v_rcp_f32_e32 v167, v167
	v_rcp_f32_e32 v168, v168
	v_rcp_f32_e32 v169, v169
	v_rcp_f32_e32 v170, v170
	v_rcp_f32_e32 v171, v171
	v_pk_mul_f32 v[164:165], v[24:25], v[164:165]
	v_pk_mul_f32 v[166:167], v[26:27], v[166:167]
	v_pk_mul_f32 v[168:169], v[20:21], v[168:169]
	v_pk_mul_f32 v[170:171], v[22:23], v[170:171]
	v_cvt_pk_bf16_f32 v174, v164, v165
	v_cvt_pk_bf16_f32 v175, v166, v167
	v_cvt_pk_bf16_f32 v176, v168, v169
	v_cvt_pk_bf16_f32 v177, v170, v171
	global_store_dwordx4 v1, v[174:177], s[22:23] offset:-3840
	s_mov_b64 s[40:41], 0
	s_branch .LBB0_206

.LBB0_242:
	s_add_u32 s23, s0, 0xfffc0080
	s_addc_u32 s24, s1, -1
	s_add_i32 s25, 0, 0x10000
	v_add_u32_e32 v2, s25, v187
	ds_read_b128 v[132:135], v2
	ds_read_b128 v[136:139], v2 offset:1024
	ds_read_b128 v[140:143], v2 offset:2048
	ds_read_b128 v[144:147], v2 offset:3072
	s_cmp_eq_u32 s22, 12
	s_cselect_b32 s47, s57, s24
	s_cselect_b32 s46, s56, s23
	s_cselect_b32 s45, s59, s21
	s_cselect_b32 s44, s58, s20
	v_lshl_add_u64 v[208:209], s[0:1], 0, v[194:195]
	s_add_i32 m0, s67, 0xc000
	ds_read_b128 v[148:151], v240
	ds_read_b128 v[152:155], v240 offset:1024
	ds_read_b128 v[156:159], v240 offset:2048
	ds_read_b128 v[160:163], v240 offset:3072
	ds_read_b128 v[164:167], v240 offset:4096
	ds_read_b128 v[168:171], v240 offset:5120
	ds_read_b128 v[172:175], v240 offset:6144
	ds_read_b128 v[204:207], v240 offset:7168
	global_load_lds_dwordx4 v[208:209], off
	v_lshl_add_u64 v[208:209], s[0:1], 0, v[202:203]
	s_add_i32 m0, s67, 0xe000
	s_nop 0
	global_load_lds_dwordx4 v[208:209], off
	s_waitcnt lgkmcnt(8)
	s_waitcnt vmcnt(10)
	s_barrier
	s_waitcnt lgkmcnt(0)
	s_setprio 1
	s_waitcnt lgkmcnt(0)
	v_mfma_f32_16x16x32_bf16 v[128:131], v[132:135], v[148:151], v[128:131]
	v_mfma_f32_16x16x32_bf16 v[124:127], v[140:143], v[148:151], v[124:127]
	v_mfma_f32_16x16x32_bf16 v[120:123], v[132:135], v[156:159], v[120:123]
	v_mfma_f32_16x16x32_bf16 v[116:119], v[140:143], v[156:159], v[116:119]
	v_mfma_f32_16x16x32_bf16 v[112:115], v[132:135], v[164:167], v[112:115]
	v_mfma_f32_16x16x32_bf16 v[108:111], v[140:143], v[164:167], v[108:111]
	v_mfma_f32_16x16x32_bf16 v[104:107], v[132:135], v[172:175], v[104:107]
	v_mfma_f32_16x16x32_bf16 v[100:103], v[140:143], v[172:175], v[100:103]
	v_mfma_f32_16x16x32_bf16 v[128:131], v[136:139], v[152:155], v[128:131]
	v_mfma_f32_16x16x32_bf16 v[124:127], v[144:147], v[152:155], v[124:127]
	v_mfma_f32_16x16x32_bf16 v[120:123], v[136:139], v[160:163], v[120:123]
	v_mfma_f32_16x16x32_bf16 v[116:119], v[144:147], v[160:163], v[116:119]
	v_mfma_f32_16x16x32_bf16 v[112:115], v[136:139], v[168:171], v[112:115]
	v_mfma_f32_16x16x32_bf16 v[108:111], v[144:147], v[168:171], v[108:111]
	v_mfma_f32_16x16x32_bf16 v[104:107], v[136:139], v[204:207], v[104:107]
	v_mfma_f32_16x16x32_bf16 v[100:103], v[144:147], v[204:207], v[100:103]
	s_setprio 0
	s_barrier
	s_add_i32 s23, 0, 0x14000
	s_add_i32 s24, s25, s61
	v_add_u32_e32 v2, s23, v187
	v_lshl_add_u64 v[222:223], s[44:45], 0, v[176:177]
	s_mov_b32 m0, s24
	ds_read_b128 v[208:211], v2
	ds_read_b128 v[212:215], v2 offset:1024
	ds_read_b128 v[242:245], v2 offset:2048
	ds_read_b128 v[246:249], v2 offset:3072
	global_load_lds_dwordx4 v[222:223], off
	v_lshl_add_u64 v[250:251], s[44:45], 0, v[180:181]
	s_add_i32 m0, s24, 0x2000
	s_nop 0
	global_load_lds_dwordx4 v[250:251], off
	s_waitcnt vmcnt(10)
	s_barrier
	s_waitcnt lgkmcnt(0)
	s_setprio 1
	s_waitcnt lgkmcnt(0)
	v_mfma_f32_16x16x32_bf16 v[64:67], v[208:211], v[148:151], v[64:67]
	v_mfma_f32_16x16x32_bf16 v[60:63], v[242:245], v[148:151], v[60:63]
	v_mfma_f32_16x16x32_bf16 v[56:59], v[208:211], v[156:159], v[56:59]
	v_mfma_f32_16x16x32_bf16 v[52:55], v[242:245], v[156:159], v[52:55]
	v_mfma_f32_16x16x32_bf16 v[48:51], v[208:211], v[164:167], v[48:51]
	v_mfma_f32_16x16x32_bf16 v[44:47], v[242:245], v[164:167], v[44:47]
	v_mfma_f32_16x16x32_bf16 v[40:43], v[208:211], v[172:175], v[40:43]
	v_mfma_f32_16x16x32_bf16 v[36:39], v[242:245], v[172:175], v[36:39]
	v_mfma_f32_16x16x32_bf16 v[64:67], v[212:215], v[152:155], v[64:67]
	v_mfma_f32_16x16x32_bf16 v[60:63], v[246:249], v[152:155], v[60:63]
	v_mfma_f32_16x16x32_bf16 v[56:59], v[212:215], v[160:163], v[56:59]
	v_mfma_f32_16x16x32_bf16 v[52:55], v[246:249], v[160:163], v[52:55]
	v_mfma_f32_16x16x32_bf16 v[48:51], v[212:215], v[168:171], v[48:51]
	v_mfma_f32_16x16x32_bf16 v[44:47], v[246:249], v[168:171], v[44:47]
	v_mfma_f32_16x16x32_bf16 v[40:43], v[212:215], v[204:207], v[40:43]
	v_mfma_f32_16x16x32_bf16 v[36:39], v[246:249], v[204:207], v[36:39]
	s_setprio 0
	s_mov_b32 m0, s67
	v_lshl_add_u64 v[216:217], s[46:47], 0, v[0:1]
	s_barrier
	ds_read_b128 v[148:151], v240 offset:16384
	ds_read_b128 v[152:155], v240 offset:17408
	ds_read_b128 v[156:159], v240 offset:18432
	ds_read_b128 v[160:163], v240 offset:19456
	ds_read_b128 v[164:167], v240 offset:20480
	ds_read_b128 v[168:171], v240 offset:21504
	ds_read_b128 v[172:175], v240 offset:22528
	ds_read_b128 v[204:207], v240 offset:23552
	global_load_lds_dwordx4 v[216:217], off
	v_lshl_add_u64 v[236:237], s[46:47], 0, v[178:179]
	s_mov_b32 m0, s74
	s_nop 0
	global_load_lds_dwordx4 v[236:237], off
	s_barrier
	s_waitcnt lgkmcnt(0)
	s_setprio 1
	s_waitcnt lgkmcnt(0)
	v_mfma_f32_16x16x32_bf16 v[96:99], v[132:135], v[148:151], v[96:99]
	v_mfma_f32_16x16x32_bf16 v[92:95], v[140:143], v[148:151], v[92:95]
	v_mfma_f32_16x16x32_bf16 v[88:91], v[132:135], v[156:159], v[88:91]
	v_mfma_f32_16x16x32_bf16 v[84:87], v[140:143], v[156:159], v[84:87]
	v_mfma_f32_16x16x32_bf16 v[80:83], v[132:135], v[164:167], v[80:83]
	v_mfma_f32_16x16x32_bf16 v[76:79], v[140:143], v[164:167], v[76:79]
	v_mfma_f32_16x16x32_bf16 v[72:75], v[132:135], v[172:175], v[72:75]
	v_mfma_f32_16x16x32_bf16 v[68:71], v[140:143], v[172:175], v[68:71]
	v_mfma_f32_16x16x32_bf16 v[96:99], v[136:139], v[152:155], v[96:99]
	v_mfma_f32_16x16x32_bf16 v[92:95], v[144:147], v[152:155], v[92:95]
	v_mfma_f32_16x16x32_bf16 v[88:91], v[136:139], v[160:163], v[88:91]
	v_mfma_f32_16x16x32_bf16 v[84:87], v[144:147], v[160:163], v[84:87]
	v_mfma_f32_16x16x32_bf16 v[80:83], v[136:139], v[168:171], v[80:83]
	v_mfma_f32_16x16x32_bf16 v[76:79], v[144:147], v[168:171], v[76:79]
	v_mfma_f32_16x16x32_bf16 v[72:75], v[136:139], v[204:207], v[72:75]
	v_mfma_f32_16x16x32_bf16 v[68:71], v[144:147], v[204:207], v[68:71]
	s_setprio 0
	s_barrier
	s_add_u32 s24, s44, 0x40000
	s_addc_u32 s25, s45, 0
	s_add_i32 s23, s23, s61
	v_lshl_add_u64 v[132:133], s[24:25], 0, v[176:177]
	s_mov_b32 m0, s23
	s_nop 0
	global_load_lds_dwordx4 v[132:133], off
	v_lshl_add_u64 v[132:133], s[24:25], 0, v[180:181]
	s_add_i32 m0, s23, 0x2000
	s_nop 0
	global_load_lds_dwordx4 v[132:133], off
	s_waitcnt vmcnt(10)
	s_barrier
	s_setprio 1
	v_mfma_f32_16x16x32_bf16 v[32:35], v[208:211], v[148:151], v[32:35]
	v_mfma_f32_16x16x32_bf16 v[28:31], v[242:245], v[148:151], v[28:31]
	v_mfma_f32_16x16x32_bf16 v[24:27], v[208:211], v[156:159], v[24:27]
	v_mfma_f32_16x16x32_bf16 v[20:23], v[242:245], v[156:159], v[20:23]
	v_mfma_f32_16x16x32_bf16 v[16:19], v[208:211], v[164:167], v[16:19]
	v_mfma_f32_16x16x32_bf16 v[12:15], v[242:245], v[164:167], v[12:15]
	v_mfma_f32_16x16x32_bf16 v[8:11], v[208:211], v[172:175], v[8:11]
	v_mfma_f32_16x16x32_bf16 v[4:7], v[242:245], v[172:175], v[4:7]
	v_mfma_f32_16x16x32_bf16 v[32:35], v[212:215], v[152:155], v[32:35]
	v_mfma_f32_16x16x32_bf16 v[28:31], v[246:249], v[152:155], v[28:31]
	v_mfma_f32_16x16x32_bf16 v[24:27], v[212:215], v[160:163], v[24:27]
	v_mfma_f32_16x16x32_bf16 v[20:23], v[246:249], v[160:163], v[20:23]
	v_mfma_f32_16x16x32_bf16 v[16:19], v[212:215], v[168:171], v[16:19]
	v_mfma_f32_16x16x32_bf16 v[12:15], v[246:249], v[168:171], v[12:15]
	v_mfma_f32_16x16x32_bf16 v[8:11], v[212:215], v[204:207], v[8:11]
	v_mfma_f32_16x16x32_bf16 v[4:7], v[246:249], v[204:207], v[4:7]
	s_setprio 0
	s_add_i32 s23, 0, 0x18000
	v_add_u32_e32 v2, s23, v187
	s_barrier
	ds_read_b128 v[132:135], v2
	ds_read_b128 v[136:139], v2 offset:1024
	ds_read_b128 v[140:143], v2 offset:2048
	ds_read_b128 v[144:147], v2 offset:3072
	s_add_u32 s24, s46, 0x40000
	s_addc_u32 s25, s47, 0
	s_mov_b32 m0, s75
	v_lshl_add_u64 v[208:209], s[24:25], 0, v[0:1]
	ds_read_b128 v[148:151], v240 offset:32768
	ds_read_b128 v[152:155], v240 offset:33792
	ds_read_b128 v[156:159], v240 offset:34816
	ds_read_b128 v[160:163], v240 offset:35840
	ds_read_b128 v[164:167], v240 offset:36864
	ds_read_b128 v[168:171], v240 offset:37888
	ds_read_b128 v[172:175], v240 offset:38912
	ds_read_b128 v[204:207], v240 offset:39936
	global_load_lds_dwordx4 v[208:209], off
	v_lshl_add_u64 v[208:209], s[24:25], 0, v[178:179]
	s_mov_b32 m0, s82
	s_nop 0
	global_load_lds_dwordx4 v[208:209], off
	s_waitcnt lgkmcnt(8)
	s_waitcnt vmcnt(10)
	s_barrier
	s_waitcnt lgkmcnt(0)
	s_setprio 1
	s_waitcnt lgkmcnt(0)
	v_mfma_f32_16x16x32_bf16 v[128:131], v[132:135], v[148:151], v[128:131]
	v_mfma_f32_16x16x32_bf16 v[124:127], v[140:143], v[148:151], v[124:127]
	v_mfma_f32_16x16x32_bf16 v[120:123], v[132:135], v[156:159], v[120:123]
	v_mfma_f32_16x16x32_bf16 v[116:119], v[140:143], v[156:159], v[116:119]
	v_mfma_f32_16x16x32_bf16 v[112:115], v[132:135], v[164:167], v[112:115]
	v_mfma_f32_16x16x32_bf16 v[108:111], v[140:143], v[164:167], v[108:111]
	v_mfma_f32_16x16x32_bf16 v[104:107], v[132:135], v[172:175], v[104:107]
	v_mfma_f32_16x16x32_bf16 v[100:103], v[140:143], v[172:175], v[100:103]
	v_mfma_f32_16x16x32_bf16 v[128:131], v[136:139], v[152:155], v[128:131]
	v_mfma_f32_16x16x32_bf16 v[124:127], v[144:147], v[152:155], v[124:127]
	v_mfma_f32_16x16x32_bf16 v[120:123], v[136:139], v[160:163], v[120:123]
	v_mfma_f32_16x16x32_bf16 v[116:119], v[144:147], v[160:163], v[116:119]
	v_mfma_f32_16x16x32_bf16 v[112:115], v[136:139], v[168:171], v[112:115]
	v_mfma_f32_16x16x32_bf16 v[108:111], v[144:147], v[168:171], v[108:111]
	v_mfma_f32_16x16x32_bf16 v[104:107], v[136:139], v[204:207], v[104:107]
	v_mfma_f32_16x16x32_bf16 v[100:103], v[144:147], v[204:207], v[100:103]
	s_setprio 0
	s_barrier
	s_add_i32 s26, 0, 0x1c000
	s_add_i32 s23, s23, s61
	v_add_u32_e32 v2, s26, v187
	v_lshl_add_u64 v[222:223], v[222:223], 0, s[76:77]
	s_mov_b32 m0, s23
	ds_read_b128 v[208:211], v2
	ds_read_b128 v[212:215], v2 offset:1024
	ds_read_b128 v[242:245], v2 offset:2048
	ds_read_b128 v[246:249], v2 offset:3072
	global_load_lds_dwordx4 v[222:223], off
	v_lshl_add_u64 v[222:223], v[250:251], 0, s[76:77]
	s_add_i32 m0, s23, 0x2000
	s_nop 0
	global_load_lds_dwordx4 v[222:223], off
	s_waitcnt vmcnt(10)
	s_barrier
	s_waitcnt lgkmcnt(0)
	s_setprio 1
	s_waitcnt lgkmcnt(0)
	v_mfma_f32_16x16x32_bf16 v[64:67], v[208:211], v[148:151], v[64:67]
	v_mfma_f32_16x16x32_bf16 v[60:63], v[242:245], v[148:151], v[60:63]
	v_mfma_f32_16x16x32_bf16 v[56:59], v[208:211], v[156:159], v[56:59]
	v_mfma_f32_16x16x32_bf16 v[52:55], v[242:245], v[156:159], v[52:55]
	v_mfma_f32_16x16x32_bf16 v[48:51], v[208:211], v[164:167], v[48:51]
	v_mfma_f32_16x16x32_bf16 v[44:47], v[242:245], v[164:167], v[44:47]
	v_mfma_f32_16x16x32_bf16 v[40:43], v[208:211], v[172:175], v[40:43]
	v_mfma_f32_16x16x32_bf16 v[36:39], v[242:245], v[172:175], v[36:39]
	v_mfma_f32_16x16x32_bf16 v[64:67], v[212:215], v[152:155], v[64:67]
	v_mfma_f32_16x16x32_bf16 v[60:63], v[246:249], v[152:155], v[60:63]
	v_mfma_f32_16x16x32_bf16 v[56:59], v[212:215], v[160:163], v[56:59]
	v_mfma_f32_16x16x32_bf16 v[52:55], v[246:249], v[160:163], v[52:55]
	v_mfma_f32_16x16x32_bf16 v[48:51], v[212:215], v[168:171], v[48:51]
	v_mfma_f32_16x16x32_bf16 v[44:47], v[246:249], v[168:171], v[44:47]
	v_mfma_f32_16x16x32_bf16 v[40:43], v[212:215], v[204:207], v[40:43]
	v_mfma_f32_16x16x32_bf16 v[36:39], v[246:249], v[204:207], v[36:39]
	s_setprio 0
	s_mov_b32 m0, s48
	v_lshl_add_u64 v[216:217], v[216:217], 0, s[76:77]
	s_barrier
	ds_read_b128 v[148:151], v240 offset:49152
	ds_read_b128 v[152:155], v240 offset:50176
	ds_read_b128 v[156:159], v240 offset:51200
	ds_read_b128 v[160:163], v240 offset:52224
	ds_read_b128 v[164:167], v240 offset:53248
	ds_read_b128 v[168:171], v240 offset:54272
	ds_read_b128 v[172:175], v240 offset:55296
	ds_read_b128 v[204:207], v240 offset:56320
	global_load_lds_dwordx4 v[216:217], off
	v_lshl_add_u64 v[216:217], v[236:237], 0, s[76:77]
	s_mov_b32 m0, s50
	s_nop 0
	global_load_lds_dwordx4 v[216:217], off
	s_barrier
	s_waitcnt lgkmcnt(0)
	s_setprio 1
	s_waitcnt lgkmcnt(0)
	v_mfma_f32_16x16x32_bf16 v[96:99], v[132:135], v[148:151], v[96:99]
	v_mfma_f32_16x16x32_bf16 v[92:95], v[140:143], v[148:151], v[92:95]
	v_mfma_f32_16x16x32_bf16 v[88:91], v[132:135], v[156:159], v[88:91]
	v_mfma_f32_16x16x32_bf16 v[84:87], v[140:143], v[156:159], v[84:87]
	v_mfma_f32_16x16x32_bf16 v[80:83], v[132:135], v[164:167], v[80:83]
	v_mfma_f32_16x16x32_bf16 v[76:79], v[140:143], v[164:167], v[76:79]
	v_mfma_f32_16x16x32_bf16 v[72:75], v[132:135], v[172:175], v[72:75]
	v_mfma_f32_16x16x32_bf16 v[68:71], v[140:143], v[172:175], v[68:71]
	v_mfma_f32_16x16x32_bf16 v[96:99], v[136:139], v[152:155], v[96:99]
	v_mfma_f32_16x16x32_bf16 v[92:95], v[144:147], v[152:155], v[92:95]
	v_mfma_f32_16x16x32_bf16 v[88:91], v[136:139], v[160:163], v[88:91]
	v_mfma_f32_16x16x32_bf16 v[84:87], v[144:147], v[160:163], v[84:87]
	v_mfma_f32_16x16x32_bf16 v[80:83], v[136:139], v[168:171], v[80:83]
	v_mfma_f32_16x16x32_bf16 v[76:79], v[144:147], v[168:171], v[76:79]
	v_mfma_f32_16x16x32_bf16 v[72:75], v[136:139], v[204:207], v[72:75]
	v_mfma_f32_16x16x32_bf16 v[68:71], v[144:147], v[204:207], v[68:71]
	s_setprio 0
	s_barrier
	s_add_u32 s24, s44, 0x40080
	s_addc_u32 s25, s45, 0
	s_add_i32 s23, s26, s61
	v_lshl_add_u64 v[132:133], s[24:25], 0, v[176:177]
	s_mov_b32 m0, s23
	s_nop 0
	global_load_lds_dwordx4 v[132:133], off
	v_lshl_add_u64 v[132:133], s[24:25], 0, v[180:181]
	s_add_i32 m0, s23, 0x2000
	s_nop 0
	global_load_lds_dwordx4 v[132:133], off
	s_waitcnt vmcnt(10)
	s_barrier
	s_setprio 1
	v_mfma_f32_16x16x32_bf16 v[32:35], v[208:211], v[148:151], v[32:35]
	v_mfma_f32_16x16x32_bf16 v[28:31], v[242:245], v[148:151], v[28:31]
	v_mfma_f32_16x16x32_bf16 v[24:27], v[208:211], v[156:159], v[24:27]
	v_mfma_f32_16x16x32_bf16 v[20:23], v[242:245], v[156:159], v[20:23]
	v_mfma_f32_16x16x32_bf16 v[16:19], v[208:211], v[164:167], v[16:19]
	v_mfma_f32_16x16x32_bf16 v[12:15], v[242:245], v[164:167], v[12:15]
	v_mfma_f32_16x16x32_bf16 v[8:11], v[208:211], v[172:175], v[8:11]
	v_mfma_f32_16x16x32_bf16 v[4:7], v[242:245], v[172:175], v[4:7]
	v_mfma_f32_16x16x32_bf16 v[32:35], v[212:215], v[152:155], v[32:35]
	v_mfma_f32_16x16x32_bf16 v[28:31], v[246:249], v[152:155], v[28:31]
	v_mfma_f32_16x16x32_bf16 v[24:27], v[212:215], v[160:163], v[24:27]
	v_mfma_f32_16x16x32_bf16 v[20:23], v[246:249], v[160:163], v[20:23]
	v_mfma_f32_16x16x32_bf16 v[16:19], v[212:215], v[168:171], v[16:19]
	v_mfma_f32_16x16x32_bf16 v[12:15], v[246:249], v[168:171], v[12:15]
	v_mfma_f32_16x16x32_bf16 v[8:11], v[212:215], v[204:207], v[8:11]
	v_mfma_f32_16x16x32_bf16 v[4:7], v[246:249], v[204:207], v[4:7]
	s_setprio 0
	s_add_i32 s22, s22, 2
	s_add_u32 s0, s0, 0x100
	s_addc_u32 s1, s1, 0
	s_add_u32 s20, s20, 0x100
	s_addc_u32 s21, s21, 0
	s_cmp_gt_u32 s22, 13
	s_barrier
	s_cbranch_scc0 .LBB0_242
	s_add_i32 s0, s66, -8
	s_cmp_lt_u32 s0, 12
	s_mov_b64 s[0:1], -1
	s_cbranch_scc1 .LBB0_266
	s_cmp_gt_i32 s66, 33
	s_cselect_b64 s[64:65], -1, 0
	s_lshl_b32 s0, s66, 8
	s_lshl_b32 s53, s60, 8
	s_add_i32 s1, s0, 0xffffee00
	s_cmp_lt_i32 s66, 26
	v_cndmask_b32_e64 v2, 0, 1, s[80:81]
	s_cselect_b32 s62, s0, s1
	s_mov_b64 s[0:1], -1
	s_and_b64 vcc, exec, s[64:65]
	v_cmp_ne_u32_e64 s[44:45], 1, v2
	s_cbranch_vccz .LBB0_248
	s_and_b64 vcc, exec, s[44:45]
	s_cbranch_vccnz .LBB0_247
	v_add_u32_e32 v132, s53, v185
	v_ashrrev_i32_e32 v133, 31, v132
	v_lshlrev_b64 v[140:141], 7, v[132:133]
	global_load_dwordx4 v[132:135], v[188:189], off offset:16
	global_load_dwordx4 v[136:139], v[188:189], off
	s_mov_b32 s3, 0xbfb8aa3b
	s_mov_b32 s2, 0x800000
	s_mov_b32 s5, 0x3f317217
	s_mov_b32 s6, 0x7f800000
	s_waitcnt vmcnt(0)
	v_add_f32_e32 v147, v126, v134
	v_add_f32_e32 v2, v128, v136
	v_max_f32_e32 v142, 0, v2
	v_mul_f32_e64 v2, |v2|, s3
	v_exp_f32_e32 v2, v2
	v_add_f32_e32 v136, v124, v132
	v_add_f32_e32 v149, v127, v135
	v_add_f32_e32 v2, 1.0, v2
	v_cmp_gt_f32_e32 vcc, s2, v2
	s_nop 1
	v_cndmask_b32_e64 v132, 0, 32, vcc
	v_ldexp_f32 v2, v2, v132
	v_log_f32_e32 v2, v2
	s_nop 0
	v_mul_f32_e32 v132, 0x3f317217, v2
	v_fma_f32 v132, v2, s5, -v132
	v_fmac_f32_e32 v132, 0x3377d1cf, v2
	v_fmac_f32_e32 v132, 0x3f317217, v2
	v_cmp_lt_f32_e64 s[0:1], |v2|, s6
	s_nop 1
	v_cndmask_b32_e64 v2, v2, v132, s[0:1]
	v_cndmask_b32_e32 v132, 0, v228, vcc
	v_sub_f32_e32 v144, v2, v132
	v_mul_f32_e64 v2, |v136|, s3
	v_exp_f32_e32 v2, v2
	v_max_f32_e32 v132, 0, v136
	v_add_f32_e32 v2, 1.0, v2
	v_cmp_gt_f32_e32 vcc, s2, v2
	s_nop 1
	v_cndmask_b32_e64 v136, 0, 32, vcc
	v_ldexp_f32 v2, v2, v136
	v_log_f32_e32 v2, v2
	s_nop 0
	v_mul_f32_e32 v136, 0x3f317217, v2
	v_fma_f32 v136, v2, s5, -v136
	v_fmac_f32_e32 v136, 0x3377d1cf, v2
	v_fmac_f32_e32 v136, 0x3f317217, v2
	v_cmp_lt_f32_e64 s[0:1], |v2|, s6
	s_nop 1
	v_cndmask_b32_e64 v2, v2, v136, s[0:1]
	v_cndmask_b32_e32 v136, 0, v228, vcc
	v_sub_f32_e32 v136, v2, v136
	v_add_f32_e32 v2, v129, v137
	v_max_f32_e32 v143, 0, v2
	v_mul_f32_e64 v2, |v2|, s3
	v_exp_f32_e32 v2, v2
	v_add_f32_e32 v137, v125, v133
	v_add_f32_e32 v2, 1.0, v2
	v_cmp_gt_f32_e32 vcc, s2, v2
	s_nop 1
	v_cndmask_b32_e64 v133, 0, 32, vcc
	v_ldexp_f32 v2, v2, v133
	v_log_f32_e32 v2, v2
	s_nop 0
	v_mul_f32_e32 v133, 0x3f317217, v2
	v_fma_f32 v133, v2, s5, -v133
	v_fmac_f32_e32 v133, 0x3377d1cf, v2
	v_fmac_f32_e32 v133, 0x3f317217, v2
	v_cmp_lt_f32_e64 s[0:1], |v2|, s6
	s_nop 1
	v_cndmask_b32_e64 v2, v2, v133, s[0:1]
	v_cndmask_b32_e32 v133, 0, v228, vcc
	v_sub_f32_e32 v145, v2, v133
	v_mul_f32_e64 v2, |v137|, s3
	v_exp_f32_e32 v2, v2
	v_max_f32_e32 v133, 0, v137
	v_pk_add_f32 v[142:143], v[142:143], v[144:145]
	v_add_f32_e32 v2, 1.0, v2
	v_cmp_gt_f32_e32 vcc, s2, v2
	s_nop 1
	v_cndmask_b32_e64 v137, 0, 32, vcc
	v_ldexp_f32 v2, v2, v137
	v_log_f32_e32 v2, v2
	s_nop 0
	v_mul_f32_e32 v137, 0x3f317217, v2
	v_fma_f32 v137, v2, s5, -v137
	v_fmac_f32_e32 v137, 0x3377d1cf, v2
	v_fmac_f32_e32 v137, 0x3f317217, v2
	v_cmp_lt_f32_e64 s[0:1], |v2|, s6
	s_nop 1
	v_cndmask_b32_e64 v2, v2, v137, s[0:1]
	v_cndmask_b32_e32 v137, 0, v228, vcc
	v_sub_f32_e32 v137, v2, v137
	v_add_f32_e32 v2, v130, v138
	v_max_f32_e32 v138, 0, v2
	v_mul_f32_e64 v2, |v2|, s3
	v_exp_f32_e32 v2, v2
	v_pk_add_f32 v[132:133], v[132:133], v[136:137]
	v_lshl_add_u64 v[136:137], v[190:191], 0, v[140:141]
	v_add_f32_e32 v2, 1.0, v2
	v_cmp_gt_f32_e32 vcc, s2, v2
	s_nop 1
	v_cndmask_b32_e64 v134, 0, 32, vcc
	v_ldexp_f32 v2, v2, v134
	v_log_f32_e32 v2, v2
	s_nop 0
	v_mul_f32_e32 v134, 0x3f317217, v2
	v_fma_f32 v134, v2, s5, -v134
	v_fmac_f32_e32 v134, 0x3377d1cf, v2
	v_fmac_f32_e32 v134, 0x3f317217, v2
	v_cmp_lt_f32_e64 s[0:1], |v2|, s6
	s_nop 1
	v_cndmask_b32_e64 v2, v2, v134, s[0:1]
	v_cndmask_b32_e32 v134, 0, v228, vcc
	v_sub_f32_e32 v146, v2, v134
	v_mul_f32_e64 v2, |v147|, s3
	v_exp_f32_e32 v2, v2
	v_max_f32_e32 v134, 0, v147
	v_add_f32_e32 v2, 1.0, v2
	v_cmp_gt_f32_e32 vcc, s2, v2
	s_nop 1
	v_cndmask_b32_e64 v147, 0, 32, vcc
	v_ldexp_f32 v2, v2, v147
	v_log_f32_e32 v2, v2
	s_nop 0
	v_mul_f32_e32 v147, 0x3f317217, v2
	v_fma_f32 v147, v2, s5, -v147
	v_fmac_f32_e32 v147, 0x3377d1cf, v2
	v_fmac_f32_e32 v147, 0x3f317217, v2
	v_cmp_lt_f32_e64 s[0:1], |v2|, s6
	s_nop 1
	v_cndmask_b32_e64 v2, v2, v147, s[0:1]
	v_cndmask_b32_e32 v147, 0, v228, vcc
	v_sub_f32_e32 v148, v2, v147
	v_add_f32_e32 v2, v131, v139
	v_max_f32_e32 v139, 0, v2
	v_mul_f32_e64 v2, |v2|, s3
	v_exp_f32_e32 v2, v2
	s_nop 0
	v_add_f32_e32 v2, 1.0, v2
	v_cmp_gt_f32_e32 vcc, s2, v2
	s_nop 1
	v_cndmask_b32_e64 v135, 0, 32, vcc
	v_ldexp_f32 v2, v2, v135
	v_log_f32_e32 v2, v2
	s_nop 0
	v_mul_f32_e32 v135, 0x3f317217, v2
	v_fma_f32 v135, v2, s5, -v135
	v_fmac_f32_e32 v135, 0x3377d1cf, v2
	v_fmac_f32_e32 v135, 0x3f317217, v2
	v_cmp_lt_f32_e64 s[0:1], |v2|, s6
	s_nop 1
	v_cndmask_b32_e64 v2, v2, v135, s[0:1]
	v_cndmask_b32_e32 v135, 0, v228, vcc
	v_sub_f32_e32 v147, v2, v135
	v_mul_f32_e64 v2, |v149|, s3
	v_exp_f32_e32 v2, v2
	v_pk_add_f32 v[144:145], v[138:139], v[146:147]
	v_max_f32_e32 v135, 0, v149
	v_add_f32_e32 v2, 1.0, v2
	v_cmp_gt_f32_e32 vcc, s2, v2
	s_nop 1
	v_cndmask_b32_e64 v138, 0, 32, vcc
	v_ldexp_f32 v2, v2, v138
	v_log_f32_e32 v2, v2
	s_nop 0
	v_mul_f32_e32 v138, 0x3f317217, v2
	v_fma_f32 v138, v2, s5, -v138
	v_fmac_f32_e32 v138, 0x3377d1cf, v2
	v_fmac_f32_e32 v138, 0x3f317217, v2
	v_cmp_lt_f32_e64 s[0:1], |v2|, s6
	s_nop 1
	v_cndmask_b32_e64 v2, v2, v138, s[0:1]
	v_cndmask_b32_e32 v138, 0, v228, vcc
	v_sub_f32_e32 v149, v2, v138
	v_pk_add_f32 v[134:135], v[134:135], v[148:149]
	global_store_dwordx4 v[136:137], v[142:145], off
	global_store_dwordx4 v[136:137], v[132:135], off offset:16

.LBB0_427:
	s_add_u32 s23, s0, 0xfffc0080
	s_addc_u32 s24, s1, -1
	s_add_i32 s25, 0, 0x10000
	v_add_u32_e32 v2, s25, v187
	ds_read_b128 v[132:135], v2
	ds_read_b128 v[136:139], v2 offset:1024
	ds_read_b128 v[140:143], v2 offset:2048
	ds_read_b128 v[144:147], v2 offset:3072
	s_cmp_eq_u32 s22, 12
	s_cselect_b32 s47, s57, s24
	s_cselect_b32 s46, s56, s23
	s_cselect_b32 s45, s59, s21
	s_cselect_b32 s44, s58, s20
	v_lshl_add_u64 v[208:209], s[0:1], 0, v[194:195]
	s_add_i32 m0, s74, 0xc000
	ds_read_b128 v[148:151], v240
	ds_read_b128 v[152:155], v240 offset:1024
	ds_read_b128 v[156:159], v240 offset:2048
	ds_read_b128 v[160:163], v240 offset:3072
	ds_read_b128 v[164:167], v240 offset:4096
	ds_read_b128 v[168:171], v240 offset:5120
	ds_read_b128 v[172:175], v240 offset:6144
	ds_read_b128 v[204:207], v240 offset:7168
	global_load_lds_dwordx4 v[208:209], off
	v_lshl_add_u64 v[208:209], s[0:1], 0, v[202:203]
	s_add_i32 m0, s74, 0xe000
	s_nop 0
	global_load_lds_dwordx4 v[208:209], off
	s_waitcnt lgkmcnt(8)
	s_waitcnt vmcnt(10)
	s_barrier
	s_waitcnt lgkmcnt(0)
	s_setprio 1
	s_waitcnt lgkmcnt(0)
	v_mfma_f32_16x16x32_bf16 v[128:131], v[132:135], v[148:151], v[128:131]
	v_mfma_f32_16x16x32_bf16 v[124:127], v[140:143], v[148:151], v[124:127]
	v_mfma_f32_16x16x32_bf16 v[120:123], v[132:135], v[156:159], v[120:123]
	v_mfma_f32_16x16x32_bf16 v[116:119], v[140:143], v[156:159], v[116:119]
	v_mfma_f32_16x16x32_bf16 v[112:115], v[132:135], v[164:167], v[112:115]
	v_mfma_f32_16x16x32_bf16 v[108:111], v[140:143], v[164:167], v[108:111]
	v_mfma_f32_16x16x32_bf16 v[104:107], v[132:135], v[172:175], v[104:107]
	v_mfma_f32_16x16x32_bf16 v[100:103], v[140:143], v[172:175], v[100:103]
	v_mfma_f32_16x16x32_bf16 v[128:131], v[136:139], v[152:155], v[128:131]
	v_mfma_f32_16x16x32_bf16 v[124:127], v[144:147], v[152:155], v[124:127]
	v_mfma_f32_16x16x32_bf16 v[120:123], v[136:139], v[160:163], v[120:123]
	v_mfma_f32_16x16x32_bf16 v[116:119], v[144:147], v[160:163], v[116:119]
	v_mfma_f32_16x16x32_bf16 v[112:115], v[136:139], v[168:171], v[112:115]
	v_mfma_f32_16x16x32_bf16 v[108:111], v[144:147], v[168:171], v[108:111]
	v_mfma_f32_16x16x32_bf16 v[104:107], v[136:139], v[204:207], v[104:107]
	v_mfma_f32_16x16x32_bf16 v[100:103], v[144:147], v[204:207], v[100:103]
	s_setprio 0
	s_barrier
	s_add_i32 s23, 0, 0x14000
	s_add_i32 s24, s25, s67
	v_add_u32_e32 v2, s23, v187
	v_lshl_add_u64 v[250:251], s[44:45], 0, v[176:177]
	s_mov_b32 m0, s24
	ds_read_b128 v[208:211], v2
	ds_read_b128 v[212:215], v2 offset:1024
	ds_read_b128 v[242:245], v2 offset:2048
	ds_read_b128 v[246:249], v2 offset:3072
	global_load_lds_dwordx4 v[250:251], off
	v_lshl_add_u64 v[222:223], s[44:45], 0, v[180:181]
	s_add_i32 m0, s24, 0x2000
	s_nop 0
	global_load_lds_dwordx4 v[222:223], off
	s_waitcnt vmcnt(10)
	s_barrier
	s_waitcnt lgkmcnt(0)
	s_setprio 1
	s_waitcnt lgkmcnt(0)
	v_mfma_f32_16x16x32_bf16 v[64:67], v[208:211], v[148:151], v[64:67]
	v_mfma_f32_16x16x32_bf16 v[60:63], v[242:245], v[148:151], v[60:63]
	v_mfma_f32_16x16x32_bf16 v[56:59], v[208:211], v[156:159], v[56:59]
	v_mfma_f32_16x16x32_bf16 v[52:55], v[242:245], v[156:159], v[52:55]
	v_mfma_f32_16x16x32_bf16 v[48:51], v[208:211], v[164:167], v[48:51]
	v_mfma_f32_16x16x32_bf16 v[44:47], v[242:245], v[164:167], v[44:47]
	v_mfma_f32_16x16x32_bf16 v[40:43], v[208:211], v[172:175], v[40:43]
	v_mfma_f32_16x16x32_bf16 v[36:39], v[242:245], v[172:175], v[36:39]
	v_mfma_f32_16x16x32_bf16 v[64:67], v[212:215], v[152:155], v[64:67]
	v_mfma_f32_16x16x32_bf16 v[60:63], v[246:249], v[152:155], v[60:63]
	v_mfma_f32_16x16x32_bf16 v[56:59], v[212:215], v[160:163], v[56:59]
	v_mfma_f32_16x16x32_bf16 v[52:55], v[246:249], v[160:163], v[52:55]
	v_mfma_f32_16x16x32_bf16 v[48:51], v[212:215], v[168:171], v[48:51]
	v_mfma_f32_16x16x32_bf16 v[44:47], v[246:249], v[168:171], v[44:47]
	v_mfma_f32_16x16x32_bf16 v[40:43], v[212:215], v[204:207], v[40:43]
	v_mfma_f32_16x16x32_bf16 v[36:39], v[246:249], v[204:207], v[36:39]
	s_setprio 0
	s_mov_b32 m0, s74
	v_lshl_add_u64 v[216:217], s[46:47], 0, v[0:1]
	s_barrier
	ds_read_b128 v[148:151], v240 offset:16384
	ds_read_b128 v[152:155], v240 offset:17408
	ds_read_b128 v[156:159], v240 offset:18432
	ds_read_b128 v[160:163], v240 offset:19456
	ds_read_b128 v[164:167], v240 offset:20480
	ds_read_b128 v[168:171], v240 offset:21504
	ds_read_b128 v[172:175], v240 offset:22528
	ds_read_b128 v[204:207], v240 offset:23552
	global_load_lds_dwordx4 v[216:217], off
	v_lshl_add_u64 v[236:237], s[46:47], 0, v[178:179]
	s_mov_b32 m0, s75
	s_nop 0
	global_load_lds_dwordx4 v[236:237], off
	s_barrier
	s_waitcnt lgkmcnt(0)
	s_setprio 1
	s_waitcnt lgkmcnt(0)
	v_mfma_f32_16x16x32_bf16 v[96:99], v[132:135], v[148:151], v[96:99]
	v_mfma_f32_16x16x32_bf16 v[92:95], v[140:143], v[148:151], v[92:95]
	v_mfma_f32_16x16x32_bf16 v[88:91], v[132:135], v[156:159], v[88:91]
	v_mfma_f32_16x16x32_bf16 v[84:87], v[140:143], v[156:159], v[84:87]
	v_mfma_f32_16x16x32_bf16 v[80:83], v[132:135], v[164:167], v[80:83]
	v_mfma_f32_16x16x32_bf16 v[76:79], v[140:143], v[164:167], v[76:79]
	v_mfma_f32_16x16x32_bf16 v[72:75], v[132:135], v[172:175], v[72:75]
	v_mfma_f32_16x16x32_bf16 v[68:71], v[140:143], v[172:175], v[68:71]
	v_mfma_f32_16x16x32_bf16 v[96:99], v[136:139], v[152:155], v[96:99]
	v_mfma_f32_16x16x32_bf16 v[92:95], v[144:147], v[152:155], v[92:95]
	v_mfma_f32_16x16x32_bf16 v[88:91], v[136:139], v[160:163], v[88:91]
	v_mfma_f32_16x16x32_bf16 v[84:87], v[144:147], v[160:163], v[84:87]
	v_mfma_f32_16x16x32_bf16 v[80:83], v[136:139], v[168:171], v[80:83]
	v_mfma_f32_16x16x32_bf16 v[76:79], v[144:147], v[168:171], v[76:79]
	v_mfma_f32_16x16x32_bf16 v[72:75], v[136:139], v[204:207], v[72:75]
	v_mfma_f32_16x16x32_bf16 v[68:71], v[144:147], v[204:207], v[68:71]
	s_setprio 0
	s_barrier
	s_add_u32 s24, s44, 0x40000
	s_addc_u32 s25, s45, 0
	s_add_i32 s23, s23, s67
	v_lshl_add_u64 v[132:133], s[24:25], 0, v[176:177]
	s_mov_b32 m0, s23
	s_nop 0
	global_load_lds_dwordx4 v[132:133], off
	v_lshl_add_u64 v[132:133], s[24:25], 0, v[180:181]
	s_add_i32 m0, s23, 0x2000
	s_nop 0
	global_load_lds_dwordx4 v[132:133], off
	s_waitcnt vmcnt(10)
	s_barrier
	s_setprio 1
	v_mfma_f32_16x16x32_bf16 v[32:35], v[208:211], v[148:151], v[32:35]
	v_mfma_f32_16x16x32_bf16 v[28:31], v[242:245], v[148:151], v[28:31]
	v_mfma_f32_16x16x32_bf16 v[24:27], v[208:211], v[156:159], v[24:27]
	v_mfma_f32_16x16x32_bf16 v[20:23], v[242:245], v[156:159], v[20:23]
	v_mfma_f32_16x16x32_bf16 v[16:19], v[208:211], v[164:167], v[16:19]
	v_mfma_f32_16x16x32_bf16 v[12:15], v[242:245], v[164:167], v[12:15]
	v_mfma_f32_16x16x32_bf16 v[8:11], v[208:211], v[172:175], v[8:11]
	v_mfma_f32_16x16x32_bf16 v[4:7], v[242:245], v[172:175], v[4:7]
	v_mfma_f32_16x16x32_bf16 v[32:35], v[212:215], v[152:155], v[32:35]
	v_mfma_f32_16x16x32_bf16 v[28:31], v[246:249], v[152:155], v[28:31]
	v_mfma_f32_16x16x32_bf16 v[24:27], v[212:215], v[160:163], v[24:27]
	v_mfma_f32_16x16x32_bf16 v[20:23], v[246:249], v[160:163], v[20:23]
	v_mfma_f32_16x16x32_bf16 v[16:19], v[212:215], v[168:171], v[16:19]
	v_mfma_f32_16x16x32_bf16 v[12:15], v[246:249], v[168:171], v[12:15]
	v_mfma_f32_16x16x32_bf16 v[8:11], v[212:215], v[204:207], v[8:11]
	v_mfma_f32_16x16x32_bf16 v[4:7], v[246:249], v[204:207], v[4:7]
	s_setprio 0
	s_add_i32 s23, 0, 0x18000
	v_add_u32_e32 v2, s23, v187
	s_barrier
	ds_read_b128 v[132:135], v2
	ds_read_b128 v[136:139], v2 offset:1024
	ds_read_b128 v[140:143], v2 offset:2048
	ds_read_b128 v[144:147], v2 offset:3072
	s_add_u32 s24, s46, 0x40000
	s_addc_u32 s25, s47, 0
	s_mov_b32 m0, s82
	v_lshl_add_u64 v[208:209], s[24:25], 0, v[0:1]
	ds_read_b128 v[148:151], v240 offset:32768
	ds_read_b128 v[152:155], v240 offset:33792
	ds_read_b128 v[156:159], v240 offset:34816
	ds_read_b128 v[160:163], v240 offset:35840
	ds_read_b128 v[164:167], v240 offset:36864
	ds_read_b128 v[168:171], v240 offset:37888
	ds_read_b128 v[172:175], v240 offset:38912
	ds_read_b128 v[204:207], v240 offset:39936
	global_load_lds_dwordx4 v[208:209], off
	v_lshl_add_u64 v[208:209], s[24:25], 0, v[178:179]
	s_mov_b32 m0, s83
	s_nop 0
	global_load_lds_dwordx4 v[208:209], off
	s_waitcnt lgkmcnt(8)
	s_waitcnt vmcnt(10)
	s_barrier
	s_waitcnt lgkmcnt(0)
	s_setprio 1
	s_waitcnt lgkmcnt(0)
	v_mfma_f32_16x16x32_bf16 v[128:131], v[132:135], v[148:151], v[128:131]
	v_mfma_f32_16x16x32_bf16 v[124:127], v[140:143], v[148:151], v[124:127]
	v_mfma_f32_16x16x32_bf16 v[120:123], v[132:135], v[156:159], v[120:123]
	v_mfma_f32_16x16x32_bf16 v[116:119], v[140:143], v[156:159], v[116:119]
	v_mfma_f32_16x16x32_bf16 v[112:115], v[132:135], v[164:167], v[112:115]
	v_mfma_f32_16x16x32_bf16 v[108:111], v[140:143], v[164:167], v[108:111]
	v_mfma_f32_16x16x32_bf16 v[104:107], v[132:135], v[172:175], v[104:107]
	v_mfma_f32_16x16x32_bf16 v[100:103], v[140:143], v[172:175], v[100:103]
	v_mfma_f32_16x16x32_bf16 v[128:131], v[136:139], v[152:155], v[128:131]
	v_mfma_f32_16x16x32_bf16 v[124:127], v[144:147], v[152:155], v[124:127]
	v_mfma_f32_16x16x32_bf16 v[120:123], v[136:139], v[160:163], v[120:123]
	v_mfma_f32_16x16x32_bf16 v[116:119], v[144:147], v[160:163], v[116:119]
	v_mfma_f32_16x16x32_bf16 v[112:115], v[136:139], v[168:171], v[112:115]
	v_mfma_f32_16x16x32_bf16 v[108:111], v[144:147], v[168:171], v[108:111]
	v_mfma_f32_16x16x32_bf16 v[104:107], v[136:139], v[204:207], v[104:107]
	v_mfma_f32_16x16x32_bf16 v[100:103], v[144:147], v[204:207], v[100:103]
	s_setprio 0
	s_barrier
	s_add_i32 s26, 0, 0x1c000
	s_add_i32 s23, s23, s67
	v_add_u32_e32 v2, s26, v187
	v_lshl_add_u64 v[250:251], v[250:251], 0, s[76:77]
	s_mov_b32 m0, s23
	ds_read_b128 v[208:211], v2
	ds_read_b128 v[212:215], v2 offset:1024
	ds_read_b128 v[242:245], v2 offset:2048
	ds_read_b128 v[246:249], v2 offset:3072
	global_load_lds_dwordx4 v[250:251], off
	v_lshl_add_u64 v[222:223], v[222:223], 0, s[76:77]
	s_add_i32 m0, s23, 0x2000
	s_nop 0
	global_load_lds_dwordx4 v[222:223], off
	s_waitcnt vmcnt(10)
	s_barrier
	s_waitcnt lgkmcnt(0)
	s_setprio 1
	s_waitcnt lgkmcnt(0)
	v_mfma_f32_16x16x32_bf16 v[64:67], v[208:211], v[148:151], v[64:67]
	v_mfma_f32_16x16x32_bf16 v[60:63], v[242:245], v[148:151], v[60:63]
	v_mfma_f32_16x16x32_bf16 v[56:59], v[208:211], v[156:159], v[56:59]
	v_mfma_f32_16x16x32_bf16 v[52:55], v[242:245], v[156:159], v[52:55]
	v_mfma_f32_16x16x32_bf16 v[48:51], v[208:211], v[164:167], v[48:51]
	v_mfma_f32_16x16x32_bf16 v[44:47], v[242:245], v[164:167], v[44:47]
	v_mfma_f32_16x16x32_bf16 v[40:43], v[208:211], v[172:175], v[40:43]
	v_mfma_f32_16x16x32_bf16 v[36:39], v[242:245], v[172:175], v[36:39]
	v_mfma_f32_16x16x32_bf16 v[64:67], v[212:215], v[152:155], v[64:67]
	v_mfma_f32_16x16x32_bf16 v[60:63], v[246:249], v[152:155], v[60:63]
	v_mfma_f32_16x16x32_bf16 v[56:59], v[212:215], v[160:163], v[56:59]
	v_mfma_f32_16x16x32_bf16 v[52:55], v[246:249], v[160:163], v[52:55]
	v_mfma_f32_16x16x32_bf16 v[48:51], v[212:215], v[168:171], v[48:51]
	v_mfma_f32_16x16x32_bf16 v[44:47], v[246:249], v[168:171], v[44:47]
	v_mfma_f32_16x16x32_bf16 v[40:43], v[212:215], v[204:207], v[40:43]
	v_mfma_f32_16x16x32_bf16 v[36:39], v[246:249], v[204:207], v[36:39]
	s_setprio 0
	s_mov_b32 m0, s48
	v_lshl_add_u64 v[216:217], v[216:217], 0, s[76:77]
	s_barrier
	ds_read_b128 v[148:151], v240 offset:49152
	ds_read_b128 v[152:155], v240 offset:50176
	ds_read_b128 v[156:159], v240 offset:51200
	ds_read_b128 v[160:163], v240 offset:52224
	ds_read_b128 v[164:167], v240 offset:53248
	ds_read_b128 v[168:171], v240 offset:54272
	ds_read_b128 v[172:175], v240 offset:55296
	ds_read_b128 v[204:207], v240 offset:56320
	global_load_lds_dwordx4 v[216:217], off
	v_lshl_add_u64 v[216:217], v[236:237], 0, s[76:77]
	s_mov_b32 m0, s50
	s_nop 0
	global_load_lds_dwordx4 v[216:217], off
	s_barrier
	s_waitcnt lgkmcnt(0)
	s_setprio 1
	s_waitcnt lgkmcnt(0)
	v_mfma_f32_16x16x32_bf16 v[96:99], v[132:135], v[148:151], v[96:99]
	v_mfma_f32_16x16x32_bf16 v[92:95], v[140:143], v[148:151], v[92:95]
	v_mfma_f32_16x16x32_bf16 v[88:91], v[132:135], v[156:159], v[88:91]
	v_mfma_f32_16x16x32_bf16 v[84:87], v[140:143], v[156:159], v[84:87]
	v_mfma_f32_16x16x32_bf16 v[80:83], v[132:135], v[164:167], v[80:83]
	v_mfma_f32_16x16x32_bf16 v[76:79], v[140:143], v[164:167], v[76:79]
	v_mfma_f32_16x16x32_bf16 v[72:75], v[132:135], v[172:175], v[72:75]
	v_mfma_f32_16x16x32_bf16 v[68:71], v[140:143], v[172:175], v[68:71]
	v_mfma_f32_16x16x32_bf16 v[96:99], v[136:139], v[152:155], v[96:99]
	v_mfma_f32_16x16x32_bf16 v[92:95], v[144:147], v[152:155], v[92:95]
	v_mfma_f32_16x16x32_bf16 v[88:91], v[136:139], v[160:163], v[88:91]
	v_mfma_f32_16x16x32_bf16 v[84:87], v[144:147], v[160:163], v[84:87]
	v_mfma_f32_16x16x32_bf16 v[80:83], v[136:139], v[168:171], v[80:83]
	v_mfma_f32_16x16x32_bf16 v[76:79], v[144:147], v[168:171], v[76:79]
	v_mfma_f32_16x16x32_bf16 v[72:75], v[136:139], v[204:207], v[72:75]
	v_mfma_f32_16x16x32_bf16 v[68:71], v[144:147], v[204:207], v[68:71]
	s_setprio 0
	s_barrier
	s_add_u32 s24, s44, 0x40080
	s_addc_u32 s25, s45, 0
	s_add_i32 s23, s26, s67
	v_lshl_add_u64 v[132:133], s[24:25], 0, v[176:177]
	s_mov_b32 m0, s23
	s_nop 0
	global_load_lds_dwordx4 v[132:133], off
	v_lshl_add_u64 v[132:133], s[24:25], 0, v[180:181]
	s_add_i32 m0, s23, 0x2000
	s_nop 0
	global_load_lds_dwordx4 v[132:133], off
	s_waitcnt vmcnt(10)
	s_barrier
	s_setprio 1
	v_mfma_f32_16x16x32_bf16 v[32:35], v[208:211], v[148:151], v[32:35]
	v_mfma_f32_16x16x32_bf16 v[28:31], v[242:245], v[148:151], v[28:31]
	v_mfma_f32_16x16x32_bf16 v[24:27], v[208:211], v[156:159], v[24:27]
	v_mfma_f32_16x16x32_bf16 v[20:23], v[242:245], v[156:159], v[20:23]
	v_mfma_f32_16x16x32_bf16 v[16:19], v[208:211], v[164:167], v[16:19]
	v_mfma_f32_16x16x32_bf16 v[12:15], v[242:245], v[164:167], v[12:15]
	v_mfma_f32_16x16x32_bf16 v[8:11], v[208:211], v[172:175], v[8:11]
	v_mfma_f32_16x16x32_bf16 v[4:7], v[242:245], v[172:175], v[4:7]
	v_mfma_f32_16x16x32_bf16 v[32:35], v[212:215], v[152:155], v[32:35]
	v_mfma_f32_16x16x32_bf16 v[28:31], v[246:249], v[152:155], v[28:31]
	v_mfma_f32_16x16x32_bf16 v[24:27], v[212:215], v[160:163], v[24:27]
	v_mfma_f32_16x16x32_bf16 v[20:23], v[246:249], v[160:163], v[20:23]
	v_mfma_f32_16x16x32_bf16 v[16:19], v[212:215], v[168:171], v[16:19]
	v_mfma_f32_16x16x32_bf16 v[12:15], v[246:249], v[168:171], v[12:15]
	v_mfma_f32_16x16x32_bf16 v[8:11], v[212:215], v[204:207], v[8:11]
	v_mfma_f32_16x16x32_bf16 v[4:7], v[246:249], v[204:207], v[4:7]
	s_setprio 0
	s_add_i32 s22, s22, 2
	s_add_u32 s0, s0, 0x100
	s_addc_u32 s1, s1, 0
	s_add_u32 s20, s20, 0x100
	s_addc_u32 s21, s21, 0
	s_cmp_gt_u32 s22, 13
	s_barrier
	s_cbranch_scc0 .LBB0_427
	s_add_i32 s0, s61, -8
	s_cmp_lt_u32 s0, 12
	s_mov_b64 s[0:1], -1
	s_cbranch_scc1 .LBB0_451
	s_cmp_gt_i32 s61, 33
	s_cselect_b64 s[64:65], -1, 0
	s_lshl_b32 s0, s61, 8
	s_lshl_b32 s53, s60, 8
	s_add_i32 s1, s0, 0xffffee00
	s_cmp_lt_i32 s61, 26
	v_cndmask_b32_e64 v2, 0, 1, s[36:37]
	s_cselect_b32 s62, s0, s1
	s_mov_b64 s[0:1], -1
	s_and_b64 vcc, exec, s[64:65]
	v_cmp_ne_u32_e64 s[44:45], 1, v2
	s_cbranch_vccz .LBB0_433
	s_and_b64 vcc, exec, s[44:45]
	s_cbranch_vccnz .LBB0_432
	v_add_u32_e32 v132, s53, v185
	v_ashrrev_i32_e32 v133, 31, v132
	v_lshlrev_b64 v[140:141], 7, v[132:133]
	global_load_dwordx4 v[132:135], v[188:189], off offset:16
	global_load_dwordx4 v[136:139], v[188:189], off
	s_mov_b32 s3, 0xbfb8aa3b
	s_mov_b32 s2, 0x800000
	s_mov_b32 s4, 0x3f317217
	s_mov_b32 s5, 0x7f800000
	s_waitcnt vmcnt(0)
	v_add_f32_e32 v147, v126, v134
	v_add_f32_e32 v2, v128, v136
	v_max_f32_e32 v142, 0, v2
	v_mul_f32_e64 v2, |v2|, s3
	v_exp_f32_e32 v2, v2
	v_add_f32_e32 v136, v124, v132
	v_add_f32_e32 v149, v127, v135
	v_add_f32_e32 v2, 1.0, v2
	v_cmp_gt_f32_e32 vcc, s2, v2
	s_nop 1
	v_cndmask_b32_e64 v132, 0, 32, vcc
	v_ldexp_f32 v2, v2, v132
	v_log_f32_e32 v2, v2
	s_nop 0
	v_mul_f32_e32 v132, 0x3f317217, v2
	v_fma_f32 v132, v2, s4, -v132
	v_fmac_f32_e32 v132, 0x3377d1cf, v2
	v_fmac_f32_e32 v132, 0x3f317217, v2
	v_cmp_lt_f32_e64 s[0:1], |v2|, s5
	s_nop 1
	v_cndmask_b32_e64 v2, v2, v132, s[0:1]
	v_cndmask_b32_e32 v132, 0, v228, vcc
	v_sub_f32_e32 v144, v2, v132
	v_mul_f32_e64 v2, |v136|, s3
	v_exp_f32_e32 v2, v2
	v_max_f32_e32 v132, 0, v136
	v_add_f32_e32 v2, 1.0, v2
	v_cmp_gt_f32_e32 vcc, s2, v2
	s_nop 1
	v_cndmask_b32_e64 v136, 0, 32, vcc
	v_ldexp_f32 v2, v2, v136
	v_log_f32_e32 v2, v2
	s_nop 0
	v_mul_f32_e32 v136, 0x3f317217, v2
	v_fma_f32 v136, v2, s4, -v136
	v_fmac_f32_e32 v136, 0x3377d1cf, v2
	v_fmac_f32_e32 v136, 0x3f317217, v2
	v_cmp_lt_f32_e64 s[0:1], |v2|, s5
	s_nop 1
	v_cndmask_b32_e64 v2, v2, v136, s[0:1]
	v_cndmask_b32_e32 v136, 0, v228, vcc
	v_sub_f32_e32 v136, v2, v136
	v_add_f32_e32 v2, v129, v137
	v_max_f32_e32 v143, 0, v2
	v_mul_f32_e64 v2, |v2|, s3
	v_exp_f32_e32 v2, v2
	v_add_f32_e32 v137, v125, v133
	v_add_f32_e32 v2, 1.0, v2
	v_cmp_gt_f32_e32 vcc, s2, v2
	s_nop 1
	v_cndmask_b32_e64 v133, 0, 32, vcc
	v_ldexp_f32 v2, v2, v133
	v_log_f32_e32 v2, v2
	s_nop 0
	v_mul_f32_e32 v133, 0x3f317217, v2
	v_fma_f32 v133, v2, s4, -v133
	v_fmac_f32_e32 v133, 0x3377d1cf, v2
	v_fmac_f32_e32 v133, 0x3f317217, v2
	v_cmp_lt_f32_e64 s[0:1], |v2|, s5
	s_nop 1
	v_cndmask_b32_e64 v2, v2, v133, s[0:1]
	v_cndmask_b32_e32 v133, 0, v228, vcc
	v_sub_f32_e32 v145, v2, v133
	v_mul_f32_e64 v2, |v137|, s3
	v_exp_f32_e32 v2, v2
	v_max_f32_e32 v133, 0, v137
	v_pk_add_f32 v[142:143], v[142:143], v[144:145]
	v_add_f32_e32 v2, 1.0, v2
	v_cmp_gt_f32_e32 vcc, s2, v2
	s_nop 1
	v_cndmask_b32_e64 v137, 0, 32, vcc
	v_ldexp_f32 v2, v2, v137
	v_log_f32_e32 v2, v2
	s_nop 0
	v_mul_f32_e32 v137, 0x3f317217, v2
	v_fma_f32 v137, v2, s4, -v137
	v_fmac_f32_e32 v137, 0x3377d1cf, v2
	v_fmac_f32_e32 v137, 0x3f317217, v2
	v_cmp_lt_f32_e64 s[0:1], |v2|, s5
	s_nop 1
	v_cndmask_b32_e64 v2, v2, v137, s[0:1]
	v_cndmask_b32_e32 v137, 0, v228, vcc
	v_sub_f32_e32 v137, v2, v137
	v_add_f32_e32 v2, v130, v138
	v_max_f32_e32 v138, 0, v2
	v_mul_f32_e64 v2, |v2|, s3
	v_exp_f32_e32 v2, v2
	v_pk_add_f32 v[132:133], v[132:133], v[136:137]
	v_lshl_add_u64 v[136:137], v[190:191], 0, v[140:141]
	v_add_f32_e32 v2, 1.0, v2
	v_cmp_gt_f32_e32 vcc, s2, v2
	s_nop 1
	v_cndmask_b32_e64 v134, 0, 32, vcc
	v_ldexp_f32 v2, v2, v134
	v_log_f32_e32 v2, v2
	s_nop 0
	v_mul_f32_e32 v134, 0x3f317217, v2
	v_fma_f32 v134, v2, s4, -v134
	v_fmac_f32_e32 v134, 0x3377d1cf, v2
	v_fmac_f32_e32 v134, 0x3f317217, v2
	v_cmp_lt_f32_e64 s[0:1], |v2|, s5
	s_nop 1
	v_cndmask_b32_e64 v2, v2, v134, s[0:1]
	v_cndmask_b32_e32 v134, 0, v228, vcc
	v_sub_f32_e32 v146, v2, v134
	v_mul_f32_e64 v2, |v147|, s3
	v_exp_f32_e32 v2, v2
	v_max_f32_e32 v134, 0, v147
	v_add_f32_e32 v2, 1.0, v2
	v_cmp_gt_f32_e32 vcc, s2, v2
	s_nop 1
	v_cndmask_b32_e64 v147, 0, 32, vcc
	v_ldexp_f32 v2, v2, v147
	v_log_f32_e32 v2, v2
	s_nop 0
	v_mul_f32_e32 v147, 0x3f317217, v2
	v_fma_f32 v147, v2, s4, -v147
	v_fmac_f32_e32 v147, 0x3377d1cf, v2
	v_fmac_f32_e32 v147, 0x3f317217, v2
	v_cmp_lt_f32_e64 s[0:1], |v2|, s5
	s_nop 1
	v_cndmask_b32_e64 v2, v2, v147, s[0:1]
	v_cndmask_b32_e32 v147, 0, v228, vcc
	v_sub_f32_e32 v148, v2, v147
	v_add_f32_e32 v2, v131, v139
	v_max_f32_e32 v139, 0, v2
	v_mul_f32_e64 v2, |v2|, s3
	v_exp_f32_e32 v2, v2
	s_nop 0
	v_add_f32_e32 v2, 1.0, v2
	v_cmp_gt_f32_e32 vcc, s2, v2
	s_nop 1
	v_cndmask_b32_e64 v135, 0, 32, vcc
	v_ldexp_f32 v2, v2, v135
	v_log_f32_e32 v2, v2
	s_nop 0
	v_mul_f32_e32 v135, 0x3f317217, v2
	v_fma_f32 v135, v2, s4, -v135
	v_fmac_f32_e32 v135, 0x3377d1cf, v2
	v_fmac_f32_e32 v135, 0x3f317217, v2
	v_cmp_lt_f32_e64 s[0:1], |v2|, s5
	s_nop 1
	v_cndmask_b32_e64 v2, v2, v135, s[0:1]
	v_cndmask_b32_e32 v135, 0, v228, vcc
	v_sub_f32_e32 v147, v2, v135
	v_mul_f32_e64 v2, |v149|, s3
	v_exp_f32_e32 v2, v2
	v_pk_add_f32 v[144:145], v[138:139], v[146:147]
	v_max_f32_e32 v135, 0, v149
	v_add_f32_e32 v2, 1.0, v2
	v_cmp_gt_f32_e32 vcc, s2, v2
	s_nop 1
	v_cndmask_b32_e64 v138, 0, 32, vcc
	v_ldexp_f32 v2, v2, v138
	v_log_f32_e32 v2, v2
	s_nop 0
	v_mul_f32_e32 v138, 0x3f317217, v2
	v_fma_f32 v138, v2, s4, -v138
	v_fmac_f32_e32 v138, 0x3377d1cf, v2
	v_fmac_f32_e32 v138, 0x3f317217, v2
	v_cmp_lt_f32_e64 s[0:1], |v2|, s5
	s_nop 1
	v_cndmask_b32_e64 v2, v2, v138, s[0:1]
	v_cndmask_b32_e32 v138, 0, v228, vcc
	v_sub_f32_e32 v149, v2, v138
	v_pk_add_f32 v[134:135], v[134:135], v[148:149]
	global_store_dwordx4 v[136:137], v[142:145], off
	global_store_dwordx4 v[136:137], v[132:135], off offset:16
